# GEMM k-loops: 3 LDS stages, B-fragment register ring continues across k-steps (next step's first 4 fragments read before the barrier, barrier mid-step with counted lgkmcnt), loop unrolled x6
# baseline (speedup 1.0000x reference)
.LBB0_215:
	s_mul_hi_i32 s0, s8, 0x2aaaaaab
	s_lshr_b32 s1, s0, 31
	s_ashr_i32 s0, s0, 5
	s_add_i32 s0, s0, s1
	s_lshl_b32 s1, s0, 3
	s_sub_i32 s2, 17, s1
	s_min_u32 s2, s2, 8
	v_cvt_f32_ubyte0_e32 v0, s2
	v_rcp_iflag_f32_e32 v0, v0
	s_sub_i32 s5, 0, s2
	s_mulk_i32 s0, 0xff40
	s_add_i32 s3, s0, s8
	v_mul_f32_e32 v0, 0x4f7ffffe, v0
	v_cvt_u32_f32_e32 v0, v0
	s_abs_i32 s4, s3
	s_ashr_i32 s0, s3, 31
	v_mov_b32_e32 v181, v179
	v_readfirstlane_b32 s6, v0
	s_mul_i32 s5, s5, s6
	s_mul_hi_u32 s5, s6, s5
	s_add_i32 s6, s6, s5
	s_mul_hi_u32 s5, s4, s6
	s_mul_i32 s6, s5, s2
	s_sub_i32 s4, s4, s6
	s_add_i32 s6, s5, 1
	s_sub_i32 s7, s4, s2
	s_cmp_ge_u32 s4, s2
	s_cselect_b32 s5, s6, s5
	s_cselect_b32 s4, s7, s4
	s_add_i32 s6, s5, 1
	s_cmp_ge_u32 s4, s2
	s_cselect_b32 s4, s6, s5
	s_xor_b32 s4, s4, s0
	s_sub_i32 s0, s4, s0
	s_mul_i32 s2, s2, s0
	s_sub_i32 s2, s3, s2
	s_add_i32 s1, s1, s11
	s_add_i32 s2, s1, s2
	v_ashrrev_i32_e32 v233, 6, v181
	v_lshlrev_b32_e32 v0, 1, v233
	v_lshl_add_u32 v0, s2, 3, v0
	v_ashrrev_i32_e32 v1, 31, v0
	v_bfe_u32 v183, v181, 5, 1
	v_lshlrev_b64 v[0:1], 16, v[0:1]
	v_and_b32_e32 v231, 31, v181
	v_lshl_add_u64 v[0:1], s[64:65], 0, v[0:1]
	v_lshlrev_b32_e32 v176, 9, v183
	s_ashr_i32 s1, s0, 31
	v_lshl_add_u64 v[0:1], v[0:1], 0, v[176:177]
	v_lshlrev_b32_e32 v176, 4, v231
	v_ashrrev_i32_e32 v12, 2, v181
	s_lshl_b64 s[4:5], s[0:1], 18
	v_lshl_add_u64 v[184:185], v[0:1], 0, v[176:177]
	s_add_u32 s4, s9, s4
	v_lshlrev_b32_e32 v0, 5, v12
	s_addc_u32 s5, s10, s5
	v_ashrrev_i32_e32 v1, 31, v0
	v_lshlrev_b32_e32 v2, 4, v181
	v_lshl_add_u64 v[0:1], v[0:1], 1, s[4:5]
	v_and_b32_e32 v176, 48, v2
	v_lshl_add_u64 v[186:187], v[0:1], 0, v[176:177]
	s_movk_i32 s1, 0x2000
	v_add_co_u32_e32 v8, vcc, s1, v186
	v_mul_u32_u24_e32 v10, 40, v231
	s_nop 0
	v_addc_co_u32_e32 v9, vcc, 0, v187, vcc
	v_lshlrev_b32_e32 v11, 4, v183
	v_lshl_add_u32 v235, v10, 1, v11
	v_add_co_u32_e32 v10, vcc, s41, v184
	s_movk_i32 s3, 0x50
	s_nop 0
	v_addc_co_u32_e32 v11, vcc, 0, v185, vcc
	v_and_b32_e32 v232, 63, v181
	v_lshlrev_b32_e32 v234, 3, v181
	v_mov_b32_e32 v176, 0x800
	v_lshl_add_u64 v[188:189], v[186:187], 0, v[176:177]
	v_bfe_u32 v197, v181, 4, 1
	v_lshlrev_b32_e32 v176, 9, v183
	v_lshl_add_u32 v176, v197, 8, v176
	v_lshl_add_u64 v[184:185], v[184:185], 0, v[176:177]
	v_mov_b32_e32 v176, s41
	v_lshl_add_u64 v[186:187], v[184:185], 0, v[176:177]
	v_lshrrev_b32_e32 v235, 2, v181
	v_bfe_u32 v197, v181, 4, 2
	v_lshlrev_b32_e32 v197, 1, v197
	v_mov_b32_e32 v176, 0x78
	v_lshrrev_b32_e32 v197, v197, v176
	v_and_b32_e32 v197, 3, v197
	v_and_b32_e32 v196, 3, v181
	v_xor_b32_e32 v197, v197, v196
	v_lshlrev_b32_e32 v197, 4, v197
	v_lshl_add_u32 v235, v235, 6, v197
	v_bfe_u32 v197, v181, 2, 2
	v_lshlrev_b32_e32 v197, 1, v197
	v_lshrrev_b32_e32 v197, v197, v176
	v_and_b32_e32 v197, 3, v197
	v_bfe_u32 v196, v181, 4, 2
	v_xor_b32_e32 v197, v197, v196
	v_lshlrev_b32_e32 v197, 4, v197
	v_and_b32_e32 v196, 15, v181
	v_lshl_add_u32 v196, v196, 6, v197
	s_mov_b32 s96, 0
	v_lshl_add_u64 v[166:167], v[188:189], 0, s[96:97]
	global_load_dwordx4 v[160:163], v[166:167], off offset:-2048
	global_load_dwordx4 v[164:167], v[166:167], off offset:2048
	s_movk_i32 s96, 0x2000
	v_lshl_add_u64 v[174:175], v[188:189], 0, s[96:97]
	global_load_dwordx4 v[168:171], v[174:175], off offset:-2048
	global_load_dwordx4 v[172:175], v[174:175], off offset:2048
	s_mov_b32 s96, 0
	v_lshl_add_u64 v[198:199], v[184:185], 0, s[96:97]
	v_lshl_add_u64 v[200:201], v[186:187], 0, s[96:97]
	global_load_dwordx4 v[128:131], v[198:199], off
	global_load_dwordx4 v[132:135], v[198:199], off offset:256
	global_load_dwordx4 v[136:139], v[200:201], off
	global_load_dwordx4 v[140:143], v[200:201], off offset:256
	v_mov_b32_e32 v0, 0
	v_mov_b32_e32 v1, 0
	v_mov_b32_e32 v2, 0
	v_mov_b32_e32 v3, 0
	v_mov_b32_e32 v4, 0
	v_mov_b32_e32 v5, 0
	v_mov_b32_e32 v6, 0
	v_mov_b32_e32 v7, 0
	v_mov_b32_e32 v8, 0
	v_mov_b32_e32 v9, 0
	v_mov_b32_e32 v10, 0
	v_mov_b32_e32 v11, 0
	v_mov_b32_e32 v12, 0
	v_mov_b32_e32 v13, 0
	v_mov_b32_e32 v14, 0
	v_mov_b32_e32 v15, 0
	v_mov_b32_e32 v16, 0
	v_mov_b32_e32 v17, 0
	v_mov_b32_e32 v18, 0
	v_mov_b32_e32 v19, 0
	v_mov_b32_e32 v20, 0
	v_mov_b32_e32 v21, 0
	v_mov_b32_e32 v22, 0
	v_mov_b32_e32 v23, 0
	v_mov_b32_e32 v24, 0
	v_mov_b32_e32 v25, 0
	v_mov_b32_e32 v26, 0
	v_mov_b32_e32 v27, 0
	v_mov_b32_e32 v28, 0
	v_mov_b32_e32 v29, 0
	v_mov_b32_e32 v30, 0
	v_mov_b32_e32 v31, 0
	v_mov_b32_e32 v32, 0
	v_mov_b32_e32 v33, 0
	v_mov_b32_e32 v34, 0
	v_mov_b32_e32 v35, 0
	v_mov_b32_e32 v36, 0
	v_mov_b32_e32 v37, 0
	v_mov_b32_e32 v38, 0
	v_mov_b32_e32 v39, 0
	v_mov_b32_e32 v40, 0
	v_mov_b32_e32 v41, 0
	v_mov_b32_e32 v42, 0
	v_mov_b32_e32 v43, 0
	v_mov_b32_e32 v44, 0
	v_mov_b32_e32 v45, 0
	v_mov_b32_e32 v46, 0
	v_mov_b32_e32 v47, 0
	v_mov_b32_e32 v48, 0
	v_mov_b32_e32 v49, 0
	v_mov_b32_e32 v50, 0
	v_mov_b32_e32 v51, 0
	v_mov_b32_e32 v52, 0
	v_mov_b32_e32 v53, 0
	v_mov_b32_e32 v54, 0
	v_mov_b32_e32 v55, 0
	v_mov_b32_e32 v56, 0
	v_mov_b32_e32 v57, 0
	v_mov_b32_e32 v58, 0
	v_mov_b32_e32 v59, 0
	v_mov_b32_e32 v60, 0
	v_mov_b32_e32 v61, 0
	v_mov_b32_e32 v62, 0
	v_mov_b32_e32 v63, 0
	v_mov_b32_e32 v64, 0
	v_mov_b32_e32 v65, 0
	v_mov_b32_e32 v66, 0
	v_mov_b32_e32 v67, 0
	v_mov_b32_e32 v68, 0
	v_mov_b32_e32 v69, 0
	v_mov_b32_e32 v70, 0
	v_mov_b32_e32 v71, 0
	v_mov_b32_e32 v72, 0
	v_mov_b32_e32 v73, 0
	v_mov_b32_e32 v74, 0
	v_mov_b32_e32 v75, 0
	v_mov_b32_e32 v76, 0
	v_mov_b32_e32 v77, 0
	v_mov_b32_e32 v78, 0
	v_mov_b32_e32 v79, 0
	v_mov_b32_e32 v80, 0
	v_mov_b32_e32 v81, 0
	v_mov_b32_e32 v82, 0
	v_mov_b32_e32 v83, 0
	v_mov_b32_e32 v84, 0
	v_mov_b32_e32 v85, 0
	v_mov_b32_e32 v86, 0
	v_mov_b32_e32 v87, 0
	v_mov_b32_e32 v88, 0
	v_mov_b32_e32 v89, 0
	v_mov_b32_e32 v90, 0
	v_mov_b32_e32 v91, 0
	v_mov_b32_e32 v92, 0
	v_mov_b32_e32 v93, 0
	v_mov_b32_e32 v94, 0
	v_mov_b32_e32 v95, 0
	v_mov_b32_e32 v96, 0
	v_mov_b32_e32 v97, 0
	v_mov_b32_e32 v98, 0
	v_mov_b32_e32 v99, 0
	v_mov_b32_e32 v100, 0
	v_mov_b32_e32 v101, 0
	v_mov_b32_e32 v102, 0
	v_mov_b32_e32 v103, 0
	v_mov_b32_e32 v104, 0
	v_mov_b32_e32 v105, 0
	v_mov_b32_e32 v106, 0
	v_mov_b32_e32 v107, 0
	v_mov_b32_e32 v108, 0
	v_mov_b32_e32 v109, 0
	v_mov_b32_e32 v110, 0
	v_mov_b32_e32 v111, 0
	v_mov_b32_e32 v112, 0
	v_mov_b32_e32 v113, 0
	v_mov_b32_e32 v114, 0
	v_mov_b32_e32 v115, 0
	v_mov_b32_e32 v116, 0
	v_mov_b32_e32 v117, 0
	v_mov_b32_e32 v118, 0
	v_mov_b32_e32 v119, 0
	v_mov_b32_e32 v120, 0
	v_mov_b32_e32 v121, 0
	v_mov_b32_e32 v122, 0
	v_mov_b32_e32 v123, 0
	v_mov_b32_e32 v124, 0
	v_mov_b32_e32 v125, 0
	v_mov_b32_e32 v126, 0
	v_mov_b32_e32 v127, 0
	s_mov_b32 s1, 0
	s_waitcnt vmcnt(4)
	ds_write_b128 v235, v[160:163]
	ds_write_b128 v235, v[164:167] offset:4096
	ds_write_b128 v235, v[168:171] offset:8192
	ds_write_b128 v235, v[172:175] offset:12288
	s_nop 3
	s_movk_i32 s96, 0x4000
	v_lshl_add_u64 v[174:175], v[188:189], 0, s[96:97]
	global_load_dwordx4 v[168:171], v[174:175], off offset:-2048
	global_load_dwordx4 v[172:175], v[174:175], off offset:2048
	s_movk_i32 s96, 0x800
	v_lshl_add_u64 v[198:199], v[184:185], 0, s[96:97]
	v_lshl_add_u64 v[200:201], v[186:187], 0, s[96:97]
	global_load_dwordx4 v[144:147], v[198:199], off
	global_load_dwordx4 v[148:151], v[198:199], off offset:256
	global_load_dwordx4 v[152:155], v[200:201], off
	global_load_dwordx4 v[156:159], v[200:201], off offset:256
	s_waitcnt lgkmcnt(0)
	s_barrier
	ds_read_b128 v[236:239], v196 offset:0
	ds_read_b128 v[240:243], v196 offset:1024
	ds_read_b128 v[244:247], v196 offset:2048
	ds_read_b128 v[248:251], v196 offset:3072
.Lg16_proj_k:
	s_add_i32 s3, s1, 3
	s_min_u32 s4, s3, 31
	s_lshl_b32 s96, s4, 13
	v_lshl_add_u64 v[166:167], v[188:189], 0, s[96:97]
	global_load_dwordx4 v[160:163], v[166:167], off offset:-2048
	global_load_dwordx4 v[164:167], v[166:167], off offset:2048
	s_add_i32 s3, s1, 2
	s_min_u32 s4, s3, 31
	s_lshl_b32 s96, s4, 11
	v_lshl_add_u64 v[198:199], v[184:185], 0, s[96:97]
	v_lshl_add_u64 v[200:201], v[186:187], 0, s[96:97]
	s_waitcnt vmcnt(8) lgkmcnt(3)
	v_mfma_f32_16x16x32_bf16 v[16:19], v[128:131], v[236:239], v[16:19]
	v_mfma_f32_16x16x32_bf16 v[24:27], v[132:135], v[236:239], v[24:27]
	v_mfma_f32_16x16x32_bf16 v[0:3], v[136:139], v[236:239], v[0:3]
	v_mfma_f32_16x16x32_bf16 v[8:11], v[140:143], v[236:239], v[8:11]
	ds_read_b128 v[236:239], v196 offset:4096
	s_waitcnt lgkmcnt(3)
	v_mfma_f32_16x16x32_bf16 v[20:23], v[128:131], v[240:243], v[20:23]
	v_mfma_f32_16x16x32_bf16 v[28:31], v[132:135], v[240:243], v[28:31]
	v_mfma_f32_16x16x32_bf16 v[4:7], v[136:139], v[240:243], v[4:7]
	v_mfma_f32_16x16x32_bf16 v[12:15], v[140:143], v[240:243], v[12:15]
	ds_read_b128 v[240:243], v196 offset:5120
	s_waitcnt lgkmcnt(3)
	v_mfma_f32_16x16x32_bf16 v[112:115], v[128:131], v[244:247], v[112:115]
	v_mfma_f32_16x16x32_bf16 v[120:123], v[132:135], v[244:247], v[120:123]
	v_mfma_f32_16x16x32_bf16 v[96:99], v[136:139], v[244:247], v[96:99]
	v_mfma_f32_16x16x32_bf16 v[104:107], v[140:143], v[244:247], v[104:107]
	ds_read_b128 v[244:247], v196 offset:6144
	s_waitcnt lgkmcnt(3)
	v_mfma_f32_16x16x32_bf16 v[116:119], v[128:131], v[248:251], v[116:119]
	v_mfma_f32_16x16x32_bf16 v[124:127], v[132:135], v[248:251], v[124:127]
	v_mfma_f32_16x16x32_bf16 v[100:103], v[136:139], v[248:251], v[100:103]
	v_mfma_f32_16x16x32_bf16 v[108:111], v[140:143], v[248:251], v[108:111]
	ds_read_b128 v[248:251], v196 offset:7168
	s_waitcnt vmcnt(6)
	ds_write_b128 v235, v[168:171] offset:16384
	ds_write_b128 v235, v[172:175] offset:20480
	s_waitcnt lgkmcnt(5)
	v_mfma_f32_16x16x32_bf16 v[80:83], v[128:131], v[236:239], v[80:83]
	v_mfma_f32_16x16x32_bf16 v[88:91], v[132:135], v[236:239], v[88:91]
	v_mfma_f32_16x16x32_bf16 v[48:51], v[136:139], v[236:239], v[48:51]
	v_mfma_f32_16x16x32_bf16 v[56:59], v[140:143], v[236:239], v[56:59]
	ds_read_b128 v[236:239], v196 offset:8192
	s_waitcnt lgkmcnt(5)
	v_mfma_f32_16x16x32_bf16 v[84:87], v[128:131], v[240:243], v[84:87]
	v_mfma_f32_16x16x32_bf16 v[92:95], v[132:135], v[240:243], v[92:95]
	v_mfma_f32_16x16x32_bf16 v[52:55], v[136:139], v[240:243], v[52:55]
	v_mfma_f32_16x16x32_bf16 v[60:63], v[140:143], v[240:243], v[60:63]
	ds_read_b128 v[240:243], v196 offset:9216
	s_waitcnt lgkmcnt(2)
	s_barrier
	v_mfma_f32_16x16x32_bf16 v[64:67], v[128:131], v[244:247], v[64:67]
	v_mfma_f32_16x16x32_bf16 v[72:75], v[132:135], v[244:247], v[72:75]
	v_mfma_f32_16x16x32_bf16 v[32:35], v[136:139], v[244:247], v[32:35]
	v_mfma_f32_16x16x32_bf16 v[40:43], v[140:143], v[244:247], v[40:43]
	ds_read_b128 v[244:247], v196 offset:10240
	v_mfma_f32_16x16x32_bf16 v[68:71], v[128:131], v[248:251], v[68:71]
	v_mfma_f32_16x16x32_bf16 v[76:79], v[132:135], v[248:251], v[76:79]
	v_mfma_f32_16x16x32_bf16 v[36:39], v[136:139], v[248:251], v[36:39]
	v_mfma_f32_16x16x32_bf16 v[44:47], v[140:143], v[248:251], v[44:47]
	ds_read_b128 v[248:251], v196 offset:11264
	global_load_dwordx4 v[128:131], v[198:199], off
	global_load_dwordx4 v[132:135], v[198:199], off offset:256
	global_load_dwordx4 v[136:139], v[200:201], off
	global_load_dwordx4 v[140:143], v[200:201], off offset:256
	s_add_i32 s3, s1, 4
	s_min_u32 s4, s3, 31
	s_lshl_b32 s96, s4, 13
	v_lshl_add_u64 v[174:175], v[188:189], 0, s[96:97]
	global_load_dwordx4 v[168:171], v[174:175], off offset:-2048
	global_load_dwordx4 v[172:175], v[174:175], off offset:2048
	s_add_i32 s3, s1, 3
	s_min_u32 s4, s3, 31
	s_lshl_b32 s96, s4, 11
	v_lshl_add_u64 v[198:199], v[184:185], 0, s[96:97]
	v_lshl_add_u64 v[200:201], v[186:187], 0, s[96:97]
	s_waitcnt vmcnt(8) lgkmcnt(3)
	v_mfma_f32_16x16x32_bf16 v[16:19], v[144:147], v[236:239], v[16:19]
	v_mfma_f32_16x16x32_bf16 v[24:27], v[148:151], v[236:239], v[24:27]
	v_mfma_f32_16x16x32_bf16 v[0:3], v[152:155], v[236:239], v[0:3]
	v_mfma_f32_16x16x32_bf16 v[8:11], v[156:159], v[236:239], v[8:11]
	ds_read_b128 v[236:239], v196 offset:12288
	s_waitcnt lgkmcnt(3)
	v_mfma_f32_16x16x32_bf16 v[20:23], v[144:147], v[240:243], v[20:23]
	v_mfma_f32_16x16x32_bf16 v[28:31], v[148:151], v[240:243], v[28:31]
	v_mfma_f32_16x16x32_bf16 v[4:7], v[152:155], v[240:243], v[4:7]
	v_mfma_f32_16x16x32_bf16 v[12:15], v[156:159], v[240:243], v[12:15]
	ds_read_b128 v[240:243], v196 offset:13312
	s_waitcnt lgkmcnt(3)
	v_mfma_f32_16x16x32_bf16 v[112:115], v[144:147], v[244:247], v[112:115]
	v_mfma_f32_16x16x32_bf16 v[120:123], v[148:151], v[244:247], v[120:123]
	v_mfma_f32_16x16x32_bf16 v[96:99], v[152:155], v[244:247], v[96:99]
	v_mfma_f32_16x16x32_bf16 v[104:107], v[156:159], v[244:247], v[104:107]
	ds_read_b128 v[244:247], v196 offset:14336
	s_waitcnt lgkmcnt(3)
	v_mfma_f32_16x16x32_bf16 v[116:119], v[144:147], v[248:251], v[116:119]
	v_mfma_f32_16x16x32_bf16 v[124:127], v[148:151], v[248:251], v[124:127]
	v_mfma_f32_16x16x32_bf16 v[100:103], v[152:155], v[248:251], v[100:103]
	v_mfma_f32_16x16x32_bf16 v[108:111], v[156:159], v[248:251], v[108:111]
	ds_read_b128 v[248:251], v196 offset:15360
	s_waitcnt vmcnt(6)
	ds_write_b128 v235, v[160:163] offset:0
	ds_write_b128 v235, v[164:167] offset:4096
	s_waitcnt lgkmcnt(5)
	v_mfma_f32_16x16x32_bf16 v[80:83], v[144:147], v[236:239], v[80:83]
	v_mfma_f32_16x16x32_bf16 v[88:91], v[148:151], v[236:239], v[88:91]
	v_mfma_f32_16x16x32_bf16 v[48:51], v[152:155], v[236:239], v[48:51]
	v_mfma_f32_16x16x32_bf16 v[56:59], v[156:159], v[236:239], v[56:59]
	ds_read_b128 v[236:239], v196 offset:16384
	s_waitcnt lgkmcnt(5)
	v_mfma_f32_16x16x32_bf16 v[84:87], v[144:147], v[240:243], v[84:87]
	v_mfma_f32_16x16x32_bf16 v[92:95], v[148:151], v[240:243], v[92:95]
	v_mfma_f32_16x16x32_bf16 v[52:55], v[152:155], v[240:243], v[52:55]
	v_mfma_f32_16x16x32_bf16 v[60:63], v[156:159], v[240:243], v[60:63]
	ds_read_b128 v[240:243], v196 offset:17408
	s_waitcnt lgkmcnt(2)
	s_barrier
	v_mfma_f32_16x16x32_bf16 v[64:67], v[144:147], v[244:247], v[64:67]
	v_mfma_f32_16x16x32_bf16 v[72:75], v[148:151], v[244:247], v[72:75]
	v_mfma_f32_16x16x32_bf16 v[32:35], v[152:155], v[244:247], v[32:35]
	v_mfma_f32_16x16x32_bf16 v[40:43], v[156:159], v[244:247], v[40:43]
	ds_read_b128 v[244:247], v196 offset:18432
	v_mfma_f32_16x16x32_bf16 v[68:71], v[144:147], v[248:251], v[68:71]
	v_mfma_f32_16x16x32_bf16 v[76:79], v[148:151], v[248:251], v[76:79]
	v_mfma_f32_16x16x32_bf16 v[36:39], v[152:155], v[248:251], v[36:39]
	v_mfma_f32_16x16x32_bf16 v[44:47], v[156:159], v[248:251], v[44:47]
	ds_read_b128 v[248:251], v196 offset:19456
	global_load_dwordx4 v[144:147], v[198:199], off
	global_load_dwordx4 v[148:151], v[198:199], off offset:256
	global_load_dwordx4 v[152:155], v[200:201], off
	global_load_dwordx4 v[156:159], v[200:201], off offset:256
	s_add_i32 s3, s1, 5
	s_min_u32 s4, s3, 31
	s_lshl_b32 s96, s4, 13
	v_lshl_add_u64 v[166:167], v[188:189], 0, s[96:97]
	global_load_dwordx4 v[160:163], v[166:167], off offset:-2048
	global_load_dwordx4 v[164:167], v[166:167], off offset:2048
	s_add_i32 s3, s1, 4
	s_min_u32 s4, s3, 31
	s_lshl_b32 s96, s4, 11
	v_lshl_add_u64 v[198:199], v[184:185], 0, s[96:97]
	v_lshl_add_u64 v[200:201], v[186:187], 0, s[96:97]
	s_waitcnt vmcnt(8) lgkmcnt(3)
	v_mfma_f32_16x16x32_bf16 v[16:19], v[128:131], v[236:239], v[16:19]
	v_mfma_f32_16x16x32_bf16 v[24:27], v[132:135], v[236:239], v[24:27]
	v_mfma_f32_16x16x32_bf16 v[0:3], v[136:139], v[236:239], v[0:3]
	v_mfma_f32_16x16x32_bf16 v[8:11], v[140:143], v[236:239], v[8:11]
	ds_read_b128 v[236:239], v196 offset:20480
	s_waitcnt lgkmcnt(3)
	v_mfma_f32_16x16x32_bf16 v[20:23], v[128:131], v[240:243], v[20:23]
	v_mfma_f32_16x16x32_bf16 v[28:31], v[132:135], v[240:243], v[28:31]
	v_mfma_f32_16x16x32_bf16 v[4:7], v[136:139], v[240:243], v[4:7]
	v_mfma_f32_16x16x32_bf16 v[12:15], v[140:143], v[240:243], v[12:15]
	ds_read_b128 v[240:243], v196 offset:21504
	s_waitcnt lgkmcnt(3)
	v_mfma_f32_16x16x32_bf16 v[112:115], v[128:131], v[244:247], v[112:115]
	v_mfma_f32_16x16x32_bf16 v[120:123], v[132:135], v[244:247], v[120:123]
	v_mfma_f32_16x16x32_bf16 v[96:99], v[136:139], v[244:247], v[96:99]
	v_mfma_f32_16x16x32_bf16 v[104:107], v[140:143], v[244:247], v[104:107]
	ds_read_b128 v[244:247], v196 offset:22528
	s_waitcnt lgkmcnt(3)
	v_mfma_f32_16x16x32_bf16 v[116:119], v[128:131], v[248:251], v[116:119]
	v_mfma_f32_16x16x32_bf16 v[124:127], v[132:135], v[248:251], v[124:127]
	v_mfma_f32_16x16x32_bf16 v[100:103], v[136:139], v[248:251], v[100:103]
	v_mfma_f32_16x16x32_bf16 v[108:111], v[140:143], v[248:251], v[108:111]
	ds_read_b128 v[248:251], v196 offset:23552
	s_waitcnt vmcnt(6)
	ds_write_b128 v235, v[168:171] offset:8192
	ds_write_b128 v235, v[172:175] offset:12288
	s_waitcnt lgkmcnt(5)
	v_mfma_f32_16x16x32_bf16 v[80:83], v[128:131], v[236:239], v[80:83]
	v_mfma_f32_16x16x32_bf16 v[88:91], v[132:135], v[236:239], v[88:91]
	v_mfma_f32_16x16x32_bf16 v[48:51], v[136:139], v[236:239], v[48:51]
	v_mfma_f32_16x16x32_bf16 v[56:59], v[140:143], v[236:239], v[56:59]
	ds_read_b128 v[236:239], v196 offset:0
	s_waitcnt lgkmcnt(5)
	v_mfma_f32_16x16x32_bf16 v[84:87], v[128:131], v[240:243], v[84:87]
	v_mfma_f32_16x16x32_bf16 v[92:95], v[132:135], v[240:243], v[92:95]
	v_mfma_f32_16x16x32_bf16 v[52:55], v[136:139], v[240:243], v[52:55]
	v_mfma_f32_16x16x32_bf16 v[60:63], v[140:143], v[240:243], v[60:63]
	ds_read_b128 v[240:243], v196 offset:1024
	s_waitcnt lgkmcnt(2)
	s_barrier
	v_mfma_f32_16x16x32_bf16 v[64:67], v[128:131], v[244:247], v[64:67]
	v_mfma_f32_16x16x32_bf16 v[72:75], v[132:135], v[244:247], v[72:75]
	v_mfma_f32_16x16x32_bf16 v[32:35], v[136:139], v[244:247], v[32:35]
	v_mfma_f32_16x16x32_bf16 v[40:43], v[140:143], v[244:247], v[40:43]
	ds_read_b128 v[244:247], v196 offset:2048
	v_mfma_f32_16x16x32_bf16 v[68:71], v[128:131], v[248:251], v[68:71]
	v_mfma_f32_16x16x32_bf16 v[76:79], v[132:135], v[248:251], v[76:79]
	v_mfma_f32_16x16x32_bf16 v[36:39], v[136:139], v[248:251], v[36:39]
	v_mfma_f32_16x16x32_bf16 v[44:47], v[140:143], v[248:251], v[44:47]
	ds_read_b128 v[248:251], v196 offset:3072
	global_load_dwordx4 v[128:131], v[198:199], off
	global_load_dwordx4 v[132:135], v[198:199], off offset:256
	global_load_dwordx4 v[136:139], v[200:201], off
	global_load_dwordx4 v[140:143], v[200:201], off offset:256
	s_add_i32 s3, s1, 6
	s_min_u32 s4, s3, 31
	s_lshl_b32 s96, s4, 13
	v_lshl_add_u64 v[174:175], v[188:189], 0, s[96:97]
	global_load_dwordx4 v[168:171], v[174:175], off offset:-2048
	global_load_dwordx4 v[172:175], v[174:175], off offset:2048
	s_add_i32 s3, s1, 5
	s_min_u32 s4, s3, 31
	s_lshl_b32 s96, s4, 11
	v_lshl_add_u64 v[198:199], v[184:185], 0, s[96:97]
	v_lshl_add_u64 v[200:201], v[186:187], 0, s[96:97]
	s_waitcnt vmcnt(8) lgkmcnt(3)
	v_mfma_f32_16x16x32_bf16 v[16:19], v[144:147], v[236:239], v[16:19]
	v_mfma_f32_16x16x32_bf16 v[24:27], v[148:151], v[236:239], v[24:27]
	v_mfma_f32_16x16x32_bf16 v[0:3], v[152:155], v[236:239], v[0:3]
	v_mfma_f32_16x16x32_bf16 v[8:11], v[156:159], v[236:239], v[8:11]
	ds_read_b128 v[236:239], v196 offset:4096
	s_waitcnt lgkmcnt(3)
	v_mfma_f32_16x16x32_bf16 v[20:23], v[144:147], v[240:243], v[20:23]
	v_mfma_f32_16x16x32_bf16 v[28:31], v[148:151], v[240:243], v[28:31]
	v_mfma_f32_16x16x32_bf16 v[4:7], v[152:155], v[240:243], v[4:7]
	v_mfma_f32_16x16x32_bf16 v[12:15], v[156:159], v[240:243], v[12:15]
	ds_read_b128 v[240:243], v196 offset:5120
	s_waitcnt lgkmcnt(3)
	v_mfma_f32_16x16x32_bf16 v[112:115], v[144:147], v[244:247], v[112:115]
	v_mfma_f32_16x16x32_bf16 v[120:123], v[148:151], v[244:247], v[120:123]
	v_mfma_f32_16x16x32_bf16 v[96:99], v[152:155], v[244:247], v[96:99]
	v_mfma_f32_16x16x32_bf16 v[104:107], v[156:159], v[244:247], v[104:107]
	ds_read_b128 v[244:247], v196 offset:6144
	s_waitcnt lgkmcnt(3)
	v_mfma_f32_16x16x32_bf16 v[116:119], v[144:147], v[248:251], v[116:119]
	v_mfma_f32_16x16x32_bf16 v[124:127], v[148:151], v[248:251], v[124:127]
	v_mfma_f32_16x16x32_bf16 v[100:103], v[152:155], v[248:251], v[100:103]
	v_mfma_f32_16x16x32_bf16 v[108:111], v[156:159], v[248:251], v[108:111]
	ds_read_b128 v[248:251], v196 offset:7168
	s_waitcnt vmcnt(6)
	ds_write_b128 v235, v[160:163] offset:16384
	ds_write_b128 v235, v[164:167] offset:20480
	s_waitcnt lgkmcnt(5)
	v_mfma_f32_16x16x32_bf16 v[80:83], v[144:147], v[236:239], v[80:83]
	v_mfma_f32_16x16x32_bf16 v[88:91], v[148:151], v[236:239], v[88:91]
	v_mfma_f32_16x16x32_bf16 v[48:51], v[152:155], v[236:239], v[48:51]
	v_mfma_f32_16x16x32_bf16 v[56:59], v[156:159], v[236:239], v[56:59]
	ds_read_b128 v[236:239], v196 offset:8192
	s_waitcnt lgkmcnt(5)
	v_mfma_f32_16x16x32_bf16 v[84:87], v[144:147], v[240:243], v[84:87]
	v_mfma_f32_16x16x32_bf16 v[92:95], v[148:151], v[240:243], v[92:95]
	v_mfma_f32_16x16x32_bf16 v[52:55], v[152:155], v[240:243], v[52:55]
	v_mfma_f32_16x16x32_bf16 v[60:63], v[156:159], v[240:243], v[60:63]
	ds_read_b128 v[240:243], v196 offset:9216
	s_waitcnt lgkmcnt(2)
	s_barrier
	v_mfma_f32_16x16x32_bf16 v[64:67], v[144:147], v[244:247], v[64:67]
	v_mfma_f32_16x16x32_bf16 v[72:75], v[148:151], v[244:247], v[72:75]
	v_mfma_f32_16x16x32_bf16 v[32:35], v[152:155], v[244:247], v[32:35]
	v_mfma_f32_16x16x32_bf16 v[40:43], v[156:159], v[244:247], v[40:43]
	ds_read_b128 v[244:247], v196 offset:10240
	v_mfma_f32_16x16x32_bf16 v[68:71], v[144:147], v[248:251], v[68:71]
	v_mfma_f32_16x16x32_bf16 v[76:79], v[148:151], v[248:251], v[76:79]
	v_mfma_f32_16x16x32_bf16 v[36:39], v[152:155], v[248:251], v[36:39]
	v_mfma_f32_16x16x32_bf16 v[44:47], v[156:159], v[248:251], v[44:47]
	ds_read_b128 v[248:251], v196 offset:11264
	global_load_dwordx4 v[144:147], v[198:199], off
	global_load_dwordx4 v[148:151], v[198:199], off offset:256
	global_load_dwordx4 v[152:155], v[200:201], off
	global_load_dwordx4 v[156:159], v[200:201], off offset:256
	s_add_i32 s3, s1, 7
	s_min_u32 s4, s3, 31
	s_lshl_b32 s96, s4, 13
	v_lshl_add_u64 v[166:167], v[188:189], 0, s[96:97]
	global_load_dwordx4 v[160:163], v[166:167], off offset:-2048
	global_load_dwordx4 v[164:167], v[166:167], off offset:2048
	s_add_i32 s3, s1, 6
	s_min_u32 s4, s3, 31
	s_lshl_b32 s96, s4, 11
	v_lshl_add_u64 v[198:199], v[184:185], 0, s[96:97]
	v_lshl_add_u64 v[200:201], v[186:187], 0, s[96:97]
	s_waitcnt vmcnt(8) lgkmcnt(3)
	v_mfma_f32_16x16x32_bf16 v[16:19], v[128:131], v[236:239], v[16:19]
	v_mfma_f32_16x16x32_bf16 v[24:27], v[132:135], v[236:239], v[24:27]
	v_mfma_f32_16x16x32_bf16 v[0:3], v[136:139], v[236:239], v[0:3]
	v_mfma_f32_16x16x32_bf16 v[8:11], v[140:143], v[236:239], v[8:11]
	ds_read_b128 v[236:239], v196 offset:12288
	s_waitcnt lgkmcnt(3)
	v_mfma_f32_16x16x32_bf16 v[20:23], v[128:131], v[240:243], v[20:23]
	v_mfma_f32_16x16x32_bf16 v[28:31], v[132:135], v[240:243], v[28:31]
	v_mfma_f32_16x16x32_bf16 v[4:7], v[136:139], v[240:243], v[4:7]
	v_mfma_f32_16x16x32_bf16 v[12:15], v[140:143], v[240:243], v[12:15]
	ds_read_b128 v[240:243], v196 offset:13312
	s_waitcnt lgkmcnt(3)
	v_mfma_f32_16x16x32_bf16 v[112:115], v[128:131], v[244:247], v[112:115]
	v_mfma_f32_16x16x32_bf16 v[120:123], v[132:135], v[244:247], v[120:123]
	v_mfma_f32_16x16x32_bf16 v[96:99], v[136:139], v[244:247], v[96:99]
	v_mfma_f32_16x16x32_bf16 v[104:107], v[140:143], v[244:247], v[104:107]
	ds_read_b128 v[244:247], v196 offset:14336
	s_waitcnt lgkmcnt(3)
	v_mfma_f32_16x16x32_bf16 v[116:119], v[128:131], v[248:251], v[116:119]
	v_mfma_f32_16x16x32_bf16 v[124:127], v[132:135], v[248:251], v[124:127]
	v_mfma_f32_16x16x32_bf16 v[100:103], v[136:139], v[248:251], v[100:103]
	v_mfma_f32_16x16x32_bf16 v[108:111], v[140:143], v[248:251], v[108:111]
	ds_read_b128 v[248:251], v196 offset:15360
	s_waitcnt vmcnt(6)
	ds_write_b128 v235, v[168:171] offset:0
	ds_write_b128 v235, v[172:175] offset:4096
	s_waitcnt lgkmcnt(5)
	v_mfma_f32_16x16x32_bf16 v[80:83], v[128:131], v[236:239], v[80:83]
	v_mfma_f32_16x16x32_bf16 v[88:91], v[132:135], v[236:239], v[88:91]
	v_mfma_f32_16x16x32_bf16 v[48:51], v[136:139], v[236:239], v[48:51]
	v_mfma_f32_16x16x32_bf16 v[56:59], v[140:143], v[236:239], v[56:59]
	ds_read_b128 v[236:239], v196 offset:16384
	s_waitcnt lgkmcnt(5)
	v_mfma_f32_16x16x32_bf16 v[84:87], v[128:131], v[240:243], v[84:87]
	v_mfma_f32_16x16x32_bf16 v[92:95], v[132:135], v[240:243], v[92:95]
	v_mfma_f32_16x16x32_bf16 v[52:55], v[136:139], v[240:243], v[52:55]
	v_mfma_f32_16x16x32_bf16 v[60:63], v[140:143], v[240:243], v[60:63]
	ds_read_b128 v[240:243], v196 offset:17408
	s_waitcnt lgkmcnt(2)
	s_barrier
	v_mfma_f32_16x16x32_bf16 v[64:67], v[128:131], v[244:247], v[64:67]
	v_mfma_f32_16x16x32_bf16 v[72:75], v[132:135], v[244:247], v[72:75]
	v_mfma_f32_16x16x32_bf16 v[32:35], v[136:139], v[244:247], v[32:35]
	v_mfma_f32_16x16x32_bf16 v[40:43], v[140:143], v[244:247], v[40:43]
	ds_read_b128 v[244:247], v196 offset:18432
	v_mfma_f32_16x16x32_bf16 v[68:71], v[128:131], v[248:251], v[68:71]
	v_mfma_f32_16x16x32_bf16 v[76:79], v[132:135], v[248:251], v[76:79]
	v_mfma_f32_16x16x32_bf16 v[36:39], v[136:139], v[248:251], v[36:39]
	v_mfma_f32_16x16x32_bf16 v[44:47], v[140:143], v[248:251], v[44:47]
	ds_read_b128 v[248:251], v196 offset:19456
	global_load_dwordx4 v[128:131], v[198:199], off
	global_load_dwordx4 v[132:135], v[198:199], off offset:256
	global_load_dwordx4 v[136:139], v[200:201], off
	global_load_dwordx4 v[140:143], v[200:201], off offset:256
	s_add_i32 s3, s1, 8
	s_min_u32 s4, s3, 31
	s_lshl_b32 s96, s4, 13
	v_lshl_add_u64 v[174:175], v[188:189], 0, s[96:97]
	global_load_dwordx4 v[168:171], v[174:175], off offset:-2048
	global_load_dwordx4 v[172:175], v[174:175], off offset:2048
	s_add_i32 s3, s1, 7
	s_min_u32 s4, s3, 31
	s_lshl_b32 s96, s4, 11
	v_lshl_add_u64 v[198:199], v[184:185], 0, s[96:97]
	v_lshl_add_u64 v[200:201], v[186:187], 0, s[96:97]
	s_waitcnt vmcnt(8) lgkmcnt(3)
	v_mfma_f32_16x16x32_bf16 v[16:19], v[144:147], v[236:239], v[16:19]
	v_mfma_f32_16x16x32_bf16 v[24:27], v[148:151], v[236:239], v[24:27]
	v_mfma_f32_16x16x32_bf16 v[0:3], v[152:155], v[236:239], v[0:3]
	v_mfma_f32_16x16x32_bf16 v[8:11], v[156:159], v[236:239], v[8:11]
	ds_read_b128 v[236:239], v196 offset:20480
	s_waitcnt lgkmcnt(3)
	v_mfma_f32_16x16x32_bf16 v[20:23], v[144:147], v[240:243], v[20:23]
	v_mfma_f32_16x16x32_bf16 v[28:31], v[148:151], v[240:243], v[28:31]
	v_mfma_f32_16x16x32_bf16 v[4:7], v[152:155], v[240:243], v[4:7]
	v_mfma_f32_16x16x32_bf16 v[12:15], v[156:159], v[240:243], v[12:15]
	ds_read_b128 v[240:243], v196 offset:21504
	s_waitcnt lgkmcnt(3)
	v_mfma_f32_16x16x32_bf16 v[112:115], v[144:147], v[244:247], v[112:115]
	v_mfma_f32_16x16x32_bf16 v[120:123], v[148:151], v[244:247], v[120:123]
	v_mfma_f32_16x16x32_bf16 v[96:99], v[152:155], v[244:247], v[96:99]
	v_mfma_f32_16x16x32_bf16 v[104:107], v[156:159], v[244:247], v[104:107]
	ds_read_b128 v[244:247], v196 offset:22528
	s_waitcnt lgkmcnt(3)
	v_mfma_f32_16x16x32_bf16 v[116:119], v[144:147], v[248:251], v[116:119]
	v_mfma_f32_16x16x32_bf16 v[124:127], v[148:151], v[248:251], v[124:127]
	v_mfma_f32_16x16x32_bf16 v[100:103], v[152:155], v[248:251], v[100:103]
	v_mfma_f32_16x16x32_bf16 v[108:111], v[156:159], v[248:251], v[108:111]
	ds_read_b128 v[248:251], v196 offset:23552
	s_waitcnt vmcnt(6)
	ds_write_b128 v235, v[160:163] offset:8192
	ds_write_b128 v235, v[164:167] offset:12288
	s_waitcnt lgkmcnt(5)
	v_mfma_f32_16x16x32_bf16 v[80:83], v[144:147], v[236:239], v[80:83]
	v_mfma_f32_16x16x32_bf16 v[88:91], v[148:151], v[236:239], v[88:91]
	v_mfma_f32_16x16x32_bf16 v[48:51], v[152:155], v[236:239], v[48:51]
	v_mfma_f32_16x16x32_bf16 v[56:59], v[156:159], v[236:239], v[56:59]
	ds_read_b128 v[236:239], v196 offset:0
	s_waitcnt lgkmcnt(5)
	v_mfma_f32_16x16x32_bf16 v[84:87], v[144:147], v[240:243], v[84:87]
	v_mfma_f32_16x16x32_bf16 v[92:95], v[148:151], v[240:243], v[92:95]
	v_mfma_f32_16x16x32_bf16 v[52:55], v[152:155], v[240:243], v[52:55]
	v_mfma_f32_16x16x32_bf16 v[60:63], v[156:159], v[240:243], v[60:63]
	ds_read_b128 v[240:243], v196 offset:1024
	s_waitcnt lgkmcnt(2)
	s_barrier
	v_mfma_f32_16x16x32_bf16 v[64:67], v[144:147], v[244:247], v[64:67]
	v_mfma_f32_16x16x32_bf16 v[72:75], v[148:151], v[244:247], v[72:75]
	v_mfma_f32_16x16x32_bf16 v[32:35], v[152:155], v[244:247], v[32:35]
	v_mfma_f32_16x16x32_bf16 v[40:43], v[156:159], v[244:247], v[40:43]
	ds_read_b128 v[244:247], v196 offset:2048
	v_mfma_f32_16x16x32_bf16 v[68:71], v[144:147], v[248:251], v[68:71]
	v_mfma_f32_16x16x32_bf16 v[76:79], v[148:151], v[248:251], v[76:79]
	v_mfma_f32_16x16x32_bf16 v[36:39], v[152:155], v[248:251], v[36:39]
	v_mfma_f32_16x16x32_bf16 v[44:47], v[156:159], v[248:251], v[44:47]
	ds_read_b128 v[248:251], v196 offset:3072
	global_load_dwordx4 v[144:147], v[198:199], off
	global_load_dwordx4 v[148:151], v[198:199], off offset:256
	global_load_dwordx4 v[152:155], v[200:201], off
	global_load_dwordx4 v[156:159], v[200:201], off offset:256
	s_add_i32 s1, s1, 6
	s_cmp_lt_u32 s1, 30
	s_cbranch_scc1 .Lg16_proj_k
	s_add_i32 s3, s1, 3
	s_min_u32 s4, s3, 31
	s_lshl_b32 s96, s4, 13
	v_lshl_add_u64 v[166:167], v[188:189], 0, s[96:97]
	global_load_dwordx4 v[160:163], v[166:167], off offset:-2048
	global_load_dwordx4 v[164:167], v[166:167], off offset:2048
	s_add_i32 s3, s1, 2
	s_min_u32 s4, s3, 31
	s_lshl_b32 s96, s4, 11
	v_lshl_add_u64 v[198:199], v[184:185], 0, s[96:97]
	v_lshl_add_u64 v[200:201], v[186:187], 0, s[96:97]
	s_waitcnt vmcnt(8) lgkmcnt(3)
	v_mfma_f32_16x16x32_bf16 v[16:19], v[128:131], v[236:239], v[16:19]
	v_mfma_f32_16x16x32_bf16 v[24:27], v[132:135], v[236:239], v[24:27]
	v_mfma_f32_16x16x32_bf16 v[0:3], v[136:139], v[236:239], v[0:3]
	v_mfma_f32_16x16x32_bf16 v[8:11], v[140:143], v[236:239], v[8:11]
	ds_read_b128 v[236:239], v196 offset:4096
	s_waitcnt lgkmcnt(3)
	v_mfma_f32_16x16x32_bf16 v[20:23], v[128:131], v[240:243], v[20:23]
	v_mfma_f32_16x16x32_bf16 v[28:31], v[132:135], v[240:243], v[28:31]
	v_mfma_f32_16x16x32_bf16 v[4:7], v[136:139], v[240:243], v[4:7]
	v_mfma_f32_16x16x32_bf16 v[12:15], v[140:143], v[240:243], v[12:15]
	ds_read_b128 v[240:243], v196 offset:5120
	s_waitcnt lgkmcnt(3)
	v_mfma_f32_16x16x32_bf16 v[112:115], v[128:131], v[244:247], v[112:115]
	v_mfma_f32_16x16x32_bf16 v[120:123], v[132:135], v[244:247], v[120:123]
	v_mfma_f32_16x16x32_bf16 v[96:99], v[136:139], v[244:247], v[96:99]
	v_mfma_f32_16x16x32_bf16 v[104:107], v[140:143], v[244:247], v[104:107]
	ds_read_b128 v[244:247], v196 offset:6144
	s_waitcnt lgkmcnt(3)
	v_mfma_f32_16x16x32_bf16 v[116:119], v[128:131], v[248:251], v[116:119]
	v_mfma_f32_16x16x32_bf16 v[124:127], v[132:135], v[248:251], v[124:127]
	v_mfma_f32_16x16x32_bf16 v[100:103], v[136:139], v[248:251], v[100:103]
	v_mfma_f32_16x16x32_bf16 v[108:111], v[140:143], v[248:251], v[108:111]
	ds_read_b128 v[248:251], v196 offset:7168
	s_waitcnt vmcnt(6)
	ds_write_b128 v235, v[168:171] offset:16384
	ds_write_b128 v235, v[172:175] offset:20480
	s_waitcnt lgkmcnt(5)
	v_mfma_f32_16x16x32_bf16 v[80:83], v[128:131], v[236:239], v[80:83]
	v_mfma_f32_16x16x32_bf16 v[88:91], v[132:135], v[236:239], v[88:91]
	v_mfma_f32_16x16x32_bf16 v[48:51], v[136:139], v[236:239], v[48:51]
	v_mfma_f32_16x16x32_bf16 v[56:59], v[140:143], v[236:239], v[56:59]
	ds_read_b128 v[236:239], v196 offset:8192
	s_waitcnt lgkmcnt(5)
	v_mfma_f32_16x16x32_bf16 v[84:87], v[128:131], v[240:243], v[84:87]
	v_mfma_f32_16x16x32_bf16 v[92:95], v[132:135], v[240:243], v[92:95]
	v_mfma_f32_16x16x32_bf16 v[52:55], v[136:139], v[240:243], v[52:55]
	v_mfma_f32_16x16x32_bf16 v[60:63], v[140:143], v[240:243], v[60:63]
	ds_read_b128 v[240:243], v196 offset:9216
	s_waitcnt lgkmcnt(2)
	s_barrier
	v_mfma_f32_16x16x32_bf16 v[64:67], v[128:131], v[244:247], v[64:67]
	v_mfma_f32_16x16x32_bf16 v[72:75], v[132:135], v[244:247], v[72:75]
	v_mfma_f32_16x16x32_bf16 v[32:35], v[136:139], v[244:247], v[32:35]
	v_mfma_f32_16x16x32_bf16 v[40:43], v[140:143], v[244:247], v[40:43]
	ds_read_b128 v[244:247], v196 offset:10240
	v_mfma_f32_16x16x32_bf16 v[68:71], v[128:131], v[248:251], v[68:71]
	v_mfma_f32_16x16x32_bf16 v[76:79], v[132:135], v[248:251], v[76:79]
	v_mfma_f32_16x16x32_bf16 v[36:39], v[136:139], v[248:251], v[36:39]
	v_mfma_f32_16x16x32_bf16 v[44:47], v[140:143], v[248:251], v[44:47]
	ds_read_b128 v[248:251], v196 offset:11264
	global_load_dwordx4 v[128:131], v[198:199], off
	global_load_dwordx4 v[132:135], v[198:199], off offset:256
	global_load_dwordx4 v[136:139], v[200:201], off
	global_load_dwordx4 v[140:143], v[200:201], off offset:256
	s_add_i32 s3, s1, 4
	s_min_u32 s4, s3, 31
	s_lshl_b32 s96, s4, 13
	v_lshl_add_u64 v[174:175], v[188:189], 0, s[96:97]
	global_load_dwordx4 v[168:171], v[174:175], off offset:-2048
	global_load_dwordx4 v[172:175], v[174:175], off offset:2048
	s_add_i32 s3, s1, 3
	s_min_u32 s4, s3, 31
	s_lshl_b32 s96, s4, 11
	v_lshl_add_u64 v[198:199], v[184:185], 0, s[96:97]
	v_lshl_add_u64 v[200:201], v[186:187], 0, s[96:97]
	s_waitcnt vmcnt(8) lgkmcnt(3)
	v_mfma_f32_16x16x32_bf16 v[16:19], v[144:147], v[236:239], v[16:19]
	v_mfma_f32_16x16x32_bf16 v[24:27], v[148:151], v[236:239], v[24:27]
	v_mfma_f32_16x16x32_bf16 v[0:3], v[152:155], v[236:239], v[0:3]
	v_mfma_f32_16x16x32_bf16 v[8:11], v[156:159], v[236:239], v[8:11]
	ds_read_b128 v[236:239], v196 offset:12288
	s_waitcnt lgkmcnt(3)
	v_mfma_f32_16x16x32_bf16 v[20:23], v[144:147], v[240:243], v[20:23]
	v_mfma_f32_16x16x32_bf16 v[28:31], v[148:151], v[240:243], v[28:31]
	v_mfma_f32_16x16x32_bf16 v[4:7], v[152:155], v[240:243], v[4:7]
	v_mfma_f32_16x16x32_bf16 v[12:15], v[156:159], v[240:243], v[12:15]
	ds_read_b128 v[240:243], v196 offset:13312
	s_waitcnt lgkmcnt(3)
	v_mfma_f32_16x16x32_bf16 v[112:115], v[144:147], v[244:247], v[112:115]
	v_mfma_f32_16x16x32_bf16 v[120:123], v[148:151], v[244:247], v[120:123]
	v_mfma_f32_16x16x32_bf16 v[96:99], v[152:155], v[244:247], v[96:99]
	v_mfma_f32_16x16x32_bf16 v[104:107], v[156:159], v[244:247], v[104:107]
	ds_read_b128 v[244:247], v196 offset:14336
	s_waitcnt lgkmcnt(3)
	v_mfma_f32_16x16x32_bf16 v[116:119], v[144:147], v[248:251], v[116:119]
	v_mfma_f32_16x16x32_bf16 v[124:127], v[148:151], v[248:251], v[124:127]
	v_mfma_f32_16x16x32_bf16 v[100:103], v[152:155], v[248:251], v[100:103]
	v_mfma_f32_16x16x32_bf16 v[108:111], v[156:159], v[248:251], v[108:111]
	ds_read_b128 v[248:251], v196 offset:15360
	s_waitcnt vmcnt(6)
	ds_write_b128 v235, v[160:163] offset:0
	ds_write_b128 v235, v[164:167] offset:4096
	s_waitcnt lgkmcnt(5)
	v_mfma_f32_16x16x32_bf16 v[80:83], v[144:147], v[236:239], v[80:83]
	v_mfma_f32_16x16x32_bf16 v[88:91], v[148:151], v[236:239], v[88:91]
	v_mfma_f32_16x16x32_bf16 v[48:51], v[152:155], v[236:239], v[48:51]
	v_mfma_f32_16x16x32_bf16 v[56:59], v[156:159], v[236:239], v[56:59]
	ds_read_b128 v[236:239], v196 offset:16384
	s_waitcnt lgkmcnt(5)
	v_mfma_f32_16x16x32_bf16 v[84:87], v[144:147], v[240:243], v[84:87]
	v_mfma_f32_16x16x32_bf16 v[92:95], v[148:151], v[240:243], v[92:95]
	v_mfma_f32_16x16x32_bf16 v[52:55], v[152:155], v[240:243], v[52:55]
	v_mfma_f32_16x16x32_bf16 v[60:63], v[156:159], v[240:243], v[60:63]
	ds_read_b128 v[240:243], v196 offset:17408
	s_waitcnt lgkmcnt(2)
	s_barrier
	v_mfma_f32_16x16x32_bf16 v[64:67], v[144:147], v[244:247], v[64:67]
	v_mfma_f32_16x16x32_bf16 v[72:75], v[148:151], v[244:247], v[72:75]
	v_mfma_f32_16x16x32_bf16 v[32:35], v[152:155], v[244:247], v[32:35]
	v_mfma_f32_16x16x32_bf16 v[40:43], v[156:159], v[244:247], v[40:43]
	ds_read_b128 v[244:247], v196 offset:18432
	v_mfma_f32_16x16x32_bf16 v[68:71], v[144:147], v[248:251], v[68:71]
	v_mfma_f32_16x16x32_bf16 v[76:79], v[148:151], v[248:251], v[76:79]
	v_mfma_f32_16x16x32_bf16 v[36:39], v[152:155], v[248:251], v[36:39]
	v_mfma_f32_16x16x32_bf16 v[44:47], v[156:159], v[248:251], v[44:47]
	ds_read_b128 v[248:251], v196 offset:19456
	global_load_dwordx4 v[144:147], v[198:199], off
	global_load_dwordx4 v[148:151], v[198:199], off offset:256
	global_load_dwordx4 v[152:155], v[200:201], off
	global_load_dwordx4 v[156:159], v[200:201], off offset:256
	s_waitcnt lgkmcnt(0)
	s_nop 7
	v_permlane16_swap_b32_e32 v16, v20
	v_permlane16_swap_b32_e32 v17, v21
	v_permlane16_swap_b32_e32 v18, v22
	v_permlane16_swap_b32_e32 v19, v23
	v_permlane16_swap_b32_e32 v24, v28
	v_permlane16_swap_b32_e32 v25, v29
	v_permlane16_swap_b32_e32 v26, v30
	v_permlane16_swap_b32_e32 v27, v31
	v_permlane16_swap_b32_e32 v112, v116
	v_permlane16_swap_b32_e32 v113, v117
	v_permlane16_swap_b32_e32 v114, v118
	v_permlane16_swap_b32_e32 v115, v119
	v_permlane16_swap_b32_e32 v120, v124
	v_permlane16_swap_b32_e32 v121, v125
	v_permlane16_swap_b32_e32 v122, v126
	v_permlane16_swap_b32_e32 v123, v127
	v_permlane16_swap_b32_e32 v80, v84
	v_permlane16_swap_b32_e32 v81, v85
	v_permlane16_swap_b32_e32 v82, v86
	v_permlane16_swap_b32_e32 v83, v87
	v_permlane16_swap_b32_e32 v88, v92
	v_permlane16_swap_b32_e32 v89, v93
	v_permlane16_swap_b32_e32 v90, v94
	v_permlane16_swap_b32_e32 v91, v95
	v_permlane16_swap_b32_e32 v64, v68
	v_permlane16_swap_b32_e32 v65, v69
	v_permlane16_swap_b32_e32 v66, v70
	v_permlane16_swap_b32_e32 v67, v71
	v_permlane16_swap_b32_e32 v72, v76
	v_permlane16_swap_b32_e32 v73, v77
	v_permlane16_swap_b32_e32 v74, v78
	v_permlane16_swap_b32_e32 v75, v79
	v_permlane16_swap_b32_e32 v0, v4
	v_permlane16_swap_b32_e32 v1, v5
	v_permlane16_swap_b32_e32 v2, v6
	v_permlane16_swap_b32_e32 v3, v7
	v_permlane16_swap_b32_e32 v8, v12
	v_permlane16_swap_b32_e32 v9, v13
	v_permlane16_swap_b32_e32 v10, v14
	v_permlane16_swap_b32_e32 v11, v15
	v_permlane16_swap_b32_e32 v96, v100
	v_permlane16_swap_b32_e32 v97, v101
	v_permlane16_swap_b32_e32 v98, v102
	v_permlane16_swap_b32_e32 v99, v103
	v_permlane16_swap_b32_e32 v104, v108
	v_permlane16_swap_b32_e32 v105, v109
	v_permlane16_swap_b32_e32 v106, v110
	v_permlane16_swap_b32_e32 v107, v111
	v_permlane16_swap_b32_e32 v48, v52
	v_permlane16_swap_b32_e32 v49, v53
	v_permlane16_swap_b32_e32 v50, v54
	v_permlane16_swap_b32_e32 v51, v55
	v_permlane16_swap_b32_e32 v56, v60
	v_permlane16_swap_b32_e32 v57, v61
	v_permlane16_swap_b32_e32 v58, v62
	v_permlane16_swap_b32_e32 v59, v63
	v_permlane16_swap_b32_e32 v32, v36
	v_permlane16_swap_b32_e32 v33, v37
	v_permlane16_swap_b32_e32 v34, v38
	v_permlane16_swap_b32_e32 v35, v39
	v_permlane16_swap_b32_e32 v40, v44
	v_permlane16_swap_b32_e32 v41, v45
	v_permlane16_swap_b32_e32 v42, v46
	v_permlane16_swap_b32_e32 v43, v47
	v_permlane32_swap_b32_e32 v16, v20
	v_permlane32_swap_b32_e32 v17, v21
	v_permlane32_swap_b32_e32 v18, v22
	v_permlane32_swap_b32_e32 v19, v23
	v_permlane32_swap_b32_e32 v24, v28
	v_permlane32_swap_b32_e32 v25, v29
	v_permlane32_swap_b32_e32 v26, v30
	v_permlane32_swap_b32_e32 v27, v31
	v_permlane32_swap_b32_e32 v112, v116
	v_permlane32_swap_b32_e32 v113, v117
	v_permlane32_swap_b32_e32 v114, v118
	v_permlane32_swap_b32_e32 v115, v119
	v_permlane32_swap_b32_e32 v120, v124
	v_permlane32_swap_b32_e32 v121, v125
	v_permlane32_swap_b32_e32 v122, v126
	v_permlane32_swap_b32_e32 v123, v127
	v_permlane32_swap_b32_e32 v80, v84
	v_permlane32_swap_b32_e32 v81, v85
	v_permlane32_swap_b32_e32 v82, v86
	v_permlane32_swap_b32_e32 v83, v87
	v_permlane32_swap_b32_e32 v88, v92
	v_permlane32_swap_b32_e32 v89, v93
	v_permlane32_swap_b32_e32 v90, v94
	v_permlane32_swap_b32_e32 v91, v95
	v_permlane32_swap_b32_e32 v64, v68
	v_permlane32_swap_b32_e32 v65, v69
	v_permlane32_swap_b32_e32 v66, v70
	v_permlane32_swap_b32_e32 v67, v71
	v_permlane32_swap_b32_e32 v72, v76
	v_permlane32_swap_b32_e32 v73, v77
	v_permlane32_swap_b32_e32 v74, v78
	v_permlane32_swap_b32_e32 v75, v79
	v_permlane32_swap_b32_e32 v0, v4
	v_permlane32_swap_b32_e32 v1, v5
	v_permlane32_swap_b32_e32 v2, v6
	v_permlane32_swap_b32_e32 v3, v7
	v_permlane32_swap_b32_e32 v8, v12
	v_permlane32_swap_b32_e32 v9, v13
	v_permlane32_swap_b32_e32 v10, v14
	v_permlane32_swap_b32_e32 v11, v15
	v_permlane32_swap_b32_e32 v96, v100
	v_permlane32_swap_b32_e32 v97, v101
	v_permlane32_swap_b32_e32 v98, v102
	v_permlane32_swap_b32_e32 v99, v103
	v_permlane32_swap_b32_e32 v104, v108
	v_permlane32_swap_b32_e32 v105, v109
	v_permlane32_swap_b32_e32 v106, v110
	v_permlane32_swap_b32_e32 v107, v111
	v_permlane32_swap_b32_e32 v48, v52
	v_permlane32_swap_b32_e32 v49, v53
	v_permlane32_swap_b32_e32 v50, v54
	v_permlane32_swap_b32_e32 v51, v55
	v_permlane32_swap_b32_e32 v56, v60
	v_permlane32_swap_b32_e32 v57, v61
	v_permlane32_swap_b32_e32 v58, v62
	v_permlane32_swap_b32_e32 v59, v63
	v_permlane32_swap_b32_e32 v32, v36
	v_permlane32_swap_b32_e32 v33, v37
	v_permlane32_swap_b32_e32 v34, v38
	v_permlane32_swap_b32_e32 v35, v39
	v_permlane32_swap_b32_e32 v40, v44
	v_permlane32_swap_b32_e32 v41, v45
	v_permlane32_swap_b32_e32 v42, v46
	v_permlane32_swap_b32_e32 v43, v47
	s_waitcnt vmcnt(0)
	s_lshl_b32 s12, s2, 8
	s_cmp_eq_u32 s0, 23
	s_mov_b64 s[2:3], -1
	s_cbranch_scc1 .LBB0_347
	s_movk_i32 s1, 0x2400
	s_waitcnt vmcnt(6)
	v_and_b32_e32 v130, 0xffffffc0, v181
	s_cmp_gt_i32 s0, 10
	v_mul_lo_u32 v129, v233, s1
	v_and_b32_e32 v128, 56, v234
	v_add_u32_e32 v131, s12, v130
	s_cselect_b64 s[2:3], -1, 0
	s_cmp_gt_u32 s0, 19
	v_mul_u32_u24_e32 v130, 0x120, v183
	s_waitcnt vmcnt(0)
	v_lshl_or_b32 v132, v128, 1, v129
	v_lshl_or_b32 v128, s0, 7, v128
	s_cselect_b64 s[0:1], -1, 0
	v_lshl_add_u32 v129, v130, 1, v129
	v_lshl_or_b32 v130, v231, 1, v129
	v_cvt_pk_bf16_f32 v112, v112, s0
	ds_write_b16 v130, v112 offset:64
	v_cvt_pk_bf16_f32 v112, v17, s0
	v_cvt_pk_bf16_f32 v96, v96, s0
	ds_write_b16 v130, v112 offset:144
	v_cvt_pk_bf16_f32 v112, v113, s0
	ds_write_b16 v130, v96 offset:4672
	v_cvt_pk_bf16_f32 v96, v1, s0
	ds_write_b16 v130, v112 offset:208
	v_cvt_pk_bf16_f32 v112, v18, s0
	ds_write_b16 v130, v96 offset:4752
	v_cvt_pk_bf16_f32 v96, v97, s0
	ds_write_b16 v130, v112 offset:288
	v_cvt_pk_bf16_f32 v112, v114, s0
	ds_write_b16 v130, v96 offset:4816
	v_cvt_pk_bf16_f32 v96, v2, s0
	ds_write_b16 v130, v112 offset:352
	v_cvt_pk_bf16_f32 v112, v19, s0
	ds_write_b16 v130, v96 offset:4896
	v_cvt_pk_bf16_f32 v96, v98, s0
	ds_write_b16 v130, v112 offset:432
	v_cvt_pk_bf16_f32 v112, v115, s0
	ds_write_b16 v130, v96 offset:4960
	v_cvt_pk_bf16_f32 v96, v3, s0
	ds_write_b16 v130, v112 offset:496
	v_cvt_pk_bf16_f32 v112, v20, s0
	ds_write_b16 v130, v96 offset:5040
	v_cvt_pk_bf16_f32 v96, v99, s0
	ds_write_b16 v130, v112 offset:1152
	v_cvt_pk_bf16_f32 v112, v116, s0
	ds_write_b16 v130, v96 offset:5104
	v_cvt_pk_bf16_f32 v96, v4, s0
	ds_write_b16 v130, v112 offset:1216
	v_cvt_pk_bf16_f32 v112, v21, s0
	ds_write_b16 v130, v96 offset:5760
	v_cvt_pk_bf16_f32 v96, v100, s0
	ds_write_b16 v130, v112 offset:1296
	v_cvt_pk_bf16_f32 v112, v117, s0
	ds_write_b16 v130, v96 offset:5824
	v_cvt_pk_bf16_f32 v96, v5, s0
	ds_write_b16 v130, v112 offset:1360
	v_cvt_pk_bf16_f32 v112, v22, s0
	ds_write_b16 v130, v96 offset:5904
	v_cvt_pk_bf16_f32 v96, v101, s0
	ds_write_b16 v130, v112 offset:1440
	v_cvt_pk_bf16_f32 v112, v118, s0
	ds_write_b16 v130, v96 offset:5968
	v_cvt_pk_bf16_f32 v96, v6, s0
	ds_write_b16 v130, v112 offset:1504
	v_cvt_pk_bf16_f32 v112, v23, s0
	ds_write_b16 v130, v96 offset:6048
	v_cvt_pk_bf16_f32 v96, v102, s0
	ds_write_b16 v130, v112 offset:1584
	v_cvt_pk_bf16_f32 v112, v119, s0
	ds_write_b16 v130, v96 offset:6112
	v_cvt_pk_bf16_f32 v96, v7, s0
	ds_write_b16 v130, v112 offset:1648
	v_cvt_pk_bf16_f32 v112, v24, s0
	ds_write_b16 v130, v96 offset:6192
	v_cvt_pk_bf16_f32 v96, v103, s0
	ds_write_b16 v130, v112 offset:2304
	v_cvt_pk_bf16_f32 v112, v120, s0
	ds_write_b16 v130, v96 offset:6256
	v_cvt_pk_bf16_f32 v96, v8, s0
	ds_write_b16 v130, v112 offset:2368
	v_cvt_pk_bf16_f32 v112, v25, s0
	ds_write_b16 v130, v96 offset:6912
	v_cvt_pk_bf16_f32 v96, v104, s0
	ds_write_b16 v130, v112 offset:2448
	v_cvt_pk_bf16_f32 v112, v121, s0
	ds_write_b16 v130, v96 offset:6976
	v_cvt_pk_bf16_f32 v96, v9, s0
	ds_write_b16 v130, v112 offset:2512
	v_cvt_pk_bf16_f32 v112, v26, s0
	ds_write_b16 v130, v96 offset:7056
	v_cvt_pk_bf16_f32 v96, v105, s0
	ds_write_b16 v130, v112 offset:2592
	v_cvt_pk_bf16_f32 v112, v122, s0
	ds_write_b16 v130, v96 offset:7120
	v_cvt_pk_bf16_f32 v96, v10, s0
	ds_write_b16 v130, v112 offset:2656
	v_cvt_pk_bf16_f32 v112, v27, s0
	ds_write_b16 v130, v96 offset:7200
	v_cvt_pk_bf16_f32 v96, v106, s0
	ds_write_b16 v130, v112 offset:2736
	v_cvt_pk_bf16_f32 v112, v123, s0
	ds_write_b16 v130, v96 offset:7264
	v_cvt_pk_bf16_f32 v96, v11, s0
	ds_write_b16 v130, v112 offset:2800
	v_cvt_pk_bf16_f32 v112, v28, s0
	ds_write_b16 v130, v96 offset:7344
	v_cvt_pk_bf16_f32 v96, v107, s0
	ds_write_b16 v130, v112 offset:3456
	v_cvt_pk_bf16_f32 v112, v124, s0
	ds_write_b16 v130, v96 offset:7408
	v_cvt_pk_bf16_f32 v96, v12, s0
	ds_write_b16 v130, v112 offset:3520
	v_cvt_pk_bf16_f32 v112, v29, s0
	ds_write_b16 v130, v96 offset:8064
	v_cvt_pk_bf16_f32 v96, v108, s0
	ds_write_b16 v130, v112 offset:3600
	v_cvt_pk_bf16_f32 v112, v125, s0
	ds_write_b16 v130, v96 offset:8128
	v_cvt_pk_bf16_f32 v96, v13, s0
	ds_write_b16 v130, v112 offset:3664
	v_cvt_pk_bf16_f32 v112, v30, s0
	ds_write_b16 v130, v96 offset:8208
	v_cvt_pk_bf16_f32 v96, v109, s0
	ds_write_b16 v130, v112 offset:3744
	v_cvt_pk_bf16_f32 v112, v126, s0
	ds_write_b16 v130, v96 offset:8272
	v_cvt_pk_bf16_f32 v96, v14, s0
	ds_write_b16 v130, v112 offset:3808
	v_cvt_pk_bf16_f32 v112, v31, s0
	ds_write_b16 v130, v96 offset:8352
	v_cvt_pk_bf16_f32 v96, v110, s0
	ds_write_b16 v130, v112 offset:3888
	v_cvt_pk_bf16_f32 v112, v127, s0
	ds_write_b16 v130, v96 offset:8416
	v_cvt_pk_bf16_f32 v96, v15, s0
	v_cvt_pk_bf16_f32 v133, v16, s0
	ds_write_b16 v130, v112 offset:3952
	v_cvt_pk_bf16_f32 v112, v0, s0
	ds_write_b16 v130, v96 offset:8496
	v_cvt_pk_bf16_f32 v96, v111, s0
	ds_write_b16 v130, v133
	ds_write_b16 v130, v112 offset:4608
	ds_write_b16 v130, v96 offset:8560
	v_lshrrev_b32_e32 v109, 3, v232
	s_waitcnt lgkmcnt(0)
	v_mad_u32_u24 v96, v109, s42, v132
	ds_read_b128 v[96:99], v96
	v_mov_b32_e32 v176, v128
	v_or_b32_e32 v110, v131, v109
	s_mov_b64 s[4:5], -1
	s_and_b64 vcc, exec, s[2:3]
	s_cbranch_vccz .LBB0_224
	s_and_b64 vcc, exec, s[0:1]
	s_cbranch_vccz .LBB0_221
	v_readlane_b32 s16, v254, 15
	v_readlane_b32 s18, v254, 17
	v_readlane_b32 s19, v254, 18
	v_readlane_b32 s17, v254, 16
	v_readlane_b32 s20, v254, 19
	v_mov_b64_e32 v[100:101], s[18:19]
	v_mad_i64_i32 v[100:101], s[4:5], v110, s89, v[100:101]
	s_movk_i32 s4, 0xec00
	v_lshl_add_u64 v[100:101], v[176:177], 1, v[100:101]
	s_mov_b32 s5, -1
	v_readlane_b32 s21, v254, 20
	v_readlane_b32 s22, v254, 21
	v_readlane_b32 s23, v254, 22
	v_readlane_b32 s24, v254, 23
	v_readlane_b32 s25, v254, 24
	v_readlane_b32 s26, v254, 25
	v_readlane_b32 s27, v254, 26
	v_readlane_b32 s28, v254, 27
	v_readlane_b32 s29, v254, 28
	v_readlane_b32 s30, v254, 29
	v_readlane_b32 s31, v254, 30
	v_lshl_add_u64 v[100:101], v[100:101], 0, s[4:5]
	s_mov_b64 s[4:5], 0

.LBB0_923:
	s_ashr_i32 s2, s4, 31
	s_lshr_b32 s2, s2, 26
	s_add_i32 s2, s4, s2
	s_ashr_i32 s3, s2, 6
	s_lshl_b32 s3, s3, 3
	s_sub_i32 s8, s25, s3
	s_min_i32 s8, s8, 8
	s_abs_i32 s9, s8
	v_cvt_f32_u32_e32 v0, s9
	s_sub_i32 s12, 0, s9
	s_andn2_b32 s2, s2, 63
	s_sub_i32 s10, s4, s2
	v_rcp_iflag_f32_e32 v0, v0
	s_abs_i32 s2, s10
	s_xor_b32 s11, s10, s8
	s_ashr_i32 s11, s11, 31
	v_mul_f32_e32 v0, 0x4f7ffffe, v0
	v_cvt_u32_f32_e32 v0, v0
	v_mov_b32_e32 v181, v179
	v_readfirstlane_b32 s13, v0
	s_mul_i32 s12, s12, s13
	s_mul_hi_u32 s12, s13, s12
	s_add_i32 s13, s13, s12
	s_mul_hi_u32 s12, s2, s13
	s_mul_i32 s13, s12, s9
	s_sub_i32 s2, s2, s13
	s_add_i32 s14, s12, 1
	s_sub_i32 s13, s2, s9
	s_cmp_ge_u32 s2, s9
	s_cselect_b32 s12, s14, s12
	s_cselect_b32 s2, s13, s2
	s_add_i32 s13, s12, 1
	s_cmp_ge_u32 s2, s9
	s_cselect_b32 s2, s13, s12
	s_xor_b32 s2, s2, s11
	s_sub_i32 s2, s2, s11
	s_mul_i32 s8, s8, s2
	s_add_i32 s3, s3, s7
	s_sub_i32 s8, s10, s8
	v_ashrrev_i32_e32 v237, 6, v181
	s_add_i32 s8, s3, s8
	v_lshlrev_b32_e32 v0, 1, v237
	v_lshl_add_u32 v0, s8, 3, v0
	v_ashrrev_i32_e32 v1, 31, v0
	v_bfe_u32 v183, v181, 5, 1
	v_lshlrev_b64 v[0:1], 16, v[0:1]
	v_and_b32_e32 v238, 31, v181
	v_lshl_add_u64 v[0:1], s[64:65], 0, v[0:1]
	v_lshlrev_b32_e32 v176, 9, v183
	s_ashr_i32 s3, s2, 31
	v_lshl_add_u64 v[0:1], v[0:1], 0, v[176:177]
	v_lshlrev_b32_e32 v176, 4, v238
	v_ashrrev_i32_e32 v40, 2, v181
	s_lshl_b64 s[10:11], s[2:3], 18
	v_lshl_add_u64 v[184:185], v[0:1], 0, v[176:177]
	s_add_u32 s10, s5, s10
	v_lshlrev_b32_e32 v0, 5, v40
	s_addc_u32 s11, s6, s11
	v_ashrrev_i32_e32 v1, 31, v0
	v_lshlrev_b32_e32 v2, 4, v181
	v_lshl_add_u64 v[0:1], v[0:1], 1, s[10:11]
	v_and_b32_e32 v176, 48, v2
	v_lshl_add_u64 v[186:187], v[0:1], 0, v[176:177]
	s_movk_i32 s3, 0x2000
	v_add_co_u32_e32 v36, vcc, s3, v186
	v_mul_u32_u24_e32 v38, 40, v238
	s_nop 0
	v_addc_co_u32_e32 v37, vcc, 0, v187, vcc
	v_lshlrev_b32_e32 v39, 4, v183
	v_lshl_add_u32 v240, v38, 1, v39
	v_add_co_u32_e32 v38, vcc, s41, v184
	s_movk_i32 s9, 0x50
	s_nop 0
	v_addc_co_u32_e32 v39, vcc, 0, v185, vcc
	v_and_b32_e32 v239, 63, v181
	v_mov_b32_e32 v176, 0x800
	v_lshl_add_u64 v[188:189], v[186:187], 0, v[176:177]
	v_bfe_u32 v247, v181, 4, 1
	v_lshlrev_b32_e32 v176, 9, v183
	v_lshl_add_u32 v176, v247, 8, v176
	v_lshl_add_u64 v[184:185], v[184:185], 0, v[176:177]
	v_mov_b32_e32 v176, s41
	v_lshl_add_u64 v[186:187], v[184:185], 0, v[176:177]
	v_lshrrev_b32_e32 v241, 2, v181
	v_bfe_u32 v247, v181, 4, 2
	v_lshlrev_b32_e32 v247, 1, v247
	v_mov_b32_e32 v176, 0x78
	v_lshrrev_b32_e32 v247, v247, v176
	v_and_b32_e32 v247, 3, v247
	v_and_b32_e32 v246, 3, v181
	v_xor_b32_e32 v247, v247, v246
	v_lshlrev_b32_e32 v247, 4, v247
	v_lshl_add_u32 v241, v241, 6, v247
	v_bfe_u32 v247, v181, 2, 2
	v_lshlrev_b32_e32 v247, 1, v247
	v_lshrrev_b32_e32 v247, v247, v176
	v_and_b32_e32 v247, 3, v247
	v_bfe_u32 v246, v181, 4, 2
	v_xor_b32_e32 v247, v247, v246
	v_lshlrev_b32_e32 v247, 4, v247
	v_and_b32_e32 v246, 15, v181
	v_lshl_add_u32 v246, v246, 6, v247
	s_mov_b32 s96, 0
	v_lshl_add_u64 v[166:167], v[188:189], 0, s[96:97]
	global_load_dwordx4 v[160:163], v[166:167], off offset:-2048
	global_load_dwordx4 v[164:167], v[166:167], off offset:2048
	s_movk_i32 s96, 0x2000
	v_lshl_add_u64 v[174:175], v[188:189], 0, s[96:97]
	global_load_dwordx4 v[168:171], v[174:175], off offset:-2048
	global_load_dwordx4 v[172:175], v[174:175], off offset:2048
	s_mov_b32 s96, 0
	v_lshl_add_u64 v[248:249], v[184:185], 0, s[96:97]
	v_lshl_add_u64 v[250:251], v[186:187], 0, s[96:97]
	global_load_dwordx4 v[128:131], v[248:249], off
	global_load_dwordx4 v[132:135], v[248:249], off offset:256
	global_load_dwordx4 v[136:139], v[250:251], off
	global_load_dwordx4 v[140:143], v[250:251], off offset:256
	v_mov_b32_e32 v0, 0
	v_mov_b32_e32 v1, 0
	v_mov_b32_e32 v2, 0
	v_mov_b32_e32 v3, 0
	v_mov_b32_e32 v4, 0
	v_mov_b32_e32 v5, 0
	v_mov_b32_e32 v6, 0
	v_mov_b32_e32 v7, 0
	v_mov_b32_e32 v8, 0
	v_mov_b32_e32 v9, 0
	v_mov_b32_e32 v10, 0
	v_mov_b32_e32 v11, 0
	v_mov_b32_e32 v12, 0
	v_mov_b32_e32 v13, 0
	v_mov_b32_e32 v14, 0
	v_mov_b32_e32 v15, 0
	v_mov_b32_e32 v16, 0
	v_mov_b32_e32 v17, 0
	v_mov_b32_e32 v18, 0
	v_mov_b32_e32 v19, 0
	v_mov_b32_e32 v20, 0
	v_mov_b32_e32 v21, 0
	v_mov_b32_e32 v22, 0
	v_mov_b32_e32 v23, 0
	v_mov_b32_e32 v24, 0
	v_mov_b32_e32 v25, 0
	v_mov_b32_e32 v26, 0
	v_mov_b32_e32 v27, 0
	v_mov_b32_e32 v28, 0
	v_mov_b32_e32 v29, 0
	v_mov_b32_e32 v30, 0
	v_mov_b32_e32 v31, 0
	v_mov_b32_e32 v32, 0
	v_mov_b32_e32 v33, 0
	v_mov_b32_e32 v34, 0
	v_mov_b32_e32 v35, 0
	v_mov_b32_e32 v36, 0
	v_mov_b32_e32 v37, 0
	v_mov_b32_e32 v38, 0
	v_mov_b32_e32 v39, 0
	v_mov_b32_e32 v40, 0
	v_mov_b32_e32 v41, 0
	v_mov_b32_e32 v42, 0
	v_mov_b32_e32 v43, 0
	v_mov_b32_e32 v44, 0
	v_mov_b32_e32 v45, 0
	v_mov_b32_e32 v46, 0
	v_mov_b32_e32 v47, 0
	v_mov_b32_e32 v48, 0
	v_mov_b32_e32 v49, 0
	v_mov_b32_e32 v50, 0
	v_mov_b32_e32 v51, 0
	v_mov_b32_e32 v52, 0
	v_mov_b32_e32 v53, 0
	v_mov_b32_e32 v54, 0
	v_mov_b32_e32 v55, 0
	v_mov_b32_e32 v56, 0
	v_mov_b32_e32 v57, 0
	v_mov_b32_e32 v58, 0
	v_mov_b32_e32 v59, 0
	v_mov_b32_e32 v60, 0
	v_mov_b32_e32 v61, 0
	v_mov_b32_e32 v62, 0
	v_mov_b32_e32 v63, 0
	v_mov_b32_e32 v64, 0
	v_mov_b32_e32 v65, 0
	v_mov_b32_e32 v66, 0
	v_mov_b32_e32 v67, 0
	v_mov_b32_e32 v68, 0
	v_mov_b32_e32 v69, 0
	v_mov_b32_e32 v70, 0
	v_mov_b32_e32 v71, 0
	v_mov_b32_e32 v72, 0
	v_mov_b32_e32 v73, 0
	v_mov_b32_e32 v74, 0
	v_mov_b32_e32 v75, 0
	v_mov_b32_e32 v76, 0
	v_mov_b32_e32 v77, 0
	v_mov_b32_e32 v78, 0
	v_mov_b32_e32 v79, 0
	v_mov_b32_e32 v80, 0
	v_mov_b32_e32 v81, 0
	v_mov_b32_e32 v82, 0
	v_mov_b32_e32 v83, 0
	v_mov_b32_e32 v84, 0
	v_mov_b32_e32 v85, 0
	v_mov_b32_e32 v86, 0
	v_mov_b32_e32 v87, 0
	v_mov_b32_e32 v88, 0
	v_mov_b32_e32 v89, 0
	v_mov_b32_e32 v90, 0
	v_mov_b32_e32 v91, 0
	v_mov_b32_e32 v92, 0
	v_mov_b32_e32 v93, 0
	v_mov_b32_e32 v94, 0
	v_mov_b32_e32 v95, 0
	v_mov_b32_e32 v96, 0
	v_mov_b32_e32 v97, 0
	v_mov_b32_e32 v98, 0
	v_mov_b32_e32 v99, 0
	v_mov_b32_e32 v100, 0
	v_mov_b32_e32 v101, 0
	v_mov_b32_e32 v102, 0
	v_mov_b32_e32 v103, 0
	v_mov_b32_e32 v104, 0
	v_mov_b32_e32 v105, 0
	v_mov_b32_e32 v106, 0
	v_mov_b32_e32 v107, 0
	v_mov_b32_e32 v108, 0
	v_mov_b32_e32 v109, 0
	v_mov_b32_e32 v110, 0
	v_mov_b32_e32 v111, 0
	v_mov_b32_e32 v112, 0
	v_mov_b32_e32 v113, 0
	v_mov_b32_e32 v114, 0
	v_mov_b32_e32 v115, 0
	v_mov_b32_e32 v116, 0
	v_mov_b32_e32 v117, 0
	v_mov_b32_e32 v118, 0
	v_mov_b32_e32 v119, 0
	v_mov_b32_e32 v120, 0
	v_mov_b32_e32 v121, 0
	v_mov_b32_e32 v122, 0
	v_mov_b32_e32 v123, 0
	v_mov_b32_e32 v124, 0
	v_mov_b32_e32 v125, 0
	v_mov_b32_e32 v126, 0
	v_mov_b32_e32 v127, 0
	s_mov_b32 s3, 0
	s_waitcnt vmcnt(4)
	ds_write_b128 v241, v[160:163]
	ds_write_b128 v241, v[164:167] offset:4096
	ds_write_b128 v241, v[168:171] offset:8192
	ds_write_b128 v241, v[172:175] offset:12288
	s_nop 3
	s_movk_i32 s96, 0x4000
	v_lshl_add_u64 v[174:175], v[188:189], 0, s[96:97]
	global_load_dwordx4 v[168:171], v[174:175], off offset:-2048
	global_load_dwordx4 v[172:175], v[174:175], off offset:2048
	s_movk_i32 s96, 0x800
	v_lshl_add_u64 v[248:249], v[184:185], 0, s[96:97]
	v_lshl_add_u64 v[250:251], v[186:187], 0, s[96:97]
	global_load_dwordx4 v[144:147], v[248:249], off
	global_load_dwordx4 v[148:151], v[248:249], off offset:256
	global_load_dwordx4 v[152:155], v[250:251], off
	global_load_dwordx4 v[156:159], v[250:251], off offset:256
	s_waitcnt lgkmcnt(0)
	s_barrier
	ds_read_b128 v[196:199], v246 offset:0
	ds_read_b128 v[200:203], v246 offset:1024
	ds_read_b128 v[204:207], v246 offset:2048
	ds_read_b128 v[242:245], v246 offset:3072
.Lg16_out_k:
	s_add_i32 s9, s3, 3
	s_min_u32 s10, s9, 31
	s_lshl_b32 s96, s10, 13
	v_lshl_add_u64 v[166:167], v[188:189], 0, s[96:97]
	global_load_dwordx4 v[160:163], v[166:167], off offset:-2048
	global_load_dwordx4 v[164:167], v[166:167], off offset:2048
	s_add_i32 s9, s3, 2
	s_min_u32 s10, s9, 31
	s_lshl_b32 s96, s10, 11
	v_lshl_add_u64 v[248:249], v[184:185], 0, s[96:97]
	v_lshl_add_u64 v[250:251], v[186:187], 0, s[96:97]
	s_waitcnt vmcnt(8) lgkmcnt(3)
	v_mfma_f32_16x16x32_bf16 v[112:115], v[128:131], v[196:199], v[112:115]
	v_mfma_f32_16x16x32_bf16 v[120:123], v[132:135], v[196:199], v[120:123]
	v_mfma_f32_16x16x32_bf16 v[48:51], v[136:139], v[196:199], v[48:51]
	v_mfma_f32_16x16x32_bf16 v[56:59], v[140:143], v[196:199], v[56:59]
	ds_read_b128 v[196:199], v246 offset:4096
	s_waitcnt lgkmcnt(3)
	v_mfma_f32_16x16x32_bf16 v[116:119], v[128:131], v[200:203], v[116:119]
	v_mfma_f32_16x16x32_bf16 v[124:127], v[132:135], v[200:203], v[124:127]
	v_mfma_f32_16x16x32_bf16 v[52:55], v[136:139], v[200:203], v[52:55]
	v_mfma_f32_16x16x32_bf16 v[60:63], v[140:143], v[200:203], v[60:63]
	ds_read_b128 v[200:203], v246 offset:5120
	s_waitcnt lgkmcnt(3)
	v_mfma_f32_16x16x32_bf16 v[96:99], v[128:131], v[204:207], v[96:99]
	v_mfma_f32_16x16x32_bf16 v[104:107], v[132:135], v[204:207], v[104:107]
	v_mfma_f32_16x16x32_bf16 v[32:35], v[136:139], v[204:207], v[32:35]
	v_mfma_f32_16x16x32_bf16 v[40:43], v[140:143], v[204:207], v[40:43]
	ds_read_b128 v[204:207], v246 offset:6144
	s_waitcnt lgkmcnt(3)
	v_mfma_f32_16x16x32_bf16 v[100:103], v[128:131], v[242:245], v[100:103]
	v_mfma_f32_16x16x32_bf16 v[108:111], v[132:135], v[242:245], v[108:111]
	v_mfma_f32_16x16x32_bf16 v[36:39], v[136:139], v[242:245], v[36:39]
	v_mfma_f32_16x16x32_bf16 v[44:47], v[140:143], v[242:245], v[44:47]
	ds_read_b128 v[242:245], v246 offset:7168
	s_waitcnt vmcnt(6)
	ds_write_b128 v241, v[168:171] offset:16384
	ds_write_b128 v241, v[172:175] offset:20480
	s_waitcnt lgkmcnt(5)
	v_mfma_f32_16x16x32_bf16 v[80:83], v[128:131], v[196:199], v[80:83]
	v_mfma_f32_16x16x32_bf16 v[88:91], v[132:135], v[196:199], v[88:91]
	v_mfma_f32_16x16x32_bf16 v[16:19], v[136:139], v[196:199], v[16:19]
	v_mfma_f32_16x16x32_bf16 v[24:27], v[140:143], v[196:199], v[24:27]
	ds_read_b128 v[196:199], v246 offset:8192
	s_waitcnt lgkmcnt(5)
	v_mfma_f32_16x16x32_bf16 v[84:87], v[128:131], v[200:203], v[84:87]
	v_mfma_f32_16x16x32_bf16 v[92:95], v[132:135], v[200:203], v[92:95]
	v_mfma_f32_16x16x32_bf16 v[20:23], v[136:139], v[200:203], v[20:23]
	v_mfma_f32_16x16x32_bf16 v[28:31], v[140:143], v[200:203], v[28:31]
	ds_read_b128 v[200:203], v246 offset:9216
	s_waitcnt lgkmcnt(2)
	s_barrier
	v_mfma_f32_16x16x32_bf16 v[64:67], v[128:131], v[204:207], v[64:67]
	v_mfma_f32_16x16x32_bf16 v[72:75], v[132:135], v[204:207], v[72:75]
	v_mfma_f32_16x16x32_bf16 v[0:3], v[136:139], v[204:207], v[0:3]
	v_mfma_f32_16x16x32_bf16 v[8:11], v[140:143], v[204:207], v[8:11]
	ds_read_b128 v[204:207], v246 offset:10240
	v_mfma_f32_16x16x32_bf16 v[68:71], v[128:131], v[242:245], v[68:71]
	v_mfma_f32_16x16x32_bf16 v[76:79], v[132:135], v[242:245], v[76:79]
	v_mfma_f32_16x16x32_bf16 v[4:7], v[136:139], v[242:245], v[4:7]
	v_mfma_f32_16x16x32_bf16 v[12:15], v[140:143], v[242:245], v[12:15]
	ds_read_b128 v[242:245], v246 offset:11264
	global_load_dwordx4 v[128:131], v[248:249], off
	global_load_dwordx4 v[132:135], v[248:249], off offset:256
	global_load_dwordx4 v[136:139], v[250:251], off
	global_load_dwordx4 v[140:143], v[250:251], off offset:256
	s_add_i32 s9, s3, 4
	s_min_u32 s10, s9, 31
	s_lshl_b32 s96, s10, 13
	v_lshl_add_u64 v[174:175], v[188:189], 0, s[96:97]
	global_load_dwordx4 v[168:171], v[174:175], off offset:-2048
	global_load_dwordx4 v[172:175], v[174:175], off offset:2048
	s_add_i32 s9, s3, 3
	s_min_u32 s10, s9, 31
	s_lshl_b32 s96, s10, 11
	v_lshl_add_u64 v[248:249], v[184:185], 0, s[96:97]
	v_lshl_add_u64 v[250:251], v[186:187], 0, s[96:97]
	s_waitcnt vmcnt(8) lgkmcnt(3)
	v_mfma_f32_16x16x32_bf16 v[112:115], v[144:147], v[196:199], v[112:115]
	v_mfma_f32_16x16x32_bf16 v[120:123], v[148:151], v[196:199], v[120:123]
	v_mfma_f32_16x16x32_bf16 v[48:51], v[152:155], v[196:199], v[48:51]
	v_mfma_f32_16x16x32_bf16 v[56:59], v[156:159], v[196:199], v[56:59]
	ds_read_b128 v[196:199], v246 offset:12288
	s_waitcnt lgkmcnt(3)
	v_mfma_f32_16x16x32_bf16 v[116:119], v[144:147], v[200:203], v[116:119]
	v_mfma_f32_16x16x32_bf16 v[124:127], v[148:151], v[200:203], v[124:127]
	v_mfma_f32_16x16x32_bf16 v[52:55], v[152:155], v[200:203], v[52:55]
	v_mfma_f32_16x16x32_bf16 v[60:63], v[156:159], v[200:203], v[60:63]
	ds_read_b128 v[200:203], v246 offset:13312
	s_waitcnt lgkmcnt(3)
	v_mfma_f32_16x16x32_bf16 v[96:99], v[144:147], v[204:207], v[96:99]
	v_mfma_f32_16x16x32_bf16 v[104:107], v[148:151], v[204:207], v[104:107]
	v_mfma_f32_16x16x32_bf16 v[32:35], v[152:155], v[204:207], v[32:35]
	v_mfma_f32_16x16x32_bf16 v[40:43], v[156:159], v[204:207], v[40:43]
	ds_read_b128 v[204:207], v246 offset:14336
	s_waitcnt lgkmcnt(3)
	v_mfma_f32_16x16x32_bf16 v[100:103], v[144:147], v[242:245], v[100:103]
	v_mfma_f32_16x16x32_bf16 v[108:111], v[148:151], v[242:245], v[108:111]
	v_mfma_f32_16x16x32_bf16 v[36:39], v[152:155], v[242:245], v[36:39]
	v_mfma_f32_16x16x32_bf16 v[44:47], v[156:159], v[242:245], v[44:47]
	ds_read_b128 v[242:245], v246 offset:15360
	s_waitcnt vmcnt(6)
	ds_write_b128 v241, v[160:163] offset:0
	ds_write_b128 v241, v[164:167] offset:4096
	s_waitcnt lgkmcnt(5)
	v_mfma_f32_16x16x32_bf16 v[80:83], v[144:147], v[196:199], v[80:83]
	v_mfma_f32_16x16x32_bf16 v[88:91], v[148:151], v[196:199], v[88:91]
	v_mfma_f32_16x16x32_bf16 v[16:19], v[152:155], v[196:199], v[16:19]
	v_mfma_f32_16x16x32_bf16 v[24:27], v[156:159], v[196:199], v[24:27]
	ds_read_b128 v[196:199], v246 offset:16384
	s_waitcnt lgkmcnt(5)
	v_mfma_f32_16x16x32_bf16 v[84:87], v[144:147], v[200:203], v[84:87]
	v_mfma_f32_16x16x32_bf16 v[92:95], v[148:151], v[200:203], v[92:95]
	v_mfma_f32_16x16x32_bf16 v[20:23], v[152:155], v[200:203], v[20:23]
	v_mfma_f32_16x16x32_bf16 v[28:31], v[156:159], v[200:203], v[28:31]
	ds_read_b128 v[200:203], v246 offset:17408
	s_waitcnt lgkmcnt(2)
	s_barrier
	v_mfma_f32_16x16x32_bf16 v[64:67], v[144:147], v[204:207], v[64:67]
	v_mfma_f32_16x16x32_bf16 v[72:75], v[148:151], v[204:207], v[72:75]
	v_mfma_f32_16x16x32_bf16 v[0:3], v[152:155], v[204:207], v[0:3]
	v_mfma_f32_16x16x32_bf16 v[8:11], v[156:159], v[204:207], v[8:11]
	ds_read_b128 v[204:207], v246 offset:18432
	v_mfma_f32_16x16x32_bf16 v[68:71], v[144:147], v[242:245], v[68:71]
	v_mfma_f32_16x16x32_bf16 v[76:79], v[148:151], v[242:245], v[76:79]
	v_mfma_f32_16x16x32_bf16 v[4:7], v[152:155], v[242:245], v[4:7]
	v_mfma_f32_16x16x32_bf16 v[12:15], v[156:159], v[242:245], v[12:15]
	ds_read_b128 v[242:245], v246 offset:19456
	global_load_dwordx4 v[144:147], v[248:249], off
	global_load_dwordx4 v[148:151], v[248:249], off offset:256
	global_load_dwordx4 v[152:155], v[250:251], off
	global_load_dwordx4 v[156:159], v[250:251], off offset:256
	s_add_i32 s9, s3, 5
	s_min_u32 s10, s9, 31
	s_lshl_b32 s96, s10, 13
	v_lshl_add_u64 v[166:167], v[188:189], 0, s[96:97]
	global_load_dwordx4 v[160:163], v[166:167], off offset:-2048
	global_load_dwordx4 v[164:167], v[166:167], off offset:2048
	s_add_i32 s9, s3, 4
	s_min_u32 s10, s9, 31
	s_lshl_b32 s96, s10, 11
	v_lshl_add_u64 v[248:249], v[184:185], 0, s[96:97]
	v_lshl_add_u64 v[250:251], v[186:187], 0, s[96:97]
	s_waitcnt vmcnt(8) lgkmcnt(3)
	v_mfma_f32_16x16x32_bf16 v[112:115], v[128:131], v[196:199], v[112:115]
	v_mfma_f32_16x16x32_bf16 v[120:123], v[132:135], v[196:199], v[120:123]
	v_mfma_f32_16x16x32_bf16 v[48:51], v[136:139], v[196:199], v[48:51]
	v_mfma_f32_16x16x32_bf16 v[56:59], v[140:143], v[196:199], v[56:59]
	ds_read_b128 v[196:199], v246 offset:20480
	s_waitcnt lgkmcnt(3)
	v_mfma_f32_16x16x32_bf16 v[116:119], v[128:131], v[200:203], v[116:119]
	v_mfma_f32_16x16x32_bf16 v[124:127], v[132:135], v[200:203], v[124:127]
	v_mfma_f32_16x16x32_bf16 v[52:55], v[136:139], v[200:203], v[52:55]
	v_mfma_f32_16x16x32_bf16 v[60:63], v[140:143], v[200:203], v[60:63]
	ds_read_b128 v[200:203], v246 offset:21504
	s_waitcnt lgkmcnt(3)
	v_mfma_f32_16x16x32_bf16 v[96:99], v[128:131], v[204:207], v[96:99]
	v_mfma_f32_16x16x32_bf16 v[104:107], v[132:135], v[204:207], v[104:107]
	v_mfma_f32_16x16x32_bf16 v[32:35], v[136:139], v[204:207], v[32:35]
	v_mfma_f32_16x16x32_bf16 v[40:43], v[140:143], v[204:207], v[40:43]
	ds_read_b128 v[204:207], v246 offset:22528
	s_waitcnt lgkmcnt(3)
	v_mfma_f32_16x16x32_bf16 v[100:103], v[128:131], v[242:245], v[100:103]
	v_mfma_f32_16x16x32_bf16 v[108:111], v[132:135], v[242:245], v[108:111]
	v_mfma_f32_16x16x32_bf16 v[36:39], v[136:139], v[242:245], v[36:39]
	v_mfma_f32_16x16x32_bf16 v[44:47], v[140:143], v[242:245], v[44:47]
	ds_read_b128 v[242:245], v246 offset:23552
	s_waitcnt vmcnt(6)
	ds_write_b128 v241, v[168:171] offset:8192
	ds_write_b128 v241, v[172:175] offset:12288
	s_waitcnt lgkmcnt(5)
	v_mfma_f32_16x16x32_bf16 v[80:83], v[128:131], v[196:199], v[80:83]
	v_mfma_f32_16x16x32_bf16 v[88:91], v[132:135], v[196:199], v[88:91]
	v_mfma_f32_16x16x32_bf16 v[16:19], v[136:139], v[196:199], v[16:19]
	v_mfma_f32_16x16x32_bf16 v[24:27], v[140:143], v[196:199], v[24:27]
	ds_read_b128 v[196:199], v246 offset:0
	s_waitcnt lgkmcnt(5)
	v_mfma_f32_16x16x32_bf16 v[84:87], v[128:131], v[200:203], v[84:87]
	v_mfma_f32_16x16x32_bf16 v[92:95], v[132:135], v[200:203], v[92:95]
	v_mfma_f32_16x16x32_bf16 v[20:23], v[136:139], v[200:203], v[20:23]
	v_mfma_f32_16x16x32_bf16 v[28:31], v[140:143], v[200:203], v[28:31]
	ds_read_b128 v[200:203], v246 offset:1024
	s_waitcnt lgkmcnt(2)
	s_barrier
	v_mfma_f32_16x16x32_bf16 v[64:67], v[128:131], v[204:207], v[64:67]
	v_mfma_f32_16x16x32_bf16 v[72:75], v[132:135], v[204:207], v[72:75]
	v_mfma_f32_16x16x32_bf16 v[0:3], v[136:139], v[204:207], v[0:3]
	v_mfma_f32_16x16x32_bf16 v[8:11], v[140:143], v[204:207], v[8:11]
	ds_read_b128 v[204:207], v246 offset:2048
	v_mfma_f32_16x16x32_bf16 v[68:71], v[128:131], v[242:245], v[68:71]
	v_mfma_f32_16x16x32_bf16 v[76:79], v[132:135], v[242:245], v[76:79]
	v_mfma_f32_16x16x32_bf16 v[4:7], v[136:139], v[242:245], v[4:7]
	v_mfma_f32_16x16x32_bf16 v[12:15], v[140:143], v[242:245], v[12:15]
	ds_read_b128 v[242:245], v246 offset:3072
	global_load_dwordx4 v[128:131], v[248:249], off
	global_load_dwordx4 v[132:135], v[248:249], off offset:256
	global_load_dwordx4 v[136:139], v[250:251], off
	global_load_dwordx4 v[140:143], v[250:251], off offset:256
	s_add_i32 s9, s3, 6
	s_min_u32 s10, s9, 31
	s_lshl_b32 s96, s10, 13
	v_lshl_add_u64 v[174:175], v[188:189], 0, s[96:97]
	global_load_dwordx4 v[168:171], v[174:175], off offset:-2048
	global_load_dwordx4 v[172:175], v[174:175], off offset:2048
	s_add_i32 s9, s3, 5
	s_min_u32 s10, s9, 31
	s_lshl_b32 s96, s10, 11
	v_lshl_add_u64 v[248:249], v[184:185], 0, s[96:97]
	v_lshl_add_u64 v[250:251], v[186:187], 0, s[96:97]
	s_waitcnt vmcnt(8) lgkmcnt(3)
	v_mfma_f32_16x16x32_bf16 v[112:115], v[144:147], v[196:199], v[112:115]
	v_mfma_f32_16x16x32_bf16 v[120:123], v[148:151], v[196:199], v[120:123]
	v_mfma_f32_16x16x32_bf16 v[48:51], v[152:155], v[196:199], v[48:51]
	v_mfma_f32_16x16x32_bf16 v[56:59], v[156:159], v[196:199], v[56:59]
	ds_read_b128 v[196:199], v246 offset:4096
	s_waitcnt lgkmcnt(3)
	v_mfma_f32_16x16x32_bf16 v[116:119], v[144:147], v[200:203], v[116:119]
	v_mfma_f32_16x16x32_bf16 v[124:127], v[148:151], v[200:203], v[124:127]
	v_mfma_f32_16x16x32_bf16 v[52:55], v[152:155], v[200:203], v[52:55]
	v_mfma_f32_16x16x32_bf16 v[60:63], v[156:159], v[200:203], v[60:63]
	ds_read_b128 v[200:203], v246 offset:5120
	s_waitcnt lgkmcnt(3)
	v_mfma_f32_16x16x32_bf16 v[96:99], v[144:147], v[204:207], v[96:99]
	v_mfma_f32_16x16x32_bf16 v[104:107], v[148:151], v[204:207], v[104:107]
	v_mfma_f32_16x16x32_bf16 v[32:35], v[152:155], v[204:207], v[32:35]
	v_mfma_f32_16x16x32_bf16 v[40:43], v[156:159], v[204:207], v[40:43]
	ds_read_b128 v[204:207], v246 offset:6144
	s_waitcnt lgkmcnt(3)
	v_mfma_f32_16x16x32_bf16 v[100:103], v[144:147], v[242:245], v[100:103]
	v_mfma_f32_16x16x32_bf16 v[108:111], v[148:151], v[242:245], v[108:111]
	v_mfma_f32_16x16x32_bf16 v[36:39], v[152:155], v[242:245], v[36:39]
	v_mfma_f32_16x16x32_bf16 v[44:47], v[156:159], v[242:245], v[44:47]
	ds_read_b128 v[242:245], v246 offset:7168
	s_waitcnt vmcnt(6)
	ds_write_b128 v241, v[160:163] offset:16384
	ds_write_b128 v241, v[164:167] offset:20480
	s_waitcnt lgkmcnt(5)
	v_mfma_f32_16x16x32_bf16 v[80:83], v[144:147], v[196:199], v[80:83]
	v_mfma_f32_16x16x32_bf16 v[88:91], v[148:151], v[196:199], v[88:91]
	v_mfma_f32_16x16x32_bf16 v[16:19], v[152:155], v[196:199], v[16:19]
	v_mfma_f32_16x16x32_bf16 v[24:27], v[156:159], v[196:199], v[24:27]
	ds_read_b128 v[196:199], v246 offset:8192
	s_waitcnt lgkmcnt(5)
	v_mfma_f32_16x16x32_bf16 v[84:87], v[144:147], v[200:203], v[84:87]
	v_mfma_f32_16x16x32_bf16 v[92:95], v[148:151], v[200:203], v[92:95]
	v_mfma_f32_16x16x32_bf16 v[20:23], v[152:155], v[200:203], v[20:23]
	v_mfma_f32_16x16x32_bf16 v[28:31], v[156:159], v[200:203], v[28:31]
	ds_read_b128 v[200:203], v246 offset:9216
	s_waitcnt lgkmcnt(2)
	s_barrier
	v_mfma_f32_16x16x32_bf16 v[64:67], v[144:147], v[204:207], v[64:67]
	v_mfma_f32_16x16x32_bf16 v[72:75], v[148:151], v[204:207], v[72:75]
	v_mfma_f32_16x16x32_bf16 v[0:3], v[152:155], v[204:207], v[0:3]
	v_mfma_f32_16x16x32_bf16 v[8:11], v[156:159], v[204:207], v[8:11]
	ds_read_b128 v[204:207], v246 offset:10240
	v_mfma_f32_16x16x32_bf16 v[68:71], v[144:147], v[242:245], v[68:71]
	v_mfma_f32_16x16x32_bf16 v[76:79], v[148:151], v[242:245], v[76:79]
	v_mfma_f32_16x16x32_bf16 v[4:7], v[152:155], v[242:245], v[4:7]
	v_mfma_f32_16x16x32_bf16 v[12:15], v[156:159], v[242:245], v[12:15]
	ds_read_b128 v[242:245], v246 offset:11264
	global_load_dwordx4 v[144:147], v[248:249], off
	global_load_dwordx4 v[148:151], v[248:249], off offset:256
	global_load_dwordx4 v[152:155], v[250:251], off
	global_load_dwordx4 v[156:159], v[250:251], off offset:256
	s_add_i32 s9, s3, 7
	s_min_u32 s10, s9, 31
	s_lshl_b32 s96, s10, 13
	v_lshl_add_u64 v[166:167], v[188:189], 0, s[96:97]
	global_load_dwordx4 v[160:163], v[166:167], off offset:-2048
	global_load_dwordx4 v[164:167], v[166:167], off offset:2048
	s_add_i32 s9, s3, 6
	s_min_u32 s10, s9, 31
	s_lshl_b32 s96, s10, 11
	v_lshl_add_u64 v[248:249], v[184:185], 0, s[96:97]
	v_lshl_add_u64 v[250:251], v[186:187], 0, s[96:97]
	s_waitcnt vmcnt(8) lgkmcnt(3)
	v_mfma_f32_16x16x32_bf16 v[112:115], v[128:131], v[196:199], v[112:115]
	v_mfma_f32_16x16x32_bf16 v[120:123], v[132:135], v[196:199], v[120:123]
	v_mfma_f32_16x16x32_bf16 v[48:51], v[136:139], v[196:199], v[48:51]
	v_mfma_f32_16x16x32_bf16 v[56:59], v[140:143], v[196:199], v[56:59]
	ds_read_b128 v[196:199], v246 offset:12288
	s_waitcnt lgkmcnt(3)
	v_mfma_f32_16x16x32_bf16 v[116:119], v[128:131], v[200:203], v[116:119]
	v_mfma_f32_16x16x32_bf16 v[124:127], v[132:135], v[200:203], v[124:127]
	v_mfma_f32_16x16x32_bf16 v[52:55], v[136:139], v[200:203], v[52:55]
	v_mfma_f32_16x16x32_bf16 v[60:63], v[140:143], v[200:203], v[60:63]
	ds_read_b128 v[200:203], v246 offset:13312
	s_waitcnt lgkmcnt(3)
	v_mfma_f32_16x16x32_bf16 v[96:99], v[128:131], v[204:207], v[96:99]
	v_mfma_f32_16x16x32_bf16 v[104:107], v[132:135], v[204:207], v[104:107]
	v_mfma_f32_16x16x32_bf16 v[32:35], v[136:139], v[204:207], v[32:35]
	v_mfma_f32_16x16x32_bf16 v[40:43], v[140:143], v[204:207], v[40:43]
	ds_read_b128 v[204:207], v246 offset:14336
	s_waitcnt lgkmcnt(3)
	v_mfma_f32_16x16x32_bf16 v[100:103], v[128:131], v[242:245], v[100:103]
	v_mfma_f32_16x16x32_bf16 v[108:111], v[132:135], v[242:245], v[108:111]
	v_mfma_f32_16x16x32_bf16 v[36:39], v[136:139], v[242:245], v[36:39]
	v_mfma_f32_16x16x32_bf16 v[44:47], v[140:143], v[242:245], v[44:47]
	ds_read_b128 v[242:245], v246 offset:15360
	s_waitcnt vmcnt(6)
	ds_write_b128 v241, v[168:171] offset:0
	ds_write_b128 v241, v[172:175] offset:4096
	s_waitcnt lgkmcnt(5)
	v_mfma_f32_16x16x32_bf16 v[80:83], v[128:131], v[196:199], v[80:83]
	v_mfma_f32_16x16x32_bf16 v[88:91], v[132:135], v[196:199], v[88:91]
	v_mfma_f32_16x16x32_bf16 v[16:19], v[136:139], v[196:199], v[16:19]
	v_mfma_f32_16x16x32_bf16 v[24:27], v[140:143], v[196:199], v[24:27]
	ds_read_b128 v[196:199], v246 offset:16384
	s_waitcnt lgkmcnt(5)
	v_mfma_f32_16x16x32_bf16 v[84:87], v[128:131], v[200:203], v[84:87]
	v_mfma_f32_16x16x32_bf16 v[92:95], v[132:135], v[200:203], v[92:95]
	v_mfma_f32_16x16x32_bf16 v[20:23], v[136:139], v[200:203], v[20:23]
	v_mfma_f32_16x16x32_bf16 v[28:31], v[140:143], v[200:203], v[28:31]
	ds_read_b128 v[200:203], v246 offset:17408
	s_waitcnt lgkmcnt(2)
	s_barrier
	v_mfma_f32_16x16x32_bf16 v[64:67], v[128:131], v[204:207], v[64:67]
	v_mfma_f32_16x16x32_bf16 v[72:75], v[132:135], v[204:207], v[72:75]
	v_mfma_f32_16x16x32_bf16 v[0:3], v[136:139], v[204:207], v[0:3]
	v_mfma_f32_16x16x32_bf16 v[8:11], v[140:143], v[204:207], v[8:11]
	ds_read_b128 v[204:207], v246 offset:18432
	v_mfma_f32_16x16x32_bf16 v[68:71], v[128:131], v[242:245], v[68:71]
	v_mfma_f32_16x16x32_bf16 v[76:79], v[132:135], v[242:245], v[76:79]
	v_mfma_f32_16x16x32_bf16 v[4:7], v[136:139], v[242:245], v[4:7]
	v_mfma_f32_16x16x32_bf16 v[12:15], v[140:143], v[242:245], v[12:15]
	ds_read_b128 v[242:245], v246 offset:19456
	global_load_dwordx4 v[128:131], v[248:249], off
	global_load_dwordx4 v[132:135], v[248:249], off offset:256
	global_load_dwordx4 v[136:139], v[250:251], off
	global_load_dwordx4 v[140:143], v[250:251], off offset:256
	s_add_i32 s9, s3, 8
	s_min_u32 s10, s9, 31
	s_lshl_b32 s96, s10, 13
	v_lshl_add_u64 v[174:175], v[188:189], 0, s[96:97]
	global_load_dwordx4 v[168:171], v[174:175], off offset:-2048
	global_load_dwordx4 v[172:175], v[174:175], off offset:2048
	s_add_i32 s9, s3, 7
	s_min_u32 s10, s9, 31
	s_lshl_b32 s96, s10, 11
	v_lshl_add_u64 v[248:249], v[184:185], 0, s[96:97]
	v_lshl_add_u64 v[250:251], v[186:187], 0, s[96:97]
	s_waitcnt vmcnt(8) lgkmcnt(3)
	v_mfma_f32_16x16x32_bf16 v[112:115], v[144:147], v[196:199], v[112:115]
	v_mfma_f32_16x16x32_bf16 v[120:123], v[148:151], v[196:199], v[120:123]
	v_mfma_f32_16x16x32_bf16 v[48:51], v[152:155], v[196:199], v[48:51]
	v_mfma_f32_16x16x32_bf16 v[56:59], v[156:159], v[196:199], v[56:59]
	ds_read_b128 v[196:199], v246 offset:20480
	s_waitcnt lgkmcnt(3)
	v_mfma_f32_16x16x32_bf16 v[116:119], v[144:147], v[200:203], v[116:119]
	v_mfma_f32_16x16x32_bf16 v[124:127], v[148:151], v[200:203], v[124:127]
	v_mfma_f32_16x16x32_bf16 v[52:55], v[152:155], v[200:203], v[52:55]
	v_mfma_f32_16x16x32_bf16 v[60:63], v[156:159], v[200:203], v[60:63]
	ds_read_b128 v[200:203], v246 offset:21504
	s_waitcnt lgkmcnt(3)
	v_mfma_f32_16x16x32_bf16 v[96:99], v[144:147], v[204:207], v[96:99]
	v_mfma_f32_16x16x32_bf16 v[104:107], v[148:151], v[204:207], v[104:107]
	v_mfma_f32_16x16x32_bf16 v[32:35], v[152:155], v[204:207], v[32:35]
	v_mfma_f32_16x16x32_bf16 v[40:43], v[156:159], v[204:207], v[40:43]
	ds_read_b128 v[204:207], v246 offset:22528
	s_waitcnt lgkmcnt(3)
	v_mfma_f32_16x16x32_bf16 v[100:103], v[144:147], v[242:245], v[100:103]
	v_mfma_f32_16x16x32_bf16 v[108:111], v[148:151], v[242:245], v[108:111]
	v_mfma_f32_16x16x32_bf16 v[36:39], v[152:155], v[242:245], v[36:39]
	v_mfma_f32_16x16x32_bf16 v[44:47], v[156:159], v[242:245], v[44:47]
	ds_read_b128 v[242:245], v246 offset:23552
	s_waitcnt vmcnt(6)
	ds_write_b128 v241, v[160:163] offset:8192
	ds_write_b128 v241, v[164:167] offset:12288
	s_waitcnt lgkmcnt(5)
	v_mfma_f32_16x16x32_bf16 v[80:83], v[144:147], v[196:199], v[80:83]
	v_mfma_f32_16x16x32_bf16 v[88:91], v[148:151], v[196:199], v[88:91]
	v_mfma_f32_16x16x32_bf16 v[16:19], v[152:155], v[196:199], v[16:19]
	v_mfma_f32_16x16x32_bf16 v[24:27], v[156:159], v[196:199], v[24:27]
	ds_read_b128 v[196:199], v246 offset:0
	s_waitcnt lgkmcnt(5)
	v_mfma_f32_16x16x32_bf16 v[84:87], v[144:147], v[200:203], v[84:87]
	v_mfma_f32_16x16x32_bf16 v[92:95], v[148:151], v[200:203], v[92:95]
	v_mfma_f32_16x16x32_bf16 v[20:23], v[152:155], v[200:203], v[20:23]
	v_mfma_f32_16x16x32_bf16 v[28:31], v[156:159], v[200:203], v[28:31]
	ds_read_b128 v[200:203], v246 offset:1024
	s_waitcnt lgkmcnt(2)
	s_barrier
	v_mfma_f32_16x16x32_bf16 v[64:67], v[144:147], v[204:207], v[64:67]
	v_mfma_f32_16x16x32_bf16 v[72:75], v[148:151], v[204:207], v[72:75]
	v_mfma_f32_16x16x32_bf16 v[0:3], v[152:155], v[204:207], v[0:3]
	v_mfma_f32_16x16x32_bf16 v[8:11], v[156:159], v[204:207], v[8:11]
	ds_read_b128 v[204:207], v246 offset:2048
	v_mfma_f32_16x16x32_bf16 v[68:71], v[144:147], v[242:245], v[68:71]
	v_mfma_f32_16x16x32_bf16 v[76:79], v[148:151], v[242:245], v[76:79]
	v_mfma_f32_16x16x32_bf16 v[4:7], v[152:155], v[242:245], v[4:7]
	v_mfma_f32_16x16x32_bf16 v[12:15], v[156:159], v[242:245], v[12:15]
	ds_read_b128 v[242:245], v246 offset:3072
	global_load_dwordx4 v[144:147], v[248:249], off
	global_load_dwordx4 v[148:151], v[248:249], off offset:256
	global_load_dwordx4 v[152:155], v[250:251], off
	global_load_dwordx4 v[156:159], v[250:251], off offset:256
	s_add_i32 s3, s3, 6
	s_cmp_lt_u32 s3, 30
	s_cbranch_scc1 .Lg16_out_k
	s_add_i32 s9, s3, 3
	s_min_u32 s10, s9, 31
	s_lshl_b32 s96, s10, 13
	v_lshl_add_u64 v[166:167], v[188:189], 0, s[96:97]
	global_load_dwordx4 v[160:163], v[166:167], off offset:-2048
	global_load_dwordx4 v[164:167], v[166:167], off offset:2048
	s_add_i32 s9, s3, 2
	s_min_u32 s10, s9, 31
	s_lshl_b32 s96, s10, 11
	v_lshl_add_u64 v[248:249], v[184:185], 0, s[96:97]
	v_lshl_add_u64 v[250:251], v[186:187], 0, s[96:97]
	s_waitcnt vmcnt(8) lgkmcnt(3)
	v_mfma_f32_16x16x32_bf16 v[112:115], v[128:131], v[196:199], v[112:115]
	v_mfma_f32_16x16x32_bf16 v[120:123], v[132:135], v[196:199], v[120:123]
	v_mfma_f32_16x16x32_bf16 v[48:51], v[136:139], v[196:199], v[48:51]
	v_mfma_f32_16x16x32_bf16 v[56:59], v[140:143], v[196:199], v[56:59]
	ds_read_b128 v[196:199], v246 offset:4096
	s_waitcnt lgkmcnt(3)
	v_mfma_f32_16x16x32_bf16 v[116:119], v[128:131], v[200:203], v[116:119]
	v_mfma_f32_16x16x32_bf16 v[124:127], v[132:135], v[200:203], v[124:127]
	v_mfma_f32_16x16x32_bf16 v[52:55], v[136:139], v[200:203], v[52:55]
	v_mfma_f32_16x16x32_bf16 v[60:63], v[140:143], v[200:203], v[60:63]
	ds_read_b128 v[200:203], v246 offset:5120
	s_waitcnt lgkmcnt(3)
	v_mfma_f32_16x16x32_bf16 v[96:99], v[128:131], v[204:207], v[96:99]
	v_mfma_f32_16x16x32_bf16 v[104:107], v[132:135], v[204:207], v[104:107]
	v_mfma_f32_16x16x32_bf16 v[32:35], v[136:139], v[204:207], v[32:35]
	v_mfma_f32_16x16x32_bf16 v[40:43], v[140:143], v[204:207], v[40:43]
	ds_read_b128 v[204:207], v246 offset:6144
	s_waitcnt lgkmcnt(3)
	v_mfma_f32_16x16x32_bf16 v[100:103], v[128:131], v[242:245], v[100:103]
	v_mfma_f32_16x16x32_bf16 v[108:111], v[132:135], v[242:245], v[108:111]
	v_mfma_f32_16x16x32_bf16 v[36:39], v[136:139], v[242:245], v[36:39]
	v_mfma_f32_16x16x32_bf16 v[44:47], v[140:143], v[242:245], v[44:47]
	ds_read_b128 v[242:245], v246 offset:7168
	s_waitcnt vmcnt(6)
	ds_write_b128 v241, v[168:171] offset:16384
	ds_write_b128 v241, v[172:175] offset:20480
	s_waitcnt lgkmcnt(5)
	v_mfma_f32_16x16x32_bf16 v[80:83], v[128:131], v[196:199], v[80:83]
	v_mfma_f32_16x16x32_bf16 v[88:91], v[132:135], v[196:199], v[88:91]
	v_mfma_f32_16x16x32_bf16 v[16:19], v[136:139], v[196:199], v[16:19]
	v_mfma_f32_16x16x32_bf16 v[24:27], v[140:143], v[196:199], v[24:27]
	ds_read_b128 v[196:199], v246 offset:8192
	s_waitcnt lgkmcnt(5)
	v_mfma_f32_16x16x32_bf16 v[84:87], v[128:131], v[200:203], v[84:87]
	v_mfma_f32_16x16x32_bf16 v[92:95], v[132:135], v[200:203], v[92:95]
	v_mfma_f32_16x16x32_bf16 v[20:23], v[136:139], v[200:203], v[20:23]
	v_mfma_f32_16x16x32_bf16 v[28:31], v[140:143], v[200:203], v[28:31]
	ds_read_b128 v[200:203], v246 offset:9216
	s_waitcnt lgkmcnt(2)
	s_barrier
	v_mfma_f32_16x16x32_bf16 v[64:67], v[128:131], v[204:207], v[64:67]
	v_mfma_f32_16x16x32_bf16 v[72:75], v[132:135], v[204:207], v[72:75]
	v_mfma_f32_16x16x32_bf16 v[0:3], v[136:139], v[204:207], v[0:3]
	v_mfma_f32_16x16x32_bf16 v[8:11], v[140:143], v[204:207], v[8:11]
	ds_read_b128 v[204:207], v246 offset:10240
	v_mfma_f32_16x16x32_bf16 v[68:71], v[128:131], v[242:245], v[68:71]
	v_mfma_f32_16x16x32_bf16 v[76:79], v[132:135], v[242:245], v[76:79]
	v_mfma_f32_16x16x32_bf16 v[4:7], v[136:139], v[242:245], v[4:7]
	v_mfma_f32_16x16x32_bf16 v[12:15], v[140:143], v[242:245], v[12:15]
	ds_read_b128 v[242:245], v246 offset:11264
	global_load_dwordx4 v[128:131], v[248:249], off
	global_load_dwordx4 v[132:135], v[248:249], off offset:256
	global_load_dwordx4 v[136:139], v[250:251], off
	global_load_dwordx4 v[140:143], v[250:251], off offset:256
	s_add_i32 s9, s3, 4
	s_min_u32 s10, s9, 31
	s_lshl_b32 s96, s10, 13
	v_lshl_add_u64 v[174:175], v[188:189], 0, s[96:97]
	global_load_dwordx4 v[168:171], v[174:175], off offset:-2048
	global_load_dwordx4 v[172:175], v[174:175], off offset:2048
	s_add_i32 s9, s3, 3
	s_min_u32 s10, s9, 31
	s_lshl_b32 s96, s10, 11
	v_lshl_add_u64 v[248:249], v[184:185], 0, s[96:97]
	v_lshl_add_u64 v[250:251], v[186:187], 0, s[96:97]
	s_waitcnt vmcnt(8) lgkmcnt(3)
	v_mfma_f32_16x16x32_bf16 v[112:115], v[144:147], v[196:199], v[112:115]
	v_mfma_f32_16x16x32_bf16 v[120:123], v[148:151], v[196:199], v[120:123]
	v_mfma_f32_16x16x32_bf16 v[48:51], v[152:155], v[196:199], v[48:51]
	v_mfma_f32_16x16x32_bf16 v[56:59], v[156:159], v[196:199], v[56:59]
	ds_read_b128 v[196:199], v246 offset:12288
	s_waitcnt lgkmcnt(3)
	v_mfma_f32_16x16x32_bf16 v[116:119], v[144:147], v[200:203], v[116:119]
	v_mfma_f32_16x16x32_bf16 v[124:127], v[148:151], v[200:203], v[124:127]
	v_mfma_f32_16x16x32_bf16 v[52:55], v[152:155], v[200:203], v[52:55]
	v_mfma_f32_16x16x32_bf16 v[60:63], v[156:159], v[200:203], v[60:63]
	ds_read_b128 v[200:203], v246 offset:13312
	s_waitcnt lgkmcnt(3)
	v_mfma_f32_16x16x32_bf16 v[96:99], v[144:147], v[204:207], v[96:99]
	v_mfma_f32_16x16x32_bf16 v[104:107], v[148:151], v[204:207], v[104:107]
	v_mfma_f32_16x16x32_bf16 v[32:35], v[152:155], v[204:207], v[32:35]
	v_mfma_f32_16x16x32_bf16 v[40:43], v[156:159], v[204:207], v[40:43]
	ds_read_b128 v[204:207], v246 offset:14336
	s_waitcnt lgkmcnt(3)
	v_mfma_f32_16x16x32_bf16 v[100:103], v[144:147], v[242:245], v[100:103]
	v_mfma_f32_16x16x32_bf16 v[108:111], v[148:151], v[242:245], v[108:111]
	v_mfma_f32_16x16x32_bf16 v[36:39], v[152:155], v[242:245], v[36:39]
	v_mfma_f32_16x16x32_bf16 v[44:47], v[156:159], v[242:245], v[44:47]
	ds_read_b128 v[242:245], v246 offset:15360
	s_waitcnt vmcnt(6)
	ds_write_b128 v241, v[160:163] offset:0
	ds_write_b128 v241, v[164:167] offset:4096
	s_waitcnt lgkmcnt(5)
	v_mfma_f32_16x16x32_bf16 v[80:83], v[144:147], v[196:199], v[80:83]
	v_mfma_f32_16x16x32_bf16 v[88:91], v[148:151], v[196:199], v[88:91]
	v_mfma_f32_16x16x32_bf16 v[16:19], v[152:155], v[196:199], v[16:19]
	v_mfma_f32_16x16x32_bf16 v[24:27], v[156:159], v[196:199], v[24:27]
	ds_read_b128 v[196:199], v246 offset:16384
	s_waitcnt lgkmcnt(5)
	v_mfma_f32_16x16x32_bf16 v[84:87], v[144:147], v[200:203], v[84:87]
	v_mfma_f32_16x16x32_bf16 v[92:95], v[148:151], v[200:203], v[92:95]
	v_mfma_f32_16x16x32_bf16 v[20:23], v[152:155], v[200:203], v[20:23]
	v_mfma_f32_16x16x32_bf16 v[28:31], v[156:159], v[200:203], v[28:31]
	ds_read_b128 v[200:203], v246 offset:17408
	s_waitcnt lgkmcnt(2)
	s_barrier
	v_mfma_f32_16x16x32_bf16 v[64:67], v[144:147], v[204:207], v[64:67]
	v_mfma_f32_16x16x32_bf16 v[72:75], v[148:151], v[204:207], v[72:75]
	v_mfma_f32_16x16x32_bf16 v[0:3], v[152:155], v[204:207], v[0:3]
	v_mfma_f32_16x16x32_bf16 v[8:11], v[156:159], v[204:207], v[8:11]
	ds_read_b128 v[204:207], v246 offset:18432
	v_mfma_f32_16x16x32_bf16 v[68:71], v[144:147], v[242:245], v[68:71]
	v_mfma_f32_16x16x32_bf16 v[76:79], v[148:151], v[242:245], v[76:79]
	v_mfma_f32_16x16x32_bf16 v[4:7], v[152:155], v[242:245], v[4:7]
	v_mfma_f32_16x16x32_bf16 v[12:15], v[156:159], v[242:245], v[12:15]
	ds_read_b128 v[242:245], v246 offset:19456
	global_load_dwordx4 v[144:147], v[248:249], off
	global_load_dwordx4 v[148:151], v[248:249], off offset:256
	global_load_dwordx4 v[152:155], v[250:251], off
	global_load_dwordx4 v[156:159], v[250:251], off offset:256
	s_waitcnt lgkmcnt(0)
	s_nop 7
	v_permlane16_swap_b32_e32 v112, v116
	v_permlane16_swap_b32_e32 v113, v117
	v_permlane16_swap_b32_e32 v114, v118
	v_permlane16_swap_b32_e32 v115, v119
	v_permlane16_swap_b32_e32 v120, v124
	v_permlane16_swap_b32_e32 v121, v125
	v_permlane16_swap_b32_e32 v122, v126
	v_permlane16_swap_b32_e32 v123, v127
	v_permlane16_swap_b32_e32 v96, v100
	v_permlane16_swap_b32_e32 v97, v101
	v_permlane16_swap_b32_e32 v98, v102
	v_permlane16_swap_b32_e32 v99, v103
	v_permlane16_swap_b32_e32 v104, v108
	v_permlane16_swap_b32_e32 v105, v109
	v_permlane16_swap_b32_e32 v106, v110
	v_permlane16_swap_b32_e32 v107, v111
	v_permlane16_swap_b32_e32 v80, v84
	v_permlane16_swap_b32_e32 v81, v85
	v_permlane16_swap_b32_e32 v82, v86
	v_permlane16_swap_b32_e32 v83, v87
	v_permlane16_swap_b32_e32 v88, v92
	v_permlane16_swap_b32_e32 v89, v93
	v_permlane16_swap_b32_e32 v90, v94
	v_permlane16_swap_b32_e32 v91, v95
	v_permlane16_swap_b32_e32 v64, v68
	v_permlane16_swap_b32_e32 v65, v69
	v_permlane16_swap_b32_e32 v66, v70
	v_permlane16_swap_b32_e32 v67, v71
	v_permlane16_swap_b32_e32 v72, v76
	v_permlane16_swap_b32_e32 v73, v77
	v_permlane16_swap_b32_e32 v74, v78
	v_permlane16_swap_b32_e32 v75, v79
	v_permlane16_swap_b32_e32 v48, v52
	v_permlane16_swap_b32_e32 v49, v53
	v_permlane16_swap_b32_e32 v50, v54
	v_permlane16_swap_b32_e32 v51, v55
	v_permlane16_swap_b32_e32 v56, v60
	v_permlane16_swap_b32_e32 v57, v61
	v_permlane16_swap_b32_e32 v58, v62
	v_permlane16_swap_b32_e32 v59, v63
	v_permlane16_swap_b32_e32 v32, v36
	v_permlane16_swap_b32_e32 v33, v37
	v_permlane16_swap_b32_e32 v34, v38
	v_permlane16_swap_b32_e32 v35, v39
	v_permlane16_swap_b32_e32 v40, v44
	v_permlane16_swap_b32_e32 v41, v45
	v_permlane16_swap_b32_e32 v42, v46
	v_permlane16_swap_b32_e32 v43, v47
	v_permlane16_swap_b32_e32 v16, v20
	v_permlane16_swap_b32_e32 v17, v21
	v_permlane16_swap_b32_e32 v18, v22
	v_permlane16_swap_b32_e32 v19, v23
	v_permlane16_swap_b32_e32 v24, v28
	v_permlane16_swap_b32_e32 v25, v29
	v_permlane16_swap_b32_e32 v26, v30
	v_permlane16_swap_b32_e32 v27, v31
	v_permlane16_swap_b32_e32 v0, v4
	v_permlane16_swap_b32_e32 v1, v5
	v_permlane16_swap_b32_e32 v2, v6
	v_permlane16_swap_b32_e32 v3, v7
	v_permlane16_swap_b32_e32 v8, v12
	v_permlane16_swap_b32_e32 v9, v13
	v_permlane16_swap_b32_e32 v10, v14
	v_permlane16_swap_b32_e32 v11, v15
	v_permlane32_swap_b32_e32 v112, v116
	v_permlane32_swap_b32_e32 v113, v117
	v_permlane32_swap_b32_e32 v114, v118
	v_permlane32_swap_b32_e32 v115, v119
	v_permlane32_swap_b32_e32 v120, v124
	v_permlane32_swap_b32_e32 v121, v125
	v_permlane32_swap_b32_e32 v122, v126
	v_permlane32_swap_b32_e32 v123, v127
	v_permlane32_swap_b32_e32 v96, v100
	v_permlane32_swap_b32_e32 v97, v101
	v_permlane32_swap_b32_e32 v98, v102
	v_permlane32_swap_b32_e32 v99, v103
	v_permlane32_swap_b32_e32 v104, v108
	v_permlane32_swap_b32_e32 v105, v109
	v_permlane32_swap_b32_e32 v106, v110
	v_permlane32_swap_b32_e32 v107, v111
	v_permlane32_swap_b32_e32 v80, v84
	v_permlane32_swap_b32_e32 v81, v85
	v_permlane32_swap_b32_e32 v82, v86
	v_permlane32_swap_b32_e32 v83, v87
	v_permlane32_swap_b32_e32 v88, v92
	v_permlane32_swap_b32_e32 v89, v93
	v_permlane32_swap_b32_e32 v90, v94
	v_permlane32_swap_b32_e32 v91, v95
	v_permlane32_swap_b32_e32 v64, v68
	v_permlane32_swap_b32_e32 v65, v69
	v_permlane32_swap_b32_e32 v66, v70
	v_permlane32_swap_b32_e32 v67, v71
	v_permlane32_swap_b32_e32 v72, v76
	v_permlane32_swap_b32_e32 v73, v77
	v_permlane32_swap_b32_e32 v74, v78
	v_permlane32_swap_b32_e32 v75, v79
	v_permlane32_swap_b32_e32 v48, v52
	v_permlane32_swap_b32_e32 v49, v53
	v_permlane32_swap_b32_e32 v50, v54
	v_permlane32_swap_b32_e32 v51, v55
	v_permlane32_swap_b32_e32 v56, v60
	v_permlane32_swap_b32_e32 v57, v61
	v_permlane32_swap_b32_e32 v58, v62
	v_permlane32_swap_b32_e32 v59, v63
	v_permlane32_swap_b32_e32 v32, v36
	v_permlane32_swap_b32_e32 v33, v37
	v_permlane32_swap_b32_e32 v34, v38
	v_permlane32_swap_b32_e32 v35, v39
	v_permlane32_swap_b32_e32 v40, v44
	v_permlane32_swap_b32_e32 v41, v45
	v_permlane32_swap_b32_e32 v42, v46
	v_permlane32_swap_b32_e32 v43, v47
	v_permlane32_swap_b32_e32 v16, v20
	v_permlane32_swap_b32_e32 v17, v21
	v_permlane32_swap_b32_e32 v18, v22
	v_permlane32_swap_b32_e32 v19, v23
	v_permlane32_swap_b32_e32 v24, v28
	v_permlane32_swap_b32_e32 v25, v29
	v_permlane32_swap_b32_e32 v26, v30
	v_permlane32_swap_b32_e32 v27, v31
	v_permlane32_swap_b32_e32 v0, v4
	v_permlane32_swap_b32_e32 v1, v5
	v_permlane32_swap_b32_e32 v2, v6
	v_permlane32_swap_b32_e32 v3, v7
	v_permlane32_swap_b32_e32 v8, v12
	v_permlane32_swap_b32_e32 v9, v13
	v_permlane32_swap_b32_e32 v10, v14
	v_permlane32_swap_b32_e32 v11, v15
	s_waitcnt vmcnt(0)
	s_movk_i32 s3, 0x2400
	s_waitcnt vmcnt(6)
	v_lshlrev_b32_e32 v128, 2, v181
	s_waitcnt vmcnt(0)
	v_and_b32_e32 v133, 0xffffffc0, v181
	v_mul_lo_u32 v129, v237, s3
	v_lshlrev_b32_e32 v130, 2, v238
	v_and_b32_e32 v128, 60, v128
	v_lshl_add_u32 v176, s8, 8, v133
	v_mul_u32_u24_e32 v133, 0x110, v183
	v_or_b32_e32 v131, v129, v130
	v_lshl_or_b32 v132, v128, 2, v129
	v_lshl_or_b32 v128, s2, 7, v128
	v_lshlrev_b32_e32 v133, 2, v133
	v_lshrrev_b32_e32 v175, 4, v239
	s_movk_i32 s2, 0x110
	v_add_u32_e32 v147, v131, v133
	v_add3_u32 v148, v129, v133, v130
	v_mad_u32_u24 v146, v175, s2, v132
	v_readlane_b32 s2, v254, 39
	v_readlane_b32 s8, v253, 36
	v_add_u32_e32 v149, 0x800, v147
	v_add_u32_e32 v150, 0x800, v148
	v_add_u32_e32 v151, 0xa00, v148
	v_mov_b32_e32 v160, s2
	v_readlane_b32 s2, v254, 37
	v_readlane_b32 s9, v253, 37
	v_readlane_b32 s10, v253, 38
	v_readlane_b32 s11, v253, 39
	v_readlane_b32 s12, v253, 40
	v_readlane_b32 s13, v253, 41
	v_readlane_b32 s14, v253, 42
	v_readlane_b32 s15, v253, 43
	v_readlane_b32 s16, v253, 44
	v_readlane_b32 s17, v253, 45
	ds_write2_b32 v147, v112, v113 offset1:68
	ds_write2_b32 v148, v96, v97 offset0:32 offset1:100
	ds_write2_b32 v147, v114, v115 offset0:136 offset1:204
	ds_write2_b32 v148, v98, v99 offset0:168 offset1:236
	ds_write2_b32 v149, v116, v117 offset0:32 offset1:100
	ds_write2_b32 v150, v100, v101 offset0:64 offset1:132
	ds_write2_b32 v149, v118, v119 offset0:168 offset1:236
	ds_write2_b32 v151, v102, v103 offset0:72 offset1:140
	v_or_b32_e32 v102, v176, v175
	v_mov_b32_e32 v161, s2
	v_readlane_b32 s2, v254, 40
	v_readlane_b32 s18, v253, 46
	v_readlane_b32 s19, v253, 47
	v_readlane_b32 s20, v253, 48
	v_readlane_b32 s21, v253, 49
	v_readlane_b32 s22, v253, 50
	v_readlane_b32 s23, v253, 51
	s_mov_b64 s[8:9], s[16:17]
	v_cmp_gt_i32_e32 vcc, s39, v102
	v_add_u32_e32 v96, 0xffff8000, v102
	v_ashrrev_i32_e32 v97, 31, v102
	v_mov_b32_e32 v162, s2
	v_readlane_b32 s2, v254, 38
	s_mov_b64 s[10:11], s[18:19]
	v_cndmask_b32_e32 v97, 0, v97, vcc
	v_cndmask_b32_e32 v96, v96, v102, vcc
	v_mov_b32_e32 v163, s2
	v_mov_b32_e32 v164, s63
	v_mov_b32_e32 v165, s11
	v_mov_b32_e32 v166, s62
	v_mov_b32_e32 v167, s10
	v_min_i32_e32 v102, 0x8000, v102
	v_add_u32_e32 v152, 0x1000, v147
	v_add_u32_e32 v153, 0x1000, v148
	v_add_u32_e32 v154, 0x1200, v147
	v_add_u32_e32 v155, 0x1200, v148
	v_add_u32_e32 v156, 0x1800, v147
	v_add_u32_e32 v157, 0x1800, v148
	v_add_u32_e32 v158, 0x1a00, v147
	v_add_u32_e32 v159, 0x1c00, v148
	v_ashrrev_i32_e32 v129, 31, v128
	v_cndmask_b32_e32 v99, v160, v161, vcc
	v_cndmask_b32_e32 v98, v162, v163, vcc
	v_lshlrev_b64 v[96:97], 12, v[96:97]
	v_cndmask_b32_e32 v101, v164, v165, vcc
	v_cndmask_b32_e32 v100, v166, v167, vcc
	v_ashrrev_i32_e32 v102, 12, v102
	ds_write2_b32 v152, v120, v121 offset0:64 offset1:132
	ds_write2_b32 v153, v104, v105 offset0:96 offset1:164
	ds_write2_b32 v154, v122, v123 offset0:72 offset1:140
	ds_write2_b32 v155, v106, v107 offset0:104 offset1:172
	ds_write2_b32 v156, v124, v125 offset0:96 offset1:164
	ds_write2_b32 v157, v108, v109 offset0:128 offset1:196
	ds_write2_b32 v158, v126, v127 offset0:104 offset1:172
	ds_write2_b32 v159, v110, v111 offset0:8 offset1:76
	v_lshl_add_u64 v[98:99], v[98:99], 0, v[96:97]
	v_lshl_add_u64 v[100:101], v[100:101], 0, v[96:97]
	v_lshlrev_b64 v[96:97], 2, v[128:129]
	v_mul_hi_i32_i24_e32 v103, 0x6000, v102
	v_mul_i32_i24_e32 v102, 0x6000, v102
	s_waitcnt lgkmcnt(0)
	v_lshl_add_u64 v[98:99], v[98:99], 0, v[96:97]
	v_lshl_add_u64 v[102:103], s[0:1], 0, v[102:103]
	v_lshl_add_u64 v[102:103], v[102:103], 0, v[96:97]
	ds_read_b128 v[104:107], v146
	global_load_dwordx4 v[108:111], v[98:99], off
	global_load_dwordx4 v[112:115], v[102:103], off
	v_or_b32_e32 v168, 4, v175
	v_lshl_add_u64 v[100:101], v[100:101], 0, v[96:97]
	v_or_b32_e32 v169, 8, v175
	v_or_b32_e32 v170, 12, v175
	v_or_b32_e32 v171, 16, v175
	v_or_b32_e32 v172, 20, v175
	v_or_b32_e32 v173, 24, v175
	v_or_b32_e32 v174, 28, v175
	v_or_b32_e32 v181, v176, v174
	v_readlane_b32 s2, v254, 11
	s_add_i32 s4, s4, s2
	s_cmp_lt_i32 s4, s26
	s_mov_b64 s[12:13], s[20:21]
	s_mov_b64 s[14:15], s[22:23]
	s_waitcnt vmcnt(0) lgkmcnt(0)
	v_pk_fma_f32 v[104:105], v[104:105], v[112:113], v[108:109]
	v_pk_fma_f32 v[106:107], v[106:107], v[114:115], v[110:111]
	v_or_b32_e32 v110, v176, v168
	global_store_dwordx4 v[100:101], v[104:107], off
	v_cmp_gt_i32_e32 vcc, s39, v110
	s_nop 0
	v_ashrrev_i32_e32 v104, 31, v110
	v_add_u32_e32 v106, 0xffff8000, v110
	v_cndmask_b32_e32 v105, 0, v104, vcc
	v_cndmask_b32_e32 v104, v106, v110, vcc
	v_cndmask_b32_e32 v107, v160, v161, vcc
	v_cndmask_b32_e32 v106, v162, v163, vcc
	v_lshlrev_b64 v[104:105], 12, v[104:105]
	v_cndmask_b32_e32 v109, v164, v165, vcc
	v_cndmask_b32_e32 v108, v166, v167, vcc
	v_lshl_add_u64 v[106:107], v[106:107], 0, v[104:105]
	v_lshl_add_u64 v[104:105], v[108:109], 0, v[104:105]
	v_min_i32_e32 v108, 0x8000, v110
	v_ashrrev_i32_e32 v108, 12, v108
	v_mul_hi_i32_i24_e32 v109, 0x6000, v108
	v_mul_i32_i24_e32 v108, 0x6000, v108
	v_lshl_add_u64 v[106:107], v[106:107], 0, v[96:97]
	v_lshl_add_u64 v[108:109], s[0:1], 0, v[108:109]
	v_lshl_add_u64 v[108:109], v[108:109], 0, v[96:97]
	ds_read_b128 v[110:113], v146 offset:1088
	global_load_dwordx4 v[114:117], v[106:107], off
	global_load_dwordx4 v[118:121], v[108:109], off
	v_lshl_add_u64 v[104:105], v[104:105], 0, v[96:97]
	s_waitcnt vmcnt(0) lgkmcnt(0)
	v_pk_fma_f32 v[110:111], v[110:111], v[118:119], v[114:115]
	v_pk_fma_f32 v[112:113], v[112:113], v[120:121], v[116:117]
	v_or_b32_e32 v118, v176, v169
	global_store_dwordx4 v[104:105], v[110:113], off
	v_cmp_gt_i32_e32 vcc, s39, v118
	s_nop 0
	v_ashrrev_i32_e32 v110, 31, v118
	v_add_u32_e32 v112, 0xffff8000, v118
	v_cndmask_b32_e32 v111, 0, v110, vcc
	v_cndmask_b32_e32 v110, v112, v118, vcc
	v_cndmask_b32_e32 v113, v160, v161, vcc
	v_cndmask_b32_e32 v112, v162, v163, vcc
	v_lshlrev_b64 v[110:111], 12, v[110:111]
	v_lshl_add_u64 v[112:113], v[112:113], 0, v[110:111]
	v_cndmask_b32_e32 v115, v164, v165, vcc
	v_cndmask_b32_e32 v114, v166, v167, vcc
	v_lshl_add_u64 v[116:117], v[114:115], 0, v[110:111]
	v_lshl_add_u64 v[110:111], v[112:113], 0, v[96:97]
	v_min_i32_e32 v112, 0x8000, v118
	v_ashrrev_i32_e32 v112, 12, v112
	v_mul_hi_i32_i24_e32 v113, 0x6000, v112
	v_mul_i32_i24_e32 v112, 0x6000, v112
	v_lshl_add_u64 v[112:113], s[0:1], 0, v[112:113]
	v_lshl_add_u64 v[114:115], v[112:113], 0, v[96:97]
	v_lshl_add_u64 v[112:113], v[116:117], 0, v[96:97]
	ds_read_b128 v[116:119], v146 offset:2176
	global_load_dwordx4 v[120:123], v[110:111], off
	global_load_dwordx4 v[124:127], v[114:115], off
	s_waitcnt vmcnt(0) lgkmcnt(0)
	v_pk_fma_f32 v[116:117], v[116:117], v[124:125], v[120:121]
	v_pk_fma_f32 v[118:119], v[118:119], v[126:127], v[122:123]
	v_or_b32_e32 v124, v176, v170
	global_store_dwordx4 v[112:113], v[116:119], off
	v_cmp_gt_i32_e32 vcc, s39, v124
	s_nop 0
	v_ashrrev_i32_e32 v116, 31, v124
	v_add_u32_e32 v118, 0xffff8000, v124
	v_cndmask_b32_e32 v117, 0, v116, vcc
	v_cndmask_b32_e32 v116, v118, v124, vcc
	v_cndmask_b32_e32 v119, v160, v161, vcc
	v_cndmask_b32_e32 v118, v162, v163, vcc
	v_lshlrev_b64 v[116:117], 12, v[116:117]
	v_lshl_add_u64 v[118:119], v[118:119], 0, v[116:117]
	v_cndmask_b32_e32 v121, v164, v165, vcc
	v_cndmask_b32_e32 v120, v166, v167, vcc
	v_lshl_add_u64 v[122:123], v[120:121], 0, v[116:117]
	v_lshl_add_u64 v[116:117], v[118:119], 0, v[96:97]
	v_min_i32_e32 v118, 0x8000, v124
	v_ashrrev_i32_e32 v118, 12, v118
	v_mul_hi_i32_i24_e32 v119, 0x6000, v118
	v_mul_i32_i24_e32 v118, 0x6000, v118
	v_lshl_add_u64 v[118:119], s[0:1], 0, v[118:119]
	v_lshl_add_u64 v[120:121], v[118:119], 0, v[96:97]
	v_lshl_add_u64 v[118:119], v[122:123], 0, v[96:97]
	ds_read_b128 v[122:125], v146 offset:3264
	global_load_dwordx4 v[126:129], v[116:117], off
	global_load_dwordx4 v[130:133], v[120:121], off
	s_waitcnt vmcnt(0) lgkmcnt(0)
	v_pk_fma_f32 v[122:123], v[122:123], v[130:131], v[126:127]
	v_pk_fma_f32 v[124:125], v[124:125], v[132:133], v[128:129]
	v_or_b32_e32 v130, v176, v171
	global_store_dwordx4 v[118:119], v[122:125], off
	v_cmp_gt_i32_e32 vcc, s39, v130
	s_nop 0
	v_ashrrev_i32_e32 v122, 31, v130
	v_add_u32_e32 v124, 0xffff8000, v130
	v_cndmask_b32_e32 v123, 0, v122, vcc
	v_cndmask_b32_e32 v122, v124, v130, vcc
	v_cndmask_b32_e32 v125, v160, v161, vcc
	v_cndmask_b32_e32 v124, v162, v163, vcc
	v_lshlrev_b64 v[122:123], 12, v[122:123]
	v_lshl_add_u64 v[124:125], v[124:125], 0, v[122:123]
	v_cndmask_b32_e32 v127, v164, v165, vcc
	v_cndmask_b32_e32 v126, v166, v167, vcc
	v_lshl_add_u64 v[128:129], v[126:127], 0, v[122:123]
	v_lshl_add_u64 v[122:123], v[124:125], 0, v[96:97]
	v_min_i32_e32 v124, 0x8000, v130
	v_ashrrev_i32_e32 v124, 12, v124
	v_mul_hi_i32_i24_e32 v125, 0x6000, v124
	v_mul_i32_i24_e32 v124, 0x6000, v124
	v_lshl_add_u64 v[124:125], s[0:1], 0, v[124:125]
	v_lshl_add_u64 v[126:127], v[124:125], 0, v[96:97]
	v_lshl_add_u64 v[124:125], v[128:129], 0, v[96:97]
	ds_read_b128 v[128:131], v146 offset:4352
	global_load_dwordx4 v[132:135], v[122:123], off
	global_load_dwordx4 v[136:139], v[126:127], off
	s_waitcnt vmcnt(0) lgkmcnt(0)
	v_pk_fma_f32 v[128:129], v[128:129], v[136:137], v[132:133]
	v_pk_fma_f32 v[130:131], v[130:131], v[138:139], v[134:135]
	v_or_b32_e32 v136, v176, v172
	global_store_dwordx4 v[124:125], v[128:131], off
	v_cmp_gt_i32_e32 vcc, s39, v136
	s_nop 0
	v_ashrrev_i32_e32 v128, 31, v136
	v_add_u32_e32 v130, 0xffff8000, v136
	v_cndmask_b32_e32 v129, 0, v128, vcc
	v_cndmask_b32_e32 v128, v130, v136, vcc
	v_cndmask_b32_e32 v131, v160, v161, vcc
	v_cndmask_b32_e32 v130, v162, v163, vcc
	v_lshlrev_b64 v[128:129], 12, v[128:129]
	v_lshl_add_u64 v[130:131], v[130:131], 0, v[128:129]
	v_cndmask_b32_e32 v133, v164, v165, vcc
	v_cndmask_b32_e32 v132, v166, v167, vcc
	v_lshl_add_u64 v[134:135], v[132:133], 0, v[128:129]
	v_lshl_add_u64 v[128:129], v[130:131], 0, v[96:97]
	v_min_i32_e32 v130, 0x8000, v136
	v_ashrrev_i32_e32 v130, 12, v130
	v_mul_hi_i32_i24_e32 v131, 0x6000, v130
	v_mul_i32_i24_e32 v130, 0x6000, v130
	v_lshl_add_u64 v[130:131], s[0:1], 0, v[130:131]
	v_lshl_add_u64 v[132:133], v[130:131], 0, v[96:97]
	v_lshl_add_u64 v[130:131], v[134:135], 0, v[96:97]
	ds_read_b128 v[134:137], v146 offset:5440
	global_load_dwordx4 v[138:141], v[128:129], off
	global_load_dwordx4 v[142:145], v[132:133], off
	s_waitcnt vmcnt(0) lgkmcnt(0)
	v_pk_fma_f32 v[134:135], v[134:135], v[142:143], v[138:139]
	v_pk_fma_f32 v[136:137], v[136:137], v[144:145], v[140:141]
	v_or_b32_e32 v142, v176, v173
	global_store_dwordx4 v[130:131], v[134:137], off
	v_cmp_gt_i32_e32 vcc, s39, v142
	s_nop 0
	v_ashrrev_i32_e32 v134, 31, v142
	v_add_u32_e32 v136, 0xffff8000, v142
	v_cndmask_b32_e32 v135, 0, v134, vcc
	v_cndmask_b32_e32 v134, v136, v142, vcc
	v_cndmask_b32_e32 v137, v160, v161, vcc
	v_cndmask_b32_e32 v136, v162, v163, vcc
	v_lshlrev_b64 v[134:135], 12, v[134:135]
	v_lshl_add_u64 v[136:137], v[136:137], 0, v[134:135]
	v_cndmask_b32_e32 v139, v164, v165, vcc
	v_cndmask_b32_e32 v138, v166, v167, vcc
	v_lshl_add_u64 v[140:141], v[138:139], 0, v[134:135]
	v_lshl_add_u64 v[134:135], v[136:137], 0, v[96:97]
	v_min_i32_e32 v136, 0x8000, v142
	v_ashrrev_i32_e32 v136, 12, v136
	v_mul_hi_i32_i24_e32 v137, 0x6000, v136
	v_mul_i32_i24_e32 v136, 0x6000, v136
	v_lshl_add_u64 v[136:137], s[0:1], 0, v[136:137]
	v_lshl_add_u64 v[138:139], v[136:137], 0, v[96:97]
	v_lshl_add_u64 v[136:137], v[140:141], 0, v[96:97]
	ds_read_b128 v[140:143], v146 offset:6528
	global_load_dwordx4 v[184:187], v[134:135], off
	global_load_dwordx4 v[196:199], v[138:139], off
	v_cmp_gt_i32_e32 vcc, s39, v181
	s_waitcnt vmcnt(0) lgkmcnt(0)
	v_pk_fma_f32 v[140:141], v[140:141], v[196:197], v[184:185]
	v_pk_fma_f32 v[142:143], v[142:143], v[198:199], v[186:187]
	global_store_dwordx4 v[136:137], v[140:143], off
	v_cndmask_b32_e32 v145, v164, v165, vcc
	v_cndmask_b32_e32 v144, v166, v167, vcc
	v_ashrrev_i32_e32 v140, 31, v181
	v_add_u32_e32 v142, 0xffff8000, v181
	v_cndmask_b32_e32 v141, 0, v140, vcc
	v_cndmask_b32_e32 v140, v142, v181, vcc
	v_cndmask_b32_e32 v143, v160, v161, vcc
	v_cndmask_b32_e32 v142, v162, v163, vcc
	v_lshlrev_b64 v[140:141], 12, v[140:141]
	v_lshl_add_u64 v[142:143], v[142:143], 0, v[140:141]
	v_lshl_add_u64 v[184:185], v[144:145], 0, v[140:141]
	v_lshl_add_u64 v[140:141], v[142:143], 0, v[96:97]
	v_min_i32_e32 v142, 0x8000, v181
	v_ashrrev_i32_e32 v142, 12, v142
	v_mul_hi_i32_i24_e32 v143, 0x6000, v142
	v_mul_i32_i24_e32 v142, 0x6000, v142
	v_lshl_add_u64 v[142:143], s[0:1], 0, v[142:143]
	v_lshl_add_u64 v[144:145], v[142:143], 0, v[96:97]
	v_lshl_add_u64 v[142:143], v[184:185], 0, v[96:97]
	ds_read_b128 v[184:187], v146 offset:7616
	global_load_dwordx4 v[196:199], v[140:141], off
	global_load_dwordx4 v[200:203], v[144:145], off
	s_waitcnt vmcnt(0) lgkmcnt(0)
	v_pk_fma_f32 v[184:185], v[184:185], v[200:201], v[196:197]
	v_pk_fma_f32 v[186:187], v[186:187], v[202:203], v[198:199]
	global_store_dwordx4 v[142:143], v[184:187], off
	s_waitcnt lgkmcnt(0)
	ds_write2_b32 v147, v80, v81 offset1:68
	ds_write2_b32 v148, v64, v65 offset0:32 offset1:100
	ds_write2_b32 v147, v82, v83 offset0:136 offset1:204
	ds_write2_b32 v148, v66, v67 offset0:168 offset1:236
	ds_write2_b32 v149, v84, v85 offset0:32 offset1:100
	ds_write2_b32 v150, v68, v69 offset0:64 offset1:132
	ds_write2_b32 v149, v86, v87 offset0:168 offset1:236
	ds_write2_b32 v151, v70, v71 offset0:72 offset1:140
	ds_write2_b32 v152, v88, v89 offset0:64 offset1:132
	ds_write2_b32 v153, v72, v73 offset0:96 offset1:164
	ds_write2_b32 v154, v90, v91 offset0:72 offset1:140
	ds_write2_b32 v155, v74, v75 offset0:104 offset1:172
	ds_write2_b32 v156, v92, v93 offset0:96 offset1:164
	ds_write2_b32 v157, v76, v77 offset0:128 offset1:196
	ds_write2_b32 v158, v94, v95 offset0:104 offset1:172
	ds_write2_b32 v159, v78, v79 offset0:8 offset1:76
	s_waitcnt lgkmcnt(0)
	ds_read_b128 v[64:67], v146
	global_load_dwordx4 v[68:71], v[98:99], off offset:256
	global_load_dwordx4 v[72:75], v[102:103], off offset:256
	s_waitcnt vmcnt(0) lgkmcnt(0)
	v_pk_fma_f32 v[64:65], v[64:65], v[72:73], v[68:69]
	v_pk_fma_f32 v[66:67], v[66:67], v[74:75], v[70:71]
	global_store_dwordx4 v[100:101], v[64:67], off offset:256
	ds_read_b128 v[64:67], v146 offset:1088
	global_load_dwordx4 v[68:71], v[106:107], off offset:256
	global_load_dwordx4 v[72:75], v[108:109], off offset:256
	s_waitcnt vmcnt(0) lgkmcnt(0)
	v_pk_fma_f32 v[64:65], v[64:65], v[72:73], v[68:69]
	v_pk_fma_f32 v[66:67], v[66:67], v[74:75], v[70:71]
	global_store_dwordx4 v[104:105], v[64:67], off offset:256
	ds_read_b128 v[64:67], v146 offset:2176
	global_load_dwordx4 v[68:71], v[110:111], off offset:256
	global_load_dwordx4 v[72:75], v[114:115], off offset:256
	s_waitcnt vmcnt(0) lgkmcnt(0)
	v_pk_fma_f32 v[64:65], v[64:65], v[72:73], v[68:69]
	v_pk_fma_f32 v[66:67], v[66:67], v[74:75], v[70:71]
	global_store_dwordx4 v[112:113], v[64:67], off offset:256
	ds_read_b128 v[64:67], v146 offset:3264
	global_load_dwordx4 v[68:71], v[116:117], off offset:256
	global_load_dwordx4 v[72:75], v[120:121], off offset:256
	s_waitcnt vmcnt(0) lgkmcnt(0)
	v_pk_fma_f32 v[64:65], v[64:65], v[72:73], v[68:69]
	v_pk_fma_f32 v[66:67], v[66:67], v[74:75], v[70:71]
	global_store_dwordx4 v[118:119], v[64:67], off offset:256
	ds_read_b128 v[64:67], v146 offset:4352
	global_load_dwordx4 v[68:71], v[122:123], off offset:256
	global_load_dwordx4 v[72:75], v[126:127], off offset:256
	s_waitcnt vmcnt(0) lgkmcnt(0)
	v_pk_fma_f32 v[64:65], v[64:65], v[72:73], v[68:69]
	v_pk_fma_f32 v[66:67], v[66:67], v[74:75], v[70:71]
	global_store_dwordx4 v[124:125], v[64:67], off offset:256
	ds_read_b128 v[64:67], v146 offset:5440
	global_load_dwordx4 v[68:71], v[128:129], off offset:256
	global_load_dwordx4 v[72:75], v[132:133], off offset:256
	s_waitcnt vmcnt(0) lgkmcnt(0)
	v_pk_fma_f32 v[64:65], v[64:65], v[72:73], v[68:69]
	v_pk_fma_f32 v[66:67], v[66:67], v[74:75], v[70:71]
	global_store_dwordx4 v[130:131], v[64:67], off offset:256
	ds_read_b128 v[64:67], v146 offset:6528
	global_load_dwordx4 v[68:71], v[134:135], off offset:256
	global_load_dwordx4 v[72:75], v[138:139], off offset:256
	s_waitcnt vmcnt(0) lgkmcnt(0)
	v_pk_fma_f32 v[64:65], v[64:65], v[72:73], v[68:69]
	v_pk_fma_f32 v[66:67], v[66:67], v[74:75], v[70:71]
	global_store_dwordx4 v[136:137], v[64:67], off offset:256
	ds_read_b128 v[64:67], v146 offset:7616
	global_load_dwordx4 v[68:71], v[140:141], off offset:256
	global_load_dwordx4 v[72:75], v[144:145], off offset:256
	s_waitcnt vmcnt(0) lgkmcnt(0)
	v_pk_fma_f32 v[64:65], v[64:65], v[72:73], v[68:69]
	v_pk_fma_f32 v[66:67], v[66:67], v[74:75], v[70:71]
	global_store_dwordx4 v[142:143], v[64:67], off offset:256
	v_or_b32_e32 v74, 32, v176
	s_waitcnt lgkmcnt(0)
	ds_write2_b32 v147, v48, v49 offset1:68
	ds_write2_b32 v148, v32, v33 offset0:32 offset1:100
	ds_write2_b32 v147, v50, v51 offset0:136 offset1:204
	ds_write2_b32 v148, v34, v35 offset0:168 offset1:236
	ds_write2_b32 v149, v52, v53 offset0:32 offset1:100
	ds_write2_b32 v150, v36, v37 offset0:64 offset1:132
	ds_write2_b32 v149, v54, v55 offset0:168 offset1:236
	ds_write2_b32 v151, v38, v39 offset0:72 offset1:140
	ds_write2_b32 v152, v56, v57 offset0:64 offset1:132
	ds_write2_b32 v153, v40, v41 offset0:96 offset1:164
	ds_write2_b32 v154, v58, v59 offset0:72 offset1:140
	ds_write2_b32 v155, v42, v43 offset0:104 offset1:172
	ds_write2_b32 v156, v60, v61 offset0:96 offset1:164
	ds_write2_b32 v157, v44, v45 offset0:128 offset1:196
	ds_write2_b32 v158, v62, v63 offset0:104 offset1:172
	ds_write2_b32 v159, v46, v47 offset0:8 offset1:76
	v_or_b32_e32 v40, v74, v175
	v_cmp_gt_i32_e32 vcc, s39, v40
	v_ashrrev_i32_e32 v32, 31, v40
	v_add_u32_e32 v34, 0xffff8000, v40
	v_cndmask_b32_e32 v33, 0, v32, vcc
	v_cndmask_b32_e32 v32, v34, v40, vcc
	v_cndmask_b32_e32 v35, v160, v161, vcc
	v_cndmask_b32_e32 v34, v162, v163, vcc
	v_lshlrev_b64 v[32:33], 12, v[32:33]
	v_lshl_add_u64 v[34:35], v[34:35], 0, v[32:33]
	v_cndmask_b32_e32 v37, v164, v165, vcc
	v_cndmask_b32_e32 v36, v166, v167, vcc
	v_lshl_add_u64 v[38:39], v[36:37], 0, v[32:33]
	v_lshl_add_u64 v[32:33], v[34:35], 0, v[96:97]
	v_min_i32_e32 v34, 0x8000, v40
	v_ashrrev_i32_e32 v34, 12, v34
	v_mul_hi_i32_i24_e32 v35, 0x6000, v34
	v_mul_i32_i24_e32 v34, 0x6000, v34
	s_waitcnt lgkmcnt(0)
	v_lshl_add_u64 v[34:35], s[0:1], 0, v[34:35]
	v_lshl_add_u64 v[36:37], v[34:35], 0, v[96:97]
	v_lshl_add_u64 v[34:35], v[38:39], 0, v[96:97]
	ds_read_b128 v[38:41], v146
	global_load_dwordx4 v[42:45], v[32:33], off
	global_load_dwordx4 v[46:49], v[36:37], off
	v_or_b32_e32 v75, v74, v173
	s_waitcnt vmcnt(0) lgkmcnt(0)
	v_pk_fma_f32 v[38:39], v[38:39], v[46:47], v[42:43]
	v_pk_fma_f32 v[40:41], v[40:41], v[48:49], v[44:45]
	v_or_b32_e32 v46, v74, v168
	global_store_dwordx4 v[34:35], v[38:41], off
	v_cmp_gt_i32_e32 vcc, s39, v46
	s_nop 0
	v_ashrrev_i32_e32 v38, 31, v46
	v_add_u32_e32 v40, 0xffff8000, v46
	v_cndmask_b32_e32 v39, 0, v38, vcc
	v_cndmask_b32_e32 v38, v40, v46, vcc
	v_cndmask_b32_e32 v41, v160, v161, vcc
	v_cndmask_b32_e32 v40, v162, v163, vcc
	v_lshlrev_b64 v[38:39], 12, v[38:39]
	v_lshl_add_u64 v[40:41], v[40:41], 0, v[38:39]
	v_cndmask_b32_e32 v43, v164, v165, vcc
	v_cndmask_b32_e32 v42, v166, v167, vcc
	v_lshl_add_u64 v[44:45], v[42:43], 0, v[38:39]
	v_lshl_add_u64 v[38:39], v[40:41], 0, v[96:97]
	v_min_i32_e32 v40, 0x8000, v46
	v_ashrrev_i32_e32 v40, 12, v40
	v_mul_hi_i32_i24_e32 v41, 0x6000, v40
	v_mul_i32_i24_e32 v40, 0x6000, v40
	v_lshl_add_u64 v[40:41], s[0:1], 0, v[40:41]
	v_lshl_add_u64 v[42:43], v[40:41], 0, v[96:97]
	v_lshl_add_u64 v[40:41], v[44:45], 0, v[96:97]
	ds_read_b128 v[44:47], v146 offset:1088
	global_load_dwordx4 v[48:51], v[38:39], off
	global_load_dwordx4 v[52:55], v[42:43], off
	s_waitcnt vmcnt(0) lgkmcnt(0)
	v_pk_fma_f32 v[44:45], v[44:45], v[52:53], v[48:49]
	v_pk_fma_f32 v[46:47], v[46:47], v[54:55], v[50:51]
	v_or_b32_e32 v52, v74, v169
	global_store_dwordx4 v[40:41], v[44:47], off
	v_cmp_gt_i32_e32 vcc, s39, v52
	s_nop 0
	v_ashrrev_i32_e32 v44, 31, v52
	v_add_u32_e32 v46, 0xffff8000, v52
	v_cndmask_b32_e32 v45, 0, v44, vcc
	v_cndmask_b32_e32 v44, v46, v52, vcc
	v_cndmask_b32_e32 v47, v160, v161, vcc
	v_cndmask_b32_e32 v46, v162, v163, vcc
	v_lshlrev_b64 v[44:45], 12, v[44:45]
	v_lshl_add_u64 v[46:47], v[46:47], 0, v[44:45]
	v_cndmask_b32_e32 v49, v164, v165, vcc
	v_cndmask_b32_e32 v48, v166, v167, vcc
	v_lshl_add_u64 v[50:51], v[48:49], 0, v[44:45]
	v_lshl_add_u64 v[44:45], v[46:47], 0, v[96:97]
	v_min_i32_e32 v46, 0x8000, v52
	v_ashrrev_i32_e32 v46, 12, v46
	v_mul_hi_i32_i24_e32 v47, 0x6000, v46
	v_mul_i32_i24_e32 v46, 0x6000, v46
	v_lshl_add_u64 v[46:47], s[0:1], 0, v[46:47]
	v_lshl_add_u64 v[48:49], v[46:47], 0, v[96:97]
	v_lshl_add_u64 v[46:47], v[50:51], 0, v[96:97]
	ds_read_b128 v[50:53], v146 offset:2176
	global_load_dwordx4 v[54:57], v[44:45], off
	global_load_dwordx4 v[58:61], v[48:49], off
	s_waitcnt vmcnt(0) lgkmcnt(0)
	v_pk_fma_f32 v[50:51], v[50:51], v[58:59], v[54:55]
	v_pk_fma_f32 v[52:53], v[52:53], v[60:61], v[56:57]
	v_or_b32_e32 v58, v74, v170
	global_store_dwordx4 v[46:47], v[50:53], off
	v_cmp_gt_i32_e32 vcc, s39, v58
	s_nop 0
	v_ashrrev_i32_e32 v50, 31, v58
	v_add_u32_e32 v52, 0xffff8000, v58
	v_cndmask_b32_e32 v51, 0, v50, vcc
	v_cndmask_b32_e32 v50, v52, v58, vcc
	v_cndmask_b32_e32 v53, v160, v161, vcc
	v_cndmask_b32_e32 v52, v162, v163, vcc
	v_lshlrev_b64 v[50:51], 12, v[50:51]
	v_lshl_add_u64 v[52:53], v[52:53], 0, v[50:51]
	v_cndmask_b32_e32 v55, v164, v165, vcc
	v_cndmask_b32_e32 v54, v166, v167, vcc
	v_lshl_add_u64 v[56:57], v[54:55], 0, v[50:51]
	v_lshl_add_u64 v[50:51], v[52:53], 0, v[96:97]
	v_min_i32_e32 v52, 0x8000, v58
	v_ashrrev_i32_e32 v52, 12, v52
	v_mul_hi_i32_i24_e32 v53, 0x6000, v52
	v_mul_i32_i24_e32 v52, 0x6000, v52
	v_lshl_add_u64 v[52:53], s[0:1], 0, v[52:53]
	v_lshl_add_u64 v[54:55], v[52:53], 0, v[96:97]
	v_lshl_add_u64 v[52:53], v[56:57], 0, v[96:97]
	ds_read_b128 v[56:59], v146 offset:3264
	global_load_dwordx4 v[60:63], v[50:51], off
	global_load_dwordx4 v[64:67], v[54:55], off
	s_waitcnt vmcnt(0) lgkmcnt(0)
	v_pk_fma_f32 v[56:57], v[56:57], v[64:65], v[60:61]
	v_pk_fma_f32 v[58:59], v[58:59], v[66:67], v[62:63]
	v_or_b32_e32 v64, v74, v171
	global_store_dwordx4 v[52:53], v[56:59], off
	v_cmp_gt_i32_e32 vcc, s39, v64
	s_nop 0
	v_ashrrev_i32_e32 v56, 31, v64
	v_add_u32_e32 v58, 0xffff8000, v64
	v_cndmask_b32_e32 v57, 0, v56, vcc
	v_cndmask_b32_e32 v56, v58, v64, vcc
	v_cndmask_b32_e32 v59, v160, v161, vcc
	v_cndmask_b32_e32 v58, v162, v163, vcc
	v_lshlrev_b64 v[56:57], 12, v[56:57]
	v_lshl_add_u64 v[58:59], v[58:59], 0, v[56:57]
	v_cndmask_b32_e32 v61, v164, v165, vcc
	v_cndmask_b32_e32 v60, v166, v167, vcc
	v_lshl_add_u64 v[62:63], v[60:61], 0, v[56:57]
	v_lshl_add_u64 v[56:57], v[58:59], 0, v[96:97]
	v_min_i32_e32 v58, 0x8000, v64
	v_ashrrev_i32_e32 v58, 12, v58
	v_mul_hi_i32_i24_e32 v59, 0x6000, v58
	v_mul_i32_i24_e32 v58, 0x6000, v58
	v_lshl_add_u64 v[58:59], s[0:1], 0, v[58:59]
	v_lshl_add_u64 v[60:61], v[58:59], 0, v[96:97]
	v_lshl_add_u64 v[58:59], v[62:63], 0, v[96:97]
	ds_read_b128 v[62:65], v146 offset:4352
	global_load_dwordx4 v[66:69], v[56:57], off
	global_load_dwordx4 v[70:73], v[60:61], off
	s_waitcnt vmcnt(0) lgkmcnt(0)
	v_pk_fma_f32 v[62:63], v[62:63], v[70:71], v[66:67]
	v_pk_fma_f32 v[64:65], v[64:65], v[72:73], v[68:69]
	v_or_b32_e32 v70, v74, v172
	global_store_dwordx4 v[58:59], v[62:65], off
	v_cmp_gt_i32_e32 vcc, s39, v70
	s_nop 0
	v_ashrrev_i32_e32 v62, 31, v70
	v_add_u32_e32 v64, 0xffff8000, v70
	v_cndmask_b32_e32 v63, 0, v62, vcc
	v_cndmask_b32_e32 v62, v64, v70, vcc
	v_cndmask_b32_e32 v65, v160, v161, vcc
	v_cndmask_b32_e32 v64, v162, v163, vcc
	v_lshlrev_b64 v[62:63], 12, v[62:63]
	v_lshl_add_u64 v[64:65], v[64:65], 0, v[62:63]
	v_cndmask_b32_e32 v67, v164, v165, vcc
	v_cndmask_b32_e32 v66, v166, v167, vcc
	v_lshl_add_u64 v[68:69], v[66:67], 0, v[62:63]
	v_lshl_add_u64 v[62:63], v[64:65], 0, v[96:97]
	v_min_i32_e32 v64, 0x8000, v70
	v_ashrrev_i32_e32 v64, 12, v64
	v_mul_hi_i32_i24_e32 v65, 0x6000, v64
	v_mul_i32_i24_e32 v64, 0x6000, v64
	v_lshl_add_u64 v[64:65], s[0:1], 0, v[64:65]
	v_lshl_add_u64 v[66:67], v[64:65], 0, v[96:97]
	v_lshl_add_u64 v[64:65], v[68:69], 0, v[96:97]
	ds_read_b128 v[68:71], v146 offset:5440
	global_load_dwordx4 v[76:79], v[62:63], off
	global_load_dwordx4 v[80:83], v[66:67], off
	v_cmp_gt_i32_e32 vcc, s39, v75
	s_waitcnt vmcnt(0) lgkmcnt(0)
	v_pk_fma_f32 v[68:69], v[68:69], v[80:81], v[76:77]
	v_pk_fma_f32 v[70:71], v[70:71], v[82:83], v[78:79]
	global_store_dwordx4 v[64:65], v[68:71], off
	v_cndmask_b32_e32 v73, v164, v165, vcc
	v_cndmask_b32_e32 v72, v166, v167, vcc
	v_ashrrev_i32_e32 v68, 31, v75
	v_add_u32_e32 v70, 0xffff8000, v75
	v_cndmask_b32_e32 v69, 0, v68, vcc
	v_cndmask_b32_e32 v68, v70, v75, vcc
	v_cndmask_b32_e32 v71, v160, v161, vcc
	v_cndmask_b32_e32 v70, v162, v163, vcc
	v_lshlrev_b64 v[68:69], 12, v[68:69]
	v_lshl_add_u64 v[70:71], v[70:71], 0, v[68:69]
	v_lshl_add_u64 v[76:77], v[72:73], 0, v[68:69]
	v_lshl_add_u64 v[68:69], v[70:71], 0, v[96:97]
	v_min_i32_e32 v70, 0x8000, v75
	v_ashrrev_i32_e32 v70, 12, v70
	v_mul_hi_i32_i24_e32 v71, 0x6000, v70
	v_mul_i32_i24_e32 v70, 0x6000, v70
	v_lshl_add_u64 v[70:71], s[0:1], 0, v[70:71]
	v_lshl_add_u64 v[72:73], v[70:71], 0, v[96:97]
	v_lshl_add_u64 v[70:71], v[76:77], 0, v[96:97]
	ds_read_b128 v[76:79], v146 offset:6528
	global_load_dwordx4 v[80:83], v[68:69], off
	global_load_dwordx4 v[84:87], v[72:73], off
	s_waitcnt vmcnt(0) lgkmcnt(0)
	v_pk_fma_f32 v[76:77], v[76:77], v[84:85], v[80:81]
	v_pk_fma_f32 v[78:79], v[78:79], v[86:87], v[82:83]
	v_or_b32_e32 v82, v74, v174
	global_store_dwordx4 v[70:71], v[76:79], off
	v_cmp_gt_i32_e32 vcc, s39, v82
	v_ashrrev_i32_e32 v74, 31, v82
	v_add_u32_e32 v76, 0xffff8000, v82
	v_cndmask_b32_e32 v75, 0, v74, vcc
	v_cndmask_b32_e32 v74, v76, v82, vcc
	v_cndmask_b32_e32 v77, v160, v161, vcc
	v_cndmask_b32_e32 v76, v162, v163, vcc
	v_lshlrev_b64 v[74:75], 12, v[74:75]
	v_lshl_add_u64 v[76:77], v[76:77], 0, v[74:75]
	v_cndmask_b32_e32 v79, v164, v165, vcc
	v_cndmask_b32_e32 v78, v166, v167, vcc
	v_lshl_add_u64 v[80:81], v[78:79], 0, v[74:75]
	v_lshl_add_u64 v[74:75], v[76:77], 0, v[96:97]
	v_min_i32_e32 v76, 0x8000, v82
	v_ashrrev_i32_e32 v76, 12, v76
	v_mul_hi_i32_i24_e32 v77, 0x6000, v76
	v_mul_i32_i24_e32 v76, 0x6000, v76
	v_lshl_add_u64 v[76:77], s[0:1], 0, v[76:77]
	v_lshl_add_u64 v[78:79], v[76:77], 0, v[96:97]
	v_lshl_add_u64 v[76:77], v[80:81], 0, v[96:97]
	ds_read_b128 v[80:83], v146 offset:7616
	global_load_dwordx4 v[84:87], v[74:75], off
	global_load_dwordx4 v[88:91], v[78:79], off
	s_waitcnt vmcnt(0) lgkmcnt(0)
	v_pk_fma_f32 v[80:81], v[80:81], v[88:89], v[84:85]
	v_pk_fma_f32 v[82:83], v[82:83], v[90:91], v[86:87]
	global_store_dwordx4 v[76:77], v[80:83], off
	s_waitcnt lgkmcnt(0)
	ds_write2_b32 v147, v16, v17 offset1:68
	ds_write2_b32 v148, v0, v1 offset0:32 offset1:100
	ds_write2_b32 v147, v18, v19 offset0:136 offset1:204
	ds_write2_b32 v148, v2, v3 offset0:168 offset1:236
	ds_write2_b32 v149, v20, v21 offset0:32 offset1:100
	ds_write2_b32 v150, v4, v5 offset0:64 offset1:132
	ds_write2_b32 v149, v22, v23 offset0:168 offset1:236
	ds_write2_b32 v151, v6, v7 offset0:72 offset1:140
	ds_write2_b32 v152, v24, v25 offset0:64 offset1:132
	ds_write2_b32 v153, v8, v9 offset0:96 offset1:164
	ds_write2_b32 v154, v26, v27 offset0:72 offset1:140
	ds_write2_b32 v155, v10, v11 offset0:104 offset1:172
	ds_write2_b32 v156, v28, v29 offset0:96 offset1:164
	ds_write2_b32 v157, v12, v13 offset0:128 offset1:196
	ds_write2_b32 v158, v30, v31 offset0:104 offset1:172
	ds_write2_b32 v159, v14, v15 offset0:8 offset1:76
	s_waitcnt lgkmcnt(0)
	ds_read_b128 v[0:3], v146
	global_load_dwordx4 v[4:7], v[32:33], off offset:256
	global_load_dwordx4 v[8:11], v[36:37], off offset:256
	s_waitcnt vmcnt(0) lgkmcnt(0)
	v_pk_fma_f32 v[0:1], v[0:1], v[8:9], v[4:5]
	v_pk_fma_f32 v[2:3], v[2:3], v[10:11], v[6:7]
	global_store_dwordx4 v[34:35], v[0:3], off offset:256
	ds_read_b128 v[0:3], v146 offset:1088
	global_load_dwordx4 v[4:7], v[38:39], off offset:256
	global_load_dwordx4 v[8:11], v[42:43], off offset:256
	s_waitcnt vmcnt(0) lgkmcnt(0)
	v_pk_fma_f32 v[0:1], v[0:1], v[8:9], v[4:5]
	v_pk_fma_f32 v[2:3], v[2:3], v[10:11], v[6:7]
	global_store_dwordx4 v[40:41], v[0:3], off offset:256
	ds_read_b128 v[0:3], v146 offset:2176
	global_load_dwordx4 v[4:7], v[44:45], off offset:256
	global_load_dwordx4 v[8:11], v[48:49], off offset:256
	s_waitcnt vmcnt(0) lgkmcnt(0)
	v_pk_fma_f32 v[0:1], v[0:1], v[8:9], v[4:5]
	v_pk_fma_f32 v[2:3], v[2:3], v[10:11], v[6:7]
	global_store_dwordx4 v[46:47], v[0:3], off offset:256
	ds_read_b128 v[0:3], v146 offset:3264
	global_load_dwordx4 v[4:7], v[50:51], off offset:256
	global_load_dwordx4 v[8:11], v[54:55], off offset:256
	s_waitcnt vmcnt(0) lgkmcnt(0)
	v_pk_fma_f32 v[0:1], v[0:1], v[8:9], v[4:5]
	v_pk_fma_f32 v[2:3], v[2:3], v[10:11], v[6:7]
	global_store_dwordx4 v[52:53], v[0:3], off offset:256
	ds_read_b128 v[0:3], v146 offset:4352
	global_load_dwordx4 v[4:7], v[56:57], off offset:256
	global_load_dwordx4 v[8:11], v[60:61], off offset:256
	s_waitcnt vmcnt(0) lgkmcnt(0)
	v_pk_fma_f32 v[0:1], v[0:1], v[8:9], v[4:5]
	v_pk_fma_f32 v[2:3], v[2:3], v[10:11], v[6:7]
	global_store_dwordx4 v[58:59], v[0:3], off offset:256
	ds_read_b128 v[0:3], v146 offset:5440
	global_load_dwordx4 v[4:7], v[62:63], off offset:256
	global_load_dwordx4 v[8:11], v[66:67], off offset:256
	s_waitcnt vmcnt(0) lgkmcnt(0)
	v_pk_fma_f32 v[0:1], v[0:1], v[8:9], v[4:5]
	v_pk_fma_f32 v[2:3], v[2:3], v[10:11], v[6:7]
	global_store_dwordx4 v[64:65], v[0:3], off offset:256
	ds_read_b128 v[0:3], v146 offset:6528
	global_load_dwordx4 v[4:7], v[68:69], off offset:256
	global_load_dwordx4 v[8:11], v[72:73], off offset:256
	s_waitcnt vmcnt(0) lgkmcnt(0)
	v_pk_fma_f32 v[0:1], v[0:1], v[8:9], v[4:5]
	v_pk_fma_f32 v[2:3], v[2:3], v[10:11], v[6:7]
	global_store_dwordx4 v[70:71], v[0:3], off offset:256
	ds_read_b128 v[0:3], v146 offset:7616
	global_load_dwordx4 v[4:7], v[74:75], off offset:256
	global_load_dwordx4 v[8:11], v[78:79], off offset:256
	s_waitcnt vmcnt(0) lgkmcnt(0)
	v_pk_fma_f32 v[0:1], v[0:1], v[8:9], v[4:5]
	v_pk_fma_f32 v[2:3], v[2:3], v[10:11], v[6:7]
	global_store_dwordx4 v[76:77], v[0:3], off offset:256
	s_waitcnt lgkmcnt(0)
	s_barrier
	s_cbranch_scc1 .LBB0_923

.LBB0_1031:
	s_mul_hi_i32 s0, s2, 0x2e8ba2e9
	s_lshr_b32 s1, s0, 31
	s_ashr_i32 s0, s0, 6
	s_add_i32 s0, s0, s1
	s_lshl_b32 s1, s0, 3
	s_sub_i32 s7, s25, s1
	s_min_i32 s7, s7, 8
	s_abs_i32 s8, s7
	v_cvt_f32_u32_e32 v0, s8
	s_sub_i32 s11, 0, s8
	s_mulk_i32 s0, 0xfea0
	s_add_i32 s9, s0, s2
	v_rcp_iflag_f32_e32 v0, v0
	s_abs_i32 s0, s9
	s_xor_b32 s10, s9, s7
	s_ashr_i32 s10, s10, 31
	v_mul_f32_e32 v0, 0x4f7ffffe, v0
	v_cvt_u32_f32_e32 v0, v0
	v_mov_b32_e32 v237, v179
	v_readfirstlane_b32 s12, v0
	s_mul_i32 s11, s11, s12
	s_mul_hi_u32 s11, s12, s11
	s_add_i32 s12, s12, s11
	s_mul_hi_u32 s11, s0, s12
	s_mul_i32 s12, s11, s8
	s_sub_i32 s0, s0, s12
	s_add_i32 s13, s11, 1
	s_sub_i32 s12, s0, s8
	s_cmp_ge_u32 s0, s8
	s_cselect_b32 s11, s13, s11
	s_cselect_b32 s0, s12, s0
	s_add_i32 s12, s11, 1
	s_cmp_ge_u32 s0, s8
	s_cselect_b32 s0, s12, s11
	s_xor_b32 s0, s0, s10
	s_sub_i32 s0, s0, s10
	s_mul_i32 s7, s7, s0
	s_sub_i32 s7, s9, s7
	s_add_i32 s1, s1, s6
	v_ashrrev_i32_e32 v238, 6, v237
	s_add_i32 s7, s1, s7
	v_lshlrev_b32_e32 v0, 1, v238
	v_lshl_add_u32 v0, s7, 3, v0
	v_ashrrev_i32_e32 v1, 31, v0
	v_bfe_u32 v183, v237, 5, 1
	v_lshlrev_b64 v[0:1], 16, v[0:1]
	v_and_b32_e32 v239, 31, v237
	v_lshl_add_u64 v[0:1], s[64:65], 0, v[0:1]
	v_lshlrev_b32_e32 v176, 9, v183
	s_ashr_i32 s1, s0, 31
	v_lshl_add_u64 v[0:1], v[0:1], 0, v[176:177]
	v_lshlrev_b32_e32 v176, 4, v239
	v_ashrrev_i32_e32 v38, 2, v237
	s_lshl_b64 s[8:9], s[0:1], 18
	v_lshl_add_u64 v[184:185], v[0:1], 0, v[176:177]
	s_add_u32 s8, s4, s8
	v_lshlrev_b32_e32 v0, 5, v38
	v_lshlrev_b32_e32 v2, 3, v237
	s_addc_u32 s9, s5, s9
	v_ashrrev_i32_e32 v1, 31, v0
	v_and_b32_e32 v181, 24, v2
	v_lshl_add_u64 v[0:1], v[0:1], 1, s[8:9]
	v_lshlrev_b32_e32 v176, 1, v181
	v_lshl_add_u64 v[186:187], v[0:1], 0, v[176:177]
	s_movk_i32 s1, 0x2000
	v_add_co_u32_e32 v34, vcc, s1, v186
	v_mul_u32_u24_e32 v36, 40, v239
	s_nop 0
	v_addc_co_u32_e32 v35, vcc, 0, v187, vcc
	v_lshlrev_b32_e32 v37, 4, v183
	v_lshl_add_u32 v241, v36, 1, v37
	v_add_co_u32_e32 v36, vcc, s41, v184
	s_movk_i32 s8, 0x50
	s_nop 0
	v_addc_co_u32_e32 v37, vcc, 0, v185, vcc
	v_mad_u64_u32 v[188:189], s[8:9], v38, s8, v[176:177]
	v_and_b32_e32 v240, 63, v237
	v_mov_b32_e32 v176, 0x800
	v_lshl_add_u64 v[188:189], v[186:187], 0, v[176:177]
	v_bfe_u32 v247, v237, 4, 1
	v_lshlrev_b32_e32 v176, 9, v183
	v_lshl_add_u32 v176, v247, 8, v176
	v_lshl_add_u64 v[184:185], v[184:185], 0, v[176:177]
	v_mov_b32_e32 v176, s41
	v_lshl_add_u64 v[186:187], v[184:185], 0, v[176:177]
	v_lshrrev_b32_e32 v241, 2, v237
	v_bfe_u32 v247, v237, 4, 2
	v_lshlrev_b32_e32 v247, 1, v247
	v_mov_b32_e32 v176, 0x78
	v_lshrrev_b32_e32 v247, v247, v176
	v_and_b32_e32 v247, 3, v247
	v_and_b32_e32 v246, 3, v237
	v_xor_b32_e32 v247, v247, v246
	v_lshlrev_b32_e32 v247, 4, v247
	v_lshl_add_u32 v241, v241, 6, v247
	v_bfe_u32 v247, v237, 2, 2
	v_lshlrev_b32_e32 v247, 1, v247
	v_lshrrev_b32_e32 v247, v247, v176
	v_and_b32_e32 v247, 3, v247
	v_bfe_u32 v246, v237, 4, 2
	v_xor_b32_e32 v247, v247, v246
	v_lshlrev_b32_e32 v247, 4, v247
	v_and_b32_e32 v246, 15, v237
	v_lshl_add_u32 v246, v246, 6, v247
	s_mov_b32 s96, 0
	v_lshl_add_u64 v[166:167], v[188:189], 0, s[96:97]
	global_load_dwordx4 v[160:163], v[166:167], off offset:-2048
	global_load_dwordx4 v[164:167], v[166:167], off offset:2048
	s_movk_i32 s96, 0x2000
	v_lshl_add_u64 v[174:175], v[188:189], 0, s[96:97]
	global_load_dwordx4 v[168:171], v[174:175], off offset:-2048
	global_load_dwordx4 v[172:175], v[174:175], off offset:2048
	s_mov_b32 s96, 0
	v_lshl_add_u64 v[248:249], v[184:185], 0, s[96:97]
	v_lshl_add_u64 v[250:251], v[186:187], 0, s[96:97]
	global_load_dwordx4 v[128:131], v[248:249], off
	global_load_dwordx4 v[132:135], v[248:249], off offset:256
	global_load_dwordx4 v[136:139], v[250:251], off
	global_load_dwordx4 v[140:143], v[250:251], off offset:256
	v_mov_b32_e32 v0, 0
	v_mov_b32_e32 v1, 0
	v_mov_b32_e32 v2, 0
	v_mov_b32_e32 v3, 0
	v_mov_b32_e32 v4, 0
	v_mov_b32_e32 v5, 0
	v_mov_b32_e32 v6, 0
	v_mov_b32_e32 v7, 0
	v_mov_b32_e32 v8, 0
	v_mov_b32_e32 v9, 0
	v_mov_b32_e32 v10, 0
	v_mov_b32_e32 v11, 0
	v_mov_b32_e32 v12, 0
	v_mov_b32_e32 v13, 0
	v_mov_b32_e32 v14, 0
	v_mov_b32_e32 v15, 0
	v_mov_b32_e32 v16, 0
	v_mov_b32_e32 v17, 0
	v_mov_b32_e32 v18, 0
	v_mov_b32_e32 v19, 0
	v_mov_b32_e32 v20, 0
	v_mov_b32_e32 v21, 0
	v_mov_b32_e32 v22, 0
	v_mov_b32_e32 v23, 0
	v_mov_b32_e32 v24, 0
	v_mov_b32_e32 v25, 0
	v_mov_b32_e32 v26, 0
	v_mov_b32_e32 v27, 0
	v_mov_b32_e32 v28, 0
	v_mov_b32_e32 v29, 0
	v_mov_b32_e32 v30, 0
	v_mov_b32_e32 v31, 0
	v_mov_b32_e32 v32, 0
	v_mov_b32_e32 v33, 0
	v_mov_b32_e32 v34, 0
	v_mov_b32_e32 v35, 0
	v_mov_b32_e32 v36, 0
	v_mov_b32_e32 v37, 0
	v_mov_b32_e32 v38, 0
	v_mov_b32_e32 v39, 0
	v_mov_b32_e32 v40, 0
	v_mov_b32_e32 v41, 0
	v_mov_b32_e32 v42, 0
	v_mov_b32_e32 v43, 0
	v_mov_b32_e32 v44, 0
	v_mov_b32_e32 v45, 0
	v_mov_b32_e32 v46, 0
	v_mov_b32_e32 v47, 0
	v_mov_b32_e32 v48, 0
	v_mov_b32_e32 v49, 0
	v_mov_b32_e32 v50, 0
	v_mov_b32_e32 v51, 0
	v_mov_b32_e32 v52, 0
	v_mov_b32_e32 v53, 0
	v_mov_b32_e32 v54, 0
	v_mov_b32_e32 v55, 0
	v_mov_b32_e32 v56, 0
	v_mov_b32_e32 v57, 0
	v_mov_b32_e32 v58, 0
	v_mov_b32_e32 v59, 0
	v_mov_b32_e32 v60, 0
	v_mov_b32_e32 v61, 0
	v_mov_b32_e32 v62, 0
	v_mov_b32_e32 v63, 0
	v_mov_b32_e32 v64, 0
	v_mov_b32_e32 v65, 0
	v_mov_b32_e32 v66, 0
	v_mov_b32_e32 v67, 0
	v_mov_b32_e32 v68, 0
	v_mov_b32_e32 v69, 0
	v_mov_b32_e32 v70, 0
	v_mov_b32_e32 v71, 0
	v_mov_b32_e32 v72, 0
	v_mov_b32_e32 v73, 0
	v_mov_b32_e32 v74, 0
	v_mov_b32_e32 v75, 0
	v_mov_b32_e32 v76, 0
	v_mov_b32_e32 v77, 0
	v_mov_b32_e32 v78, 0
	v_mov_b32_e32 v79, 0
	v_mov_b32_e32 v80, 0
	v_mov_b32_e32 v81, 0
	v_mov_b32_e32 v82, 0
	v_mov_b32_e32 v83, 0
	v_mov_b32_e32 v84, 0
	v_mov_b32_e32 v85, 0
	v_mov_b32_e32 v86, 0
	v_mov_b32_e32 v87, 0
	v_mov_b32_e32 v88, 0
	v_mov_b32_e32 v89, 0
	v_mov_b32_e32 v90, 0
	v_mov_b32_e32 v91, 0
	v_mov_b32_e32 v92, 0
	v_mov_b32_e32 v93, 0
	v_mov_b32_e32 v94, 0
	v_mov_b32_e32 v95, 0
	v_mov_b32_e32 v96, 0
	v_mov_b32_e32 v97, 0
	v_mov_b32_e32 v98, 0
	v_mov_b32_e32 v99, 0
	v_mov_b32_e32 v100, 0
	v_mov_b32_e32 v101, 0
	v_mov_b32_e32 v102, 0
	v_mov_b32_e32 v103, 0
	v_mov_b32_e32 v104, 0
	v_mov_b32_e32 v105, 0
	v_mov_b32_e32 v106, 0
	v_mov_b32_e32 v107, 0
	v_mov_b32_e32 v108, 0
	v_mov_b32_e32 v109, 0
	v_mov_b32_e32 v110, 0
	v_mov_b32_e32 v111, 0
	v_mov_b32_e32 v112, 0
	v_mov_b32_e32 v113, 0
	v_mov_b32_e32 v114, 0
	v_mov_b32_e32 v115, 0
	v_mov_b32_e32 v116, 0
	v_mov_b32_e32 v117, 0
	v_mov_b32_e32 v118, 0
	v_mov_b32_e32 v119, 0
	v_mov_b32_e32 v120, 0
	v_mov_b32_e32 v121, 0
	v_mov_b32_e32 v122, 0
	v_mov_b32_e32 v123, 0
	v_mov_b32_e32 v124, 0
	v_mov_b32_e32 v125, 0
	v_mov_b32_e32 v126, 0
	v_mov_b32_e32 v127, 0
	s_mov_b32 s1, 0
	s_waitcnt vmcnt(4)
	ds_write_b128 v241, v[160:163]
	ds_write_b128 v241, v[164:167] offset:4096
	ds_write_b128 v241, v[168:171] offset:8192
	ds_write_b128 v241, v[172:175] offset:12288
	s_nop 3
	s_movk_i32 s96, 0x4000
	v_lshl_add_u64 v[174:175], v[188:189], 0, s[96:97]
	global_load_dwordx4 v[168:171], v[174:175], off offset:-2048
	global_load_dwordx4 v[172:175], v[174:175], off offset:2048
	s_movk_i32 s96, 0x800
	v_lshl_add_u64 v[248:249], v[184:185], 0, s[96:97]
	v_lshl_add_u64 v[250:251], v[186:187], 0, s[96:97]
	global_load_dwordx4 v[144:147], v[248:249], off
	global_load_dwordx4 v[148:151], v[248:249], off offset:256
	global_load_dwordx4 v[152:155], v[250:251], off
	global_load_dwordx4 v[156:159], v[250:251], off offset:256
	s_waitcnt lgkmcnt(0)
	s_barrier
	ds_read_b128 v[196:199], v246 offset:0
	ds_read_b128 v[200:203], v246 offset:1024
	ds_read_b128 v[204:207], v246 offset:2048
	ds_read_b128 v[242:245], v246 offset:3072
.Lg16_gu_k:
	s_add_i32 s8, s1, 3
	s_min_u32 s9, s8, 31
	s_lshl_b32 s96, s9, 13
	v_lshl_add_u64 v[166:167], v[188:189], 0, s[96:97]
	global_load_dwordx4 v[160:163], v[166:167], off offset:-2048
	global_load_dwordx4 v[164:167], v[166:167], off offset:2048
	s_add_i32 s8, s1, 2
	s_min_u32 s9, s8, 31
	s_lshl_b32 s96, s9, 11
	v_lshl_add_u64 v[248:249], v[184:185], 0, s[96:97]
	v_lshl_add_u64 v[250:251], v[186:187], 0, s[96:97]
	s_waitcnt vmcnt(8) lgkmcnt(3)
	v_mfma_f32_16x16x32_bf16 v[112:115], v[128:131], v[196:199], v[112:115]
	v_mfma_f32_16x16x32_bf16 v[120:123], v[132:135], v[196:199], v[120:123]
	v_mfma_f32_16x16x32_bf16 v[80:83], v[136:139], v[196:199], v[80:83]
	v_mfma_f32_16x16x32_bf16 v[88:91], v[140:143], v[196:199], v[88:91]
	ds_read_b128 v[196:199], v246 offset:4096
	s_waitcnt lgkmcnt(3)
	v_mfma_f32_16x16x32_bf16 v[116:119], v[128:131], v[200:203], v[116:119]
	v_mfma_f32_16x16x32_bf16 v[124:127], v[132:135], v[200:203], v[124:127]
	v_mfma_f32_16x16x32_bf16 v[84:87], v[136:139], v[200:203], v[84:87]
	v_mfma_f32_16x16x32_bf16 v[92:95], v[140:143], v[200:203], v[92:95]
	ds_read_b128 v[200:203], v246 offset:5120
	s_waitcnt lgkmcnt(3)
	v_mfma_f32_16x16x32_bf16 v[96:99], v[128:131], v[204:207], v[96:99]
	v_mfma_f32_16x16x32_bf16 v[104:107], v[132:135], v[204:207], v[104:107]
	v_mfma_f32_16x16x32_bf16 v[64:67], v[136:139], v[204:207], v[64:67]
	v_mfma_f32_16x16x32_bf16 v[72:75], v[140:143], v[204:207], v[72:75]
	ds_read_b128 v[204:207], v246 offset:6144
	s_waitcnt lgkmcnt(3)
	v_mfma_f32_16x16x32_bf16 v[100:103], v[128:131], v[242:245], v[100:103]
	v_mfma_f32_16x16x32_bf16 v[108:111], v[132:135], v[242:245], v[108:111]
	v_mfma_f32_16x16x32_bf16 v[68:71], v[136:139], v[242:245], v[68:71]
	v_mfma_f32_16x16x32_bf16 v[76:79], v[140:143], v[242:245], v[76:79]
	ds_read_b128 v[242:245], v246 offset:7168
	s_waitcnt vmcnt(6)
	ds_write_b128 v241, v[168:171] offset:16384
	ds_write_b128 v241, v[172:175] offset:20480
	s_waitcnt lgkmcnt(5)
	v_mfma_f32_16x16x32_bf16 v[48:51], v[128:131], v[196:199], v[48:51]
	v_mfma_f32_16x16x32_bf16 v[56:59], v[132:135], v[196:199], v[56:59]
	v_mfma_f32_16x16x32_bf16 v[16:19], v[136:139], v[196:199], v[16:19]
	v_mfma_f32_16x16x32_bf16 v[24:27], v[140:143], v[196:199], v[24:27]
	ds_read_b128 v[196:199], v246 offset:8192
	s_waitcnt lgkmcnt(5)
	v_mfma_f32_16x16x32_bf16 v[52:55], v[128:131], v[200:203], v[52:55]
	v_mfma_f32_16x16x32_bf16 v[60:63], v[132:135], v[200:203], v[60:63]
	v_mfma_f32_16x16x32_bf16 v[20:23], v[136:139], v[200:203], v[20:23]
	v_mfma_f32_16x16x32_bf16 v[28:31], v[140:143], v[200:203], v[28:31]
	ds_read_b128 v[200:203], v246 offset:9216
	s_waitcnt lgkmcnt(2)
	s_barrier
	v_mfma_f32_16x16x32_bf16 v[32:35], v[128:131], v[204:207], v[32:35]
	v_mfma_f32_16x16x32_bf16 v[40:43], v[132:135], v[204:207], v[40:43]
	v_mfma_f32_16x16x32_bf16 v[0:3], v[136:139], v[204:207], v[0:3]
	v_mfma_f32_16x16x32_bf16 v[8:11], v[140:143], v[204:207], v[8:11]
	ds_read_b128 v[204:207], v246 offset:10240
	v_mfma_f32_16x16x32_bf16 v[36:39], v[128:131], v[242:245], v[36:39]
	v_mfma_f32_16x16x32_bf16 v[44:47], v[132:135], v[242:245], v[44:47]
	v_mfma_f32_16x16x32_bf16 v[4:7], v[136:139], v[242:245], v[4:7]
	v_mfma_f32_16x16x32_bf16 v[12:15], v[140:143], v[242:245], v[12:15]
	ds_read_b128 v[242:245], v246 offset:11264
	global_load_dwordx4 v[128:131], v[248:249], off
	global_load_dwordx4 v[132:135], v[248:249], off offset:256
	global_load_dwordx4 v[136:139], v[250:251], off
	global_load_dwordx4 v[140:143], v[250:251], off offset:256
	s_add_i32 s8, s1, 4
	s_min_u32 s9, s8, 31
	s_lshl_b32 s96, s9, 13
	v_lshl_add_u64 v[174:175], v[188:189], 0, s[96:97]
	global_load_dwordx4 v[168:171], v[174:175], off offset:-2048
	global_load_dwordx4 v[172:175], v[174:175], off offset:2048
	s_add_i32 s8, s1, 3
	s_min_u32 s9, s8, 31
	s_lshl_b32 s96, s9, 11
	v_lshl_add_u64 v[248:249], v[184:185], 0, s[96:97]
	v_lshl_add_u64 v[250:251], v[186:187], 0, s[96:97]
	s_waitcnt vmcnt(8) lgkmcnt(3)
	v_mfma_f32_16x16x32_bf16 v[112:115], v[144:147], v[196:199], v[112:115]
	v_mfma_f32_16x16x32_bf16 v[120:123], v[148:151], v[196:199], v[120:123]
	v_mfma_f32_16x16x32_bf16 v[80:83], v[152:155], v[196:199], v[80:83]
	v_mfma_f32_16x16x32_bf16 v[88:91], v[156:159], v[196:199], v[88:91]
	ds_read_b128 v[196:199], v246 offset:12288
	s_waitcnt lgkmcnt(3)
	v_mfma_f32_16x16x32_bf16 v[116:119], v[144:147], v[200:203], v[116:119]
	v_mfma_f32_16x16x32_bf16 v[124:127], v[148:151], v[200:203], v[124:127]
	v_mfma_f32_16x16x32_bf16 v[84:87], v[152:155], v[200:203], v[84:87]
	v_mfma_f32_16x16x32_bf16 v[92:95], v[156:159], v[200:203], v[92:95]
	ds_read_b128 v[200:203], v246 offset:13312
	s_waitcnt lgkmcnt(3)
	v_mfma_f32_16x16x32_bf16 v[96:99], v[144:147], v[204:207], v[96:99]
	v_mfma_f32_16x16x32_bf16 v[104:107], v[148:151], v[204:207], v[104:107]
	v_mfma_f32_16x16x32_bf16 v[64:67], v[152:155], v[204:207], v[64:67]
	v_mfma_f32_16x16x32_bf16 v[72:75], v[156:159], v[204:207], v[72:75]
	ds_read_b128 v[204:207], v246 offset:14336
	s_waitcnt lgkmcnt(3)
	v_mfma_f32_16x16x32_bf16 v[100:103], v[144:147], v[242:245], v[100:103]
	v_mfma_f32_16x16x32_bf16 v[108:111], v[148:151], v[242:245], v[108:111]
	v_mfma_f32_16x16x32_bf16 v[68:71], v[152:155], v[242:245], v[68:71]
	v_mfma_f32_16x16x32_bf16 v[76:79], v[156:159], v[242:245], v[76:79]
	ds_read_b128 v[242:245], v246 offset:15360
	s_waitcnt vmcnt(6)
	ds_write_b128 v241, v[160:163] offset:0
	ds_write_b128 v241, v[164:167] offset:4096
	s_waitcnt lgkmcnt(5)
	v_mfma_f32_16x16x32_bf16 v[48:51], v[144:147], v[196:199], v[48:51]
	v_mfma_f32_16x16x32_bf16 v[56:59], v[148:151], v[196:199], v[56:59]
	v_mfma_f32_16x16x32_bf16 v[16:19], v[152:155], v[196:199], v[16:19]
	v_mfma_f32_16x16x32_bf16 v[24:27], v[156:159], v[196:199], v[24:27]
	ds_read_b128 v[196:199], v246 offset:16384
	s_waitcnt lgkmcnt(5)
	v_mfma_f32_16x16x32_bf16 v[52:55], v[144:147], v[200:203], v[52:55]
	v_mfma_f32_16x16x32_bf16 v[60:63], v[148:151], v[200:203], v[60:63]
	v_mfma_f32_16x16x32_bf16 v[20:23], v[152:155], v[200:203], v[20:23]
	v_mfma_f32_16x16x32_bf16 v[28:31], v[156:159], v[200:203], v[28:31]
	ds_read_b128 v[200:203], v246 offset:17408
	s_waitcnt lgkmcnt(2)
	s_barrier
	v_mfma_f32_16x16x32_bf16 v[32:35], v[144:147], v[204:207], v[32:35]
	v_mfma_f32_16x16x32_bf16 v[40:43], v[148:151], v[204:207], v[40:43]
	v_mfma_f32_16x16x32_bf16 v[0:3], v[152:155], v[204:207], v[0:3]
	v_mfma_f32_16x16x32_bf16 v[8:11], v[156:159], v[204:207], v[8:11]
	ds_read_b128 v[204:207], v246 offset:18432
	v_mfma_f32_16x16x32_bf16 v[36:39], v[144:147], v[242:245], v[36:39]
	v_mfma_f32_16x16x32_bf16 v[44:47], v[148:151], v[242:245], v[44:47]
	v_mfma_f32_16x16x32_bf16 v[4:7], v[152:155], v[242:245], v[4:7]
	v_mfma_f32_16x16x32_bf16 v[12:15], v[156:159], v[242:245], v[12:15]
	ds_read_b128 v[242:245], v246 offset:19456
	global_load_dwordx4 v[144:147], v[248:249], off
	global_load_dwordx4 v[148:151], v[248:249], off offset:256
	global_load_dwordx4 v[152:155], v[250:251], off
	global_load_dwordx4 v[156:159], v[250:251], off offset:256
	s_add_i32 s8, s1, 5
	s_min_u32 s9, s8, 31
	s_lshl_b32 s96, s9, 13
	v_lshl_add_u64 v[166:167], v[188:189], 0, s[96:97]
	global_load_dwordx4 v[160:163], v[166:167], off offset:-2048
	global_load_dwordx4 v[164:167], v[166:167], off offset:2048
	s_add_i32 s8, s1, 4
	s_min_u32 s9, s8, 31
	s_lshl_b32 s96, s9, 11
	v_lshl_add_u64 v[248:249], v[184:185], 0, s[96:97]
	v_lshl_add_u64 v[250:251], v[186:187], 0, s[96:97]
	s_waitcnt vmcnt(8) lgkmcnt(3)
	v_mfma_f32_16x16x32_bf16 v[112:115], v[128:131], v[196:199], v[112:115]
	v_mfma_f32_16x16x32_bf16 v[120:123], v[132:135], v[196:199], v[120:123]
	v_mfma_f32_16x16x32_bf16 v[80:83], v[136:139], v[196:199], v[80:83]
	v_mfma_f32_16x16x32_bf16 v[88:91], v[140:143], v[196:199], v[88:91]
	ds_read_b128 v[196:199], v246 offset:20480
	s_waitcnt lgkmcnt(3)
	v_mfma_f32_16x16x32_bf16 v[116:119], v[128:131], v[200:203], v[116:119]
	v_mfma_f32_16x16x32_bf16 v[124:127], v[132:135], v[200:203], v[124:127]
	v_mfma_f32_16x16x32_bf16 v[84:87], v[136:139], v[200:203], v[84:87]
	v_mfma_f32_16x16x32_bf16 v[92:95], v[140:143], v[200:203], v[92:95]
	ds_read_b128 v[200:203], v246 offset:21504
	s_waitcnt lgkmcnt(3)
	v_mfma_f32_16x16x32_bf16 v[96:99], v[128:131], v[204:207], v[96:99]
	v_mfma_f32_16x16x32_bf16 v[104:107], v[132:135], v[204:207], v[104:107]
	v_mfma_f32_16x16x32_bf16 v[64:67], v[136:139], v[204:207], v[64:67]
	v_mfma_f32_16x16x32_bf16 v[72:75], v[140:143], v[204:207], v[72:75]
	ds_read_b128 v[204:207], v246 offset:22528
	s_waitcnt lgkmcnt(3)
	v_mfma_f32_16x16x32_bf16 v[100:103], v[128:131], v[242:245], v[100:103]
	v_mfma_f32_16x16x32_bf16 v[108:111], v[132:135], v[242:245], v[108:111]
	v_mfma_f32_16x16x32_bf16 v[68:71], v[136:139], v[242:245], v[68:71]
	v_mfma_f32_16x16x32_bf16 v[76:79], v[140:143], v[242:245], v[76:79]
	ds_read_b128 v[242:245], v246 offset:23552
	s_waitcnt vmcnt(6)
	ds_write_b128 v241, v[168:171] offset:8192
	ds_write_b128 v241, v[172:175] offset:12288
	s_waitcnt lgkmcnt(5)
	v_mfma_f32_16x16x32_bf16 v[48:51], v[128:131], v[196:199], v[48:51]
	v_mfma_f32_16x16x32_bf16 v[56:59], v[132:135], v[196:199], v[56:59]
	v_mfma_f32_16x16x32_bf16 v[16:19], v[136:139], v[196:199], v[16:19]
	v_mfma_f32_16x16x32_bf16 v[24:27], v[140:143], v[196:199], v[24:27]
	ds_read_b128 v[196:199], v246 offset:0
	s_waitcnt lgkmcnt(5)
	v_mfma_f32_16x16x32_bf16 v[52:55], v[128:131], v[200:203], v[52:55]
	v_mfma_f32_16x16x32_bf16 v[60:63], v[132:135], v[200:203], v[60:63]
	v_mfma_f32_16x16x32_bf16 v[20:23], v[136:139], v[200:203], v[20:23]
	v_mfma_f32_16x16x32_bf16 v[28:31], v[140:143], v[200:203], v[28:31]
	ds_read_b128 v[200:203], v246 offset:1024
	s_waitcnt lgkmcnt(2)
	s_barrier
	v_mfma_f32_16x16x32_bf16 v[32:35], v[128:131], v[204:207], v[32:35]
	v_mfma_f32_16x16x32_bf16 v[40:43], v[132:135], v[204:207], v[40:43]
	v_mfma_f32_16x16x32_bf16 v[0:3], v[136:139], v[204:207], v[0:3]
	v_mfma_f32_16x16x32_bf16 v[8:11], v[140:143], v[204:207], v[8:11]
	ds_read_b128 v[204:207], v246 offset:2048
	v_mfma_f32_16x16x32_bf16 v[36:39], v[128:131], v[242:245], v[36:39]
	v_mfma_f32_16x16x32_bf16 v[44:47], v[132:135], v[242:245], v[44:47]
	v_mfma_f32_16x16x32_bf16 v[4:7], v[136:139], v[242:245], v[4:7]
	v_mfma_f32_16x16x32_bf16 v[12:15], v[140:143], v[242:245], v[12:15]
	ds_read_b128 v[242:245], v246 offset:3072
	global_load_dwordx4 v[128:131], v[248:249], off
	global_load_dwordx4 v[132:135], v[248:249], off offset:256
	global_load_dwordx4 v[136:139], v[250:251], off
	global_load_dwordx4 v[140:143], v[250:251], off offset:256
	s_add_i32 s8, s1, 6
	s_min_u32 s9, s8, 31
	s_lshl_b32 s96, s9, 13
	v_lshl_add_u64 v[174:175], v[188:189], 0, s[96:97]
	global_load_dwordx4 v[168:171], v[174:175], off offset:-2048
	global_load_dwordx4 v[172:175], v[174:175], off offset:2048
	s_add_i32 s8, s1, 5
	s_min_u32 s9, s8, 31
	s_lshl_b32 s96, s9, 11
	v_lshl_add_u64 v[248:249], v[184:185], 0, s[96:97]
	v_lshl_add_u64 v[250:251], v[186:187], 0, s[96:97]
	s_waitcnt vmcnt(8) lgkmcnt(3)
	v_mfma_f32_16x16x32_bf16 v[112:115], v[144:147], v[196:199], v[112:115]
	v_mfma_f32_16x16x32_bf16 v[120:123], v[148:151], v[196:199], v[120:123]
	v_mfma_f32_16x16x32_bf16 v[80:83], v[152:155], v[196:199], v[80:83]
	v_mfma_f32_16x16x32_bf16 v[88:91], v[156:159], v[196:199], v[88:91]
	ds_read_b128 v[196:199], v246 offset:4096
	s_waitcnt lgkmcnt(3)
	v_mfma_f32_16x16x32_bf16 v[116:119], v[144:147], v[200:203], v[116:119]
	v_mfma_f32_16x16x32_bf16 v[124:127], v[148:151], v[200:203], v[124:127]
	v_mfma_f32_16x16x32_bf16 v[84:87], v[152:155], v[200:203], v[84:87]
	v_mfma_f32_16x16x32_bf16 v[92:95], v[156:159], v[200:203], v[92:95]
	ds_read_b128 v[200:203], v246 offset:5120
	s_waitcnt lgkmcnt(3)
	v_mfma_f32_16x16x32_bf16 v[96:99], v[144:147], v[204:207], v[96:99]
	v_mfma_f32_16x16x32_bf16 v[104:107], v[148:151], v[204:207], v[104:107]
	v_mfma_f32_16x16x32_bf16 v[64:67], v[152:155], v[204:207], v[64:67]
	v_mfma_f32_16x16x32_bf16 v[72:75], v[156:159], v[204:207], v[72:75]
	ds_read_b128 v[204:207], v246 offset:6144
	s_waitcnt lgkmcnt(3)
	v_mfma_f32_16x16x32_bf16 v[100:103], v[144:147], v[242:245], v[100:103]
	v_mfma_f32_16x16x32_bf16 v[108:111], v[148:151], v[242:245], v[108:111]
	v_mfma_f32_16x16x32_bf16 v[68:71], v[152:155], v[242:245], v[68:71]
	v_mfma_f32_16x16x32_bf16 v[76:79], v[156:159], v[242:245], v[76:79]
	ds_read_b128 v[242:245], v246 offset:7168
	s_waitcnt vmcnt(6)
	ds_write_b128 v241, v[160:163] offset:16384
	ds_write_b128 v241, v[164:167] offset:20480
	s_waitcnt lgkmcnt(5)
	v_mfma_f32_16x16x32_bf16 v[48:51], v[144:147], v[196:199], v[48:51]
	v_mfma_f32_16x16x32_bf16 v[56:59], v[148:151], v[196:199], v[56:59]
	v_mfma_f32_16x16x32_bf16 v[16:19], v[152:155], v[196:199], v[16:19]
	v_mfma_f32_16x16x32_bf16 v[24:27], v[156:159], v[196:199], v[24:27]
	ds_read_b128 v[196:199], v246 offset:8192
	s_waitcnt lgkmcnt(5)
	v_mfma_f32_16x16x32_bf16 v[52:55], v[144:147], v[200:203], v[52:55]
	v_mfma_f32_16x16x32_bf16 v[60:63], v[148:151], v[200:203], v[60:63]
	v_mfma_f32_16x16x32_bf16 v[20:23], v[152:155], v[200:203], v[20:23]
	v_mfma_f32_16x16x32_bf16 v[28:31], v[156:159], v[200:203], v[28:31]
	ds_read_b128 v[200:203], v246 offset:9216
	s_waitcnt lgkmcnt(2)
	s_barrier
	v_mfma_f32_16x16x32_bf16 v[32:35], v[144:147], v[204:207], v[32:35]
	v_mfma_f32_16x16x32_bf16 v[40:43], v[148:151], v[204:207], v[40:43]
	v_mfma_f32_16x16x32_bf16 v[0:3], v[152:155], v[204:207], v[0:3]
	v_mfma_f32_16x16x32_bf16 v[8:11], v[156:159], v[204:207], v[8:11]
	ds_read_b128 v[204:207], v246 offset:10240
	v_mfma_f32_16x16x32_bf16 v[36:39], v[144:147], v[242:245], v[36:39]
	v_mfma_f32_16x16x32_bf16 v[44:47], v[148:151], v[242:245], v[44:47]
	v_mfma_f32_16x16x32_bf16 v[4:7], v[152:155], v[242:245], v[4:7]
	v_mfma_f32_16x16x32_bf16 v[12:15], v[156:159], v[242:245], v[12:15]
	ds_read_b128 v[242:245], v246 offset:11264
	global_load_dwordx4 v[144:147], v[248:249], off
	global_load_dwordx4 v[148:151], v[248:249], off offset:256
	global_load_dwordx4 v[152:155], v[250:251], off
	global_load_dwordx4 v[156:159], v[250:251], off offset:256
	s_add_i32 s8, s1, 7
	s_min_u32 s9, s8, 31
	s_lshl_b32 s96, s9, 13
	v_lshl_add_u64 v[166:167], v[188:189], 0, s[96:97]
	global_load_dwordx4 v[160:163], v[166:167], off offset:-2048
	global_load_dwordx4 v[164:167], v[166:167], off offset:2048
	s_add_i32 s8, s1, 6
	s_min_u32 s9, s8, 31
	s_lshl_b32 s96, s9, 11
	v_lshl_add_u64 v[248:249], v[184:185], 0, s[96:97]
	v_lshl_add_u64 v[250:251], v[186:187], 0, s[96:97]
	s_waitcnt vmcnt(8) lgkmcnt(3)
	v_mfma_f32_16x16x32_bf16 v[112:115], v[128:131], v[196:199], v[112:115]
	v_mfma_f32_16x16x32_bf16 v[120:123], v[132:135], v[196:199], v[120:123]
	v_mfma_f32_16x16x32_bf16 v[80:83], v[136:139], v[196:199], v[80:83]
	v_mfma_f32_16x16x32_bf16 v[88:91], v[140:143], v[196:199], v[88:91]
	ds_read_b128 v[196:199], v246 offset:12288
	s_waitcnt lgkmcnt(3)
	v_mfma_f32_16x16x32_bf16 v[116:119], v[128:131], v[200:203], v[116:119]
	v_mfma_f32_16x16x32_bf16 v[124:127], v[132:135], v[200:203], v[124:127]
	v_mfma_f32_16x16x32_bf16 v[84:87], v[136:139], v[200:203], v[84:87]
	v_mfma_f32_16x16x32_bf16 v[92:95], v[140:143], v[200:203], v[92:95]
	ds_read_b128 v[200:203], v246 offset:13312
	s_waitcnt lgkmcnt(3)
	v_mfma_f32_16x16x32_bf16 v[96:99], v[128:131], v[204:207], v[96:99]
	v_mfma_f32_16x16x32_bf16 v[104:107], v[132:135], v[204:207], v[104:107]
	v_mfma_f32_16x16x32_bf16 v[64:67], v[136:139], v[204:207], v[64:67]
	v_mfma_f32_16x16x32_bf16 v[72:75], v[140:143], v[204:207], v[72:75]
	ds_read_b128 v[204:207], v246 offset:14336
	s_waitcnt lgkmcnt(3)
	v_mfma_f32_16x16x32_bf16 v[100:103], v[128:131], v[242:245], v[100:103]
	v_mfma_f32_16x16x32_bf16 v[108:111], v[132:135], v[242:245], v[108:111]
	v_mfma_f32_16x16x32_bf16 v[68:71], v[136:139], v[242:245], v[68:71]
	v_mfma_f32_16x16x32_bf16 v[76:79], v[140:143], v[242:245], v[76:79]
	ds_read_b128 v[242:245], v246 offset:15360
	s_waitcnt vmcnt(6)
	ds_write_b128 v241, v[168:171] offset:0
	ds_write_b128 v241, v[172:175] offset:4096
	s_waitcnt lgkmcnt(5)
	v_mfma_f32_16x16x32_bf16 v[48:51], v[128:131], v[196:199], v[48:51]
	v_mfma_f32_16x16x32_bf16 v[56:59], v[132:135], v[196:199], v[56:59]
	v_mfma_f32_16x16x32_bf16 v[16:19], v[136:139], v[196:199], v[16:19]
	v_mfma_f32_16x16x32_bf16 v[24:27], v[140:143], v[196:199], v[24:27]
	ds_read_b128 v[196:199], v246 offset:16384
	s_waitcnt lgkmcnt(5)
	v_mfma_f32_16x16x32_bf16 v[52:55], v[128:131], v[200:203], v[52:55]
	v_mfma_f32_16x16x32_bf16 v[60:63], v[132:135], v[200:203], v[60:63]
	v_mfma_f32_16x16x32_bf16 v[20:23], v[136:139], v[200:203], v[20:23]
	v_mfma_f32_16x16x32_bf16 v[28:31], v[140:143], v[200:203], v[28:31]
	ds_read_b128 v[200:203], v246 offset:17408
	s_waitcnt lgkmcnt(2)
	s_barrier
	v_mfma_f32_16x16x32_bf16 v[32:35], v[128:131], v[204:207], v[32:35]
	v_mfma_f32_16x16x32_bf16 v[40:43], v[132:135], v[204:207], v[40:43]
	v_mfma_f32_16x16x32_bf16 v[0:3], v[136:139], v[204:207], v[0:3]
	v_mfma_f32_16x16x32_bf16 v[8:11], v[140:143], v[204:207], v[8:11]
	ds_read_b128 v[204:207], v246 offset:18432
	v_mfma_f32_16x16x32_bf16 v[36:39], v[128:131], v[242:245], v[36:39]
	v_mfma_f32_16x16x32_bf16 v[44:47], v[132:135], v[242:245], v[44:47]
	v_mfma_f32_16x16x32_bf16 v[4:7], v[136:139], v[242:245], v[4:7]
	v_mfma_f32_16x16x32_bf16 v[12:15], v[140:143], v[242:245], v[12:15]
	ds_read_b128 v[242:245], v246 offset:19456
	global_load_dwordx4 v[128:131], v[248:249], off
	global_load_dwordx4 v[132:135], v[248:249], off offset:256
	global_load_dwordx4 v[136:139], v[250:251], off
	global_load_dwordx4 v[140:143], v[250:251], off offset:256
	s_add_i32 s8, s1, 8
	s_min_u32 s9, s8, 31
	s_lshl_b32 s96, s9, 13
	v_lshl_add_u64 v[174:175], v[188:189], 0, s[96:97]
	global_load_dwordx4 v[168:171], v[174:175], off offset:-2048
	global_load_dwordx4 v[172:175], v[174:175], off offset:2048
	s_add_i32 s8, s1, 7
	s_min_u32 s9, s8, 31
	s_lshl_b32 s96, s9, 11
	v_lshl_add_u64 v[248:249], v[184:185], 0, s[96:97]
	v_lshl_add_u64 v[250:251], v[186:187], 0, s[96:97]
	s_waitcnt vmcnt(8) lgkmcnt(3)
	v_mfma_f32_16x16x32_bf16 v[112:115], v[144:147], v[196:199], v[112:115]
	v_mfma_f32_16x16x32_bf16 v[120:123], v[148:151], v[196:199], v[120:123]
	v_mfma_f32_16x16x32_bf16 v[80:83], v[152:155], v[196:199], v[80:83]
	v_mfma_f32_16x16x32_bf16 v[88:91], v[156:159], v[196:199], v[88:91]
	ds_read_b128 v[196:199], v246 offset:20480
	s_waitcnt lgkmcnt(3)
	v_mfma_f32_16x16x32_bf16 v[116:119], v[144:147], v[200:203], v[116:119]
	v_mfma_f32_16x16x32_bf16 v[124:127], v[148:151], v[200:203], v[124:127]
	v_mfma_f32_16x16x32_bf16 v[84:87], v[152:155], v[200:203], v[84:87]
	v_mfma_f32_16x16x32_bf16 v[92:95], v[156:159], v[200:203], v[92:95]
	ds_read_b128 v[200:203], v246 offset:21504
	s_waitcnt lgkmcnt(3)
	v_mfma_f32_16x16x32_bf16 v[96:99], v[144:147], v[204:207], v[96:99]
	v_mfma_f32_16x16x32_bf16 v[104:107], v[148:151], v[204:207], v[104:107]
	v_mfma_f32_16x16x32_bf16 v[64:67], v[152:155], v[204:207], v[64:67]
	v_mfma_f32_16x16x32_bf16 v[72:75], v[156:159], v[204:207], v[72:75]
	ds_read_b128 v[204:207], v246 offset:22528
	s_waitcnt lgkmcnt(3)
	v_mfma_f32_16x16x32_bf16 v[100:103], v[144:147], v[242:245], v[100:103]
	v_mfma_f32_16x16x32_bf16 v[108:111], v[148:151], v[242:245], v[108:111]
	v_mfma_f32_16x16x32_bf16 v[68:71], v[152:155], v[242:245], v[68:71]
	v_mfma_f32_16x16x32_bf16 v[76:79], v[156:159], v[242:245], v[76:79]
	ds_read_b128 v[242:245], v246 offset:23552
	s_waitcnt vmcnt(6)
	ds_write_b128 v241, v[160:163] offset:8192
	ds_write_b128 v241, v[164:167] offset:12288
	s_waitcnt lgkmcnt(5)
	v_mfma_f32_16x16x32_bf16 v[48:51], v[144:147], v[196:199], v[48:51]
	v_mfma_f32_16x16x32_bf16 v[56:59], v[148:151], v[196:199], v[56:59]
	v_mfma_f32_16x16x32_bf16 v[16:19], v[152:155], v[196:199], v[16:19]
	v_mfma_f32_16x16x32_bf16 v[24:27], v[156:159], v[196:199], v[24:27]
	ds_read_b128 v[196:199], v246 offset:0
	s_waitcnt lgkmcnt(5)
	v_mfma_f32_16x16x32_bf16 v[52:55], v[144:147], v[200:203], v[52:55]
	v_mfma_f32_16x16x32_bf16 v[60:63], v[148:151], v[200:203], v[60:63]
	v_mfma_f32_16x16x32_bf16 v[20:23], v[152:155], v[200:203], v[20:23]
	v_mfma_f32_16x16x32_bf16 v[28:31], v[156:159], v[200:203], v[28:31]
	ds_read_b128 v[200:203], v246 offset:1024
	s_waitcnt lgkmcnt(2)
	s_barrier
	v_mfma_f32_16x16x32_bf16 v[32:35], v[144:147], v[204:207], v[32:35]
	v_mfma_f32_16x16x32_bf16 v[40:43], v[148:151], v[204:207], v[40:43]
	v_mfma_f32_16x16x32_bf16 v[0:3], v[152:155], v[204:207], v[0:3]
	v_mfma_f32_16x16x32_bf16 v[8:11], v[156:159], v[204:207], v[8:11]
	ds_read_b128 v[204:207], v246 offset:2048
	v_mfma_f32_16x16x32_bf16 v[36:39], v[144:147], v[242:245], v[36:39]
	v_mfma_f32_16x16x32_bf16 v[44:47], v[148:151], v[242:245], v[44:47]
	v_mfma_f32_16x16x32_bf16 v[4:7], v[152:155], v[242:245], v[4:7]
	v_mfma_f32_16x16x32_bf16 v[12:15], v[156:159], v[242:245], v[12:15]
	ds_read_b128 v[242:245], v246 offset:3072
	global_load_dwordx4 v[144:147], v[248:249], off
	global_load_dwordx4 v[148:151], v[248:249], off offset:256
	global_load_dwordx4 v[152:155], v[250:251], off
	global_load_dwordx4 v[156:159], v[250:251], off offset:256
	s_add_i32 s1, s1, 6
	s_cmp_lt_u32 s1, 30
	s_cbranch_scc1 .Lg16_gu_k
	s_add_i32 s8, s1, 3
	s_min_u32 s9, s8, 31
	s_lshl_b32 s96, s9, 13
	v_lshl_add_u64 v[166:167], v[188:189], 0, s[96:97]
	global_load_dwordx4 v[160:163], v[166:167], off offset:-2048
	global_load_dwordx4 v[164:167], v[166:167], off offset:2048
	s_add_i32 s8, s1, 2
	s_min_u32 s9, s8, 31
	s_lshl_b32 s96, s9, 11
	v_lshl_add_u64 v[248:249], v[184:185], 0, s[96:97]
	v_lshl_add_u64 v[250:251], v[186:187], 0, s[96:97]
	s_waitcnt vmcnt(8) lgkmcnt(3)
	v_mfma_f32_16x16x32_bf16 v[112:115], v[128:131], v[196:199], v[112:115]
	v_mfma_f32_16x16x32_bf16 v[120:123], v[132:135], v[196:199], v[120:123]
	v_mfma_f32_16x16x32_bf16 v[80:83], v[136:139], v[196:199], v[80:83]
	v_mfma_f32_16x16x32_bf16 v[88:91], v[140:143], v[196:199], v[88:91]
	ds_read_b128 v[196:199], v246 offset:4096
	s_waitcnt lgkmcnt(3)
	v_mfma_f32_16x16x32_bf16 v[116:119], v[128:131], v[200:203], v[116:119]
	v_mfma_f32_16x16x32_bf16 v[124:127], v[132:135], v[200:203], v[124:127]
	v_mfma_f32_16x16x32_bf16 v[84:87], v[136:139], v[200:203], v[84:87]
	v_mfma_f32_16x16x32_bf16 v[92:95], v[140:143], v[200:203], v[92:95]
	ds_read_b128 v[200:203], v246 offset:5120
	s_waitcnt lgkmcnt(3)
	v_mfma_f32_16x16x32_bf16 v[96:99], v[128:131], v[204:207], v[96:99]
	v_mfma_f32_16x16x32_bf16 v[104:107], v[132:135], v[204:207], v[104:107]
	v_mfma_f32_16x16x32_bf16 v[64:67], v[136:139], v[204:207], v[64:67]
	v_mfma_f32_16x16x32_bf16 v[72:75], v[140:143], v[204:207], v[72:75]
	ds_read_b128 v[204:207], v246 offset:6144
	s_waitcnt lgkmcnt(3)
	v_mfma_f32_16x16x32_bf16 v[100:103], v[128:131], v[242:245], v[100:103]
	v_mfma_f32_16x16x32_bf16 v[108:111], v[132:135], v[242:245], v[108:111]
	v_mfma_f32_16x16x32_bf16 v[68:71], v[136:139], v[242:245], v[68:71]
	v_mfma_f32_16x16x32_bf16 v[76:79], v[140:143], v[242:245], v[76:79]
	ds_read_b128 v[242:245], v246 offset:7168
	s_waitcnt vmcnt(6)
	ds_write_b128 v241, v[168:171] offset:16384
	ds_write_b128 v241, v[172:175] offset:20480
	s_waitcnt lgkmcnt(5)
	v_mfma_f32_16x16x32_bf16 v[48:51], v[128:131], v[196:199], v[48:51]
	v_mfma_f32_16x16x32_bf16 v[56:59], v[132:135], v[196:199], v[56:59]
	v_mfma_f32_16x16x32_bf16 v[16:19], v[136:139], v[196:199], v[16:19]
	v_mfma_f32_16x16x32_bf16 v[24:27], v[140:143], v[196:199], v[24:27]
	ds_read_b128 v[196:199], v246 offset:8192
	s_waitcnt lgkmcnt(5)
	v_mfma_f32_16x16x32_bf16 v[52:55], v[128:131], v[200:203], v[52:55]
	v_mfma_f32_16x16x32_bf16 v[60:63], v[132:135], v[200:203], v[60:63]
	v_mfma_f32_16x16x32_bf16 v[20:23], v[136:139], v[200:203], v[20:23]
	v_mfma_f32_16x16x32_bf16 v[28:31], v[140:143], v[200:203], v[28:31]
	ds_read_b128 v[200:203], v246 offset:9216
	s_waitcnt lgkmcnt(2)
	s_barrier
	v_mfma_f32_16x16x32_bf16 v[32:35], v[128:131], v[204:207], v[32:35]
	v_mfma_f32_16x16x32_bf16 v[40:43], v[132:135], v[204:207], v[40:43]
	v_mfma_f32_16x16x32_bf16 v[0:3], v[136:139], v[204:207], v[0:3]
	v_mfma_f32_16x16x32_bf16 v[8:11], v[140:143], v[204:207], v[8:11]
	ds_read_b128 v[204:207], v246 offset:10240
	v_mfma_f32_16x16x32_bf16 v[36:39], v[128:131], v[242:245], v[36:39]
	v_mfma_f32_16x16x32_bf16 v[44:47], v[132:135], v[242:245], v[44:47]
	v_mfma_f32_16x16x32_bf16 v[4:7], v[136:139], v[242:245], v[4:7]
	v_mfma_f32_16x16x32_bf16 v[12:15], v[140:143], v[242:245], v[12:15]
	ds_read_b128 v[242:245], v246 offset:11264
	global_load_dwordx4 v[128:131], v[248:249], off
	global_load_dwordx4 v[132:135], v[248:249], off offset:256
	global_load_dwordx4 v[136:139], v[250:251], off
	global_load_dwordx4 v[140:143], v[250:251], off offset:256
	s_add_i32 s8, s1, 4
	s_min_u32 s9, s8, 31
	s_lshl_b32 s96, s9, 13
	v_lshl_add_u64 v[174:175], v[188:189], 0, s[96:97]
	global_load_dwordx4 v[168:171], v[174:175], off offset:-2048
	global_load_dwordx4 v[172:175], v[174:175], off offset:2048
	s_add_i32 s8, s1, 3
	s_min_u32 s9, s8, 31
	s_lshl_b32 s96, s9, 11
	v_lshl_add_u64 v[248:249], v[184:185], 0, s[96:97]
	v_lshl_add_u64 v[250:251], v[186:187], 0, s[96:97]
	s_waitcnt vmcnt(8) lgkmcnt(3)
	v_mfma_f32_16x16x32_bf16 v[112:115], v[144:147], v[196:199], v[112:115]
	v_mfma_f32_16x16x32_bf16 v[120:123], v[148:151], v[196:199], v[120:123]
	v_mfma_f32_16x16x32_bf16 v[80:83], v[152:155], v[196:199], v[80:83]
	v_mfma_f32_16x16x32_bf16 v[88:91], v[156:159], v[196:199], v[88:91]
	ds_read_b128 v[196:199], v246 offset:12288
	s_waitcnt lgkmcnt(3)
	v_mfma_f32_16x16x32_bf16 v[116:119], v[144:147], v[200:203], v[116:119]
	v_mfma_f32_16x16x32_bf16 v[124:127], v[148:151], v[200:203], v[124:127]
	v_mfma_f32_16x16x32_bf16 v[84:87], v[152:155], v[200:203], v[84:87]
	v_mfma_f32_16x16x32_bf16 v[92:95], v[156:159], v[200:203], v[92:95]
	ds_read_b128 v[200:203], v246 offset:13312
	s_waitcnt lgkmcnt(3)
	v_mfma_f32_16x16x32_bf16 v[96:99], v[144:147], v[204:207], v[96:99]
	v_mfma_f32_16x16x32_bf16 v[104:107], v[148:151], v[204:207], v[104:107]
	v_mfma_f32_16x16x32_bf16 v[64:67], v[152:155], v[204:207], v[64:67]
	v_mfma_f32_16x16x32_bf16 v[72:75], v[156:159], v[204:207], v[72:75]
	ds_read_b128 v[204:207], v246 offset:14336
	s_waitcnt lgkmcnt(3)
	v_mfma_f32_16x16x32_bf16 v[100:103], v[144:147], v[242:245], v[100:103]
	v_mfma_f32_16x16x32_bf16 v[108:111], v[148:151], v[242:245], v[108:111]
	v_mfma_f32_16x16x32_bf16 v[68:71], v[152:155], v[242:245], v[68:71]
	v_mfma_f32_16x16x32_bf16 v[76:79], v[156:159], v[242:245], v[76:79]
	ds_read_b128 v[242:245], v246 offset:15360
	s_waitcnt vmcnt(6)
	ds_write_b128 v241, v[160:163] offset:0
	ds_write_b128 v241, v[164:167] offset:4096
	s_waitcnt lgkmcnt(5)
	v_mfma_f32_16x16x32_bf16 v[48:51], v[144:147], v[196:199], v[48:51]
	v_mfma_f32_16x16x32_bf16 v[56:59], v[148:151], v[196:199], v[56:59]
	v_mfma_f32_16x16x32_bf16 v[16:19], v[152:155], v[196:199], v[16:19]
	v_mfma_f32_16x16x32_bf16 v[24:27], v[156:159], v[196:199], v[24:27]
	ds_read_b128 v[196:199], v246 offset:16384
	s_waitcnt lgkmcnt(5)
	v_mfma_f32_16x16x32_bf16 v[52:55], v[144:147], v[200:203], v[52:55]
	v_mfma_f32_16x16x32_bf16 v[60:63], v[148:151], v[200:203], v[60:63]
	v_mfma_f32_16x16x32_bf16 v[20:23], v[152:155], v[200:203], v[20:23]
	v_mfma_f32_16x16x32_bf16 v[28:31], v[156:159], v[200:203], v[28:31]
	ds_read_b128 v[200:203], v246 offset:17408
	s_waitcnt lgkmcnt(2)
	s_barrier
	v_mfma_f32_16x16x32_bf16 v[32:35], v[144:147], v[204:207], v[32:35]
	v_mfma_f32_16x16x32_bf16 v[40:43], v[148:151], v[204:207], v[40:43]
	v_mfma_f32_16x16x32_bf16 v[0:3], v[152:155], v[204:207], v[0:3]
	v_mfma_f32_16x16x32_bf16 v[8:11], v[156:159], v[204:207], v[8:11]
	ds_read_b128 v[204:207], v246 offset:18432
	v_mfma_f32_16x16x32_bf16 v[36:39], v[144:147], v[242:245], v[36:39]
	v_mfma_f32_16x16x32_bf16 v[44:47], v[148:151], v[242:245], v[44:47]
	v_mfma_f32_16x16x32_bf16 v[4:7], v[152:155], v[242:245], v[4:7]
	v_mfma_f32_16x16x32_bf16 v[12:15], v[156:159], v[242:245], v[12:15]
	ds_read_b128 v[242:245], v246 offset:19456
	global_load_dwordx4 v[144:147], v[248:249], off
	global_load_dwordx4 v[148:151], v[248:249], off offset:256
	global_load_dwordx4 v[152:155], v[250:251], off
	global_load_dwordx4 v[156:159], v[250:251], off offset:256
	s_waitcnt lgkmcnt(0)
	s_nop 7
	v_permlane16_swap_b32_e32 v112, v116
	v_permlane16_swap_b32_e32 v113, v117
	v_permlane16_swap_b32_e32 v114, v118
	v_permlane16_swap_b32_e32 v115, v119
	v_permlane16_swap_b32_e32 v120, v124
	v_permlane16_swap_b32_e32 v121, v125
	v_permlane16_swap_b32_e32 v122, v126
	v_permlane16_swap_b32_e32 v123, v127
	v_permlane16_swap_b32_e32 v96, v100
	v_permlane16_swap_b32_e32 v97, v101
	v_permlane16_swap_b32_e32 v98, v102
	v_permlane16_swap_b32_e32 v99, v103
	v_permlane16_swap_b32_e32 v104, v108
	v_permlane16_swap_b32_e32 v105, v109
	v_permlane16_swap_b32_e32 v106, v110
	v_permlane16_swap_b32_e32 v107, v111
	v_permlane16_swap_b32_e32 v48, v52
	v_permlane16_swap_b32_e32 v49, v53
	v_permlane16_swap_b32_e32 v50, v54
	v_permlane16_swap_b32_e32 v51, v55
	v_permlane16_swap_b32_e32 v56, v60
	v_permlane16_swap_b32_e32 v57, v61
	v_permlane16_swap_b32_e32 v58, v62
	v_permlane16_swap_b32_e32 v59, v63
	v_permlane16_swap_b32_e32 v32, v36
	v_permlane16_swap_b32_e32 v33, v37
	v_permlane16_swap_b32_e32 v34, v38
	v_permlane16_swap_b32_e32 v35, v39
	v_permlane16_swap_b32_e32 v40, v44
	v_permlane16_swap_b32_e32 v41, v45
	v_permlane16_swap_b32_e32 v42, v46
	v_permlane16_swap_b32_e32 v43, v47
	v_permlane16_swap_b32_e32 v80, v84
	v_permlane16_swap_b32_e32 v81, v85
	v_permlane16_swap_b32_e32 v82, v86
	v_permlane16_swap_b32_e32 v83, v87
	v_permlane16_swap_b32_e32 v88, v92
	v_permlane16_swap_b32_e32 v89, v93
	v_permlane16_swap_b32_e32 v90, v94
	v_permlane16_swap_b32_e32 v91, v95
	v_permlane16_swap_b32_e32 v64, v68
	v_permlane16_swap_b32_e32 v65, v69
	v_permlane16_swap_b32_e32 v66, v70
	v_permlane16_swap_b32_e32 v67, v71
	v_permlane16_swap_b32_e32 v72, v76
	v_permlane16_swap_b32_e32 v73, v77
	v_permlane16_swap_b32_e32 v74, v78
	v_permlane16_swap_b32_e32 v75, v79
	v_permlane16_swap_b32_e32 v16, v20
	v_permlane16_swap_b32_e32 v17, v21
	v_permlane16_swap_b32_e32 v18, v22
	v_permlane16_swap_b32_e32 v19, v23
	v_permlane16_swap_b32_e32 v24, v28
	v_permlane16_swap_b32_e32 v25, v29
	v_permlane16_swap_b32_e32 v26, v30
	v_permlane16_swap_b32_e32 v27, v31
	v_permlane16_swap_b32_e32 v0, v4
	v_permlane16_swap_b32_e32 v1, v5
	v_permlane16_swap_b32_e32 v2, v6
	v_permlane16_swap_b32_e32 v3, v7
	v_permlane16_swap_b32_e32 v8, v12
	v_permlane16_swap_b32_e32 v9, v13
	v_permlane16_swap_b32_e32 v10, v14
	v_permlane16_swap_b32_e32 v11, v15
	v_permlane32_swap_b32_e32 v112, v116
	v_permlane32_swap_b32_e32 v113, v117
	v_permlane32_swap_b32_e32 v114, v118
	v_permlane32_swap_b32_e32 v115, v119
	v_permlane32_swap_b32_e32 v120, v124
	v_permlane32_swap_b32_e32 v121, v125
	v_permlane32_swap_b32_e32 v122, v126
	v_permlane32_swap_b32_e32 v123, v127
	v_permlane32_swap_b32_e32 v96, v100
	v_permlane32_swap_b32_e32 v97, v101
	v_permlane32_swap_b32_e32 v98, v102
	v_permlane32_swap_b32_e32 v99, v103
	v_permlane32_swap_b32_e32 v104, v108
	v_permlane32_swap_b32_e32 v105, v109
	v_permlane32_swap_b32_e32 v106, v110
	v_permlane32_swap_b32_e32 v107, v111
	v_permlane32_swap_b32_e32 v48, v52
	v_permlane32_swap_b32_e32 v49, v53
	v_permlane32_swap_b32_e32 v50, v54
	v_permlane32_swap_b32_e32 v51, v55
	v_permlane32_swap_b32_e32 v56, v60
	v_permlane32_swap_b32_e32 v57, v61
	v_permlane32_swap_b32_e32 v58, v62
	v_permlane32_swap_b32_e32 v59, v63
	v_permlane32_swap_b32_e32 v32, v36
	v_permlane32_swap_b32_e32 v33, v37
	v_permlane32_swap_b32_e32 v34, v38
	v_permlane32_swap_b32_e32 v35, v39
	v_permlane32_swap_b32_e32 v40, v44
	v_permlane32_swap_b32_e32 v41, v45
	v_permlane32_swap_b32_e32 v42, v46
	v_permlane32_swap_b32_e32 v43, v47
	v_permlane32_swap_b32_e32 v80, v84
	v_permlane32_swap_b32_e32 v81, v85
	v_permlane32_swap_b32_e32 v82, v86
	v_permlane32_swap_b32_e32 v83, v87
	v_permlane32_swap_b32_e32 v88, v92
	v_permlane32_swap_b32_e32 v89, v93
	v_permlane32_swap_b32_e32 v90, v94
	v_permlane32_swap_b32_e32 v91, v95
	v_permlane32_swap_b32_e32 v64, v68
	v_permlane32_swap_b32_e32 v65, v69
	v_permlane32_swap_b32_e32 v66, v70
	v_permlane32_swap_b32_e32 v67, v71
	v_permlane32_swap_b32_e32 v72, v76
	v_permlane32_swap_b32_e32 v73, v77
	v_permlane32_swap_b32_e32 v74, v78
	v_permlane32_swap_b32_e32 v75, v79
	v_permlane32_swap_b32_e32 v16, v20
	v_permlane32_swap_b32_e32 v17, v21
	v_permlane32_swap_b32_e32 v18, v22
	v_permlane32_swap_b32_e32 v19, v23
	v_permlane32_swap_b32_e32 v24, v28
	v_permlane32_swap_b32_e32 v25, v29
	v_permlane32_swap_b32_e32 v26, v30
	v_permlane32_swap_b32_e32 v27, v31
	v_permlane32_swap_b32_e32 v0, v4
	v_permlane32_swap_b32_e32 v1, v5
	v_permlane32_swap_b32_e32 v2, v6
	v_permlane32_swap_b32_e32 v3, v7
	v_permlane32_swap_b32_e32 v8, v12
	v_permlane32_swap_b32_e32 v9, v13
	v_permlane32_swap_b32_e32 v10, v14
	v_permlane32_swap_b32_e32 v11, v15
	s_waitcnt vmcnt(0)
	s_waitcnt vmcnt(0)
	v_mul_f32_e32 v133, 0xbfb8aa3b, v112
	v_exp_f32_e32 v133, v133
	s_movk_i32 s1, 0x2400
	v_mul_lo_u32 v128, v238, s1
	v_lshl_or_b32 v131, s0, 6, v181
	v_add_f32_e32 v133, 1.0, v133
	v_lshl_or_b32 v132, v239, 1, v128
	v_and_b32_e32 v129, 0xffffffc0, v237
	v_lshl_or_b32 v128, v181, 1, v128
	v_rcp_f32_e32 v135, v133
	s_nop 0
	v_mul_f32_e32 v112, v112, v135
	v_mul_f32_e32 v96, v96, v112
	v_cvt_pk_bf16_f32 v112, v96, s0
	s_movk_i32 s0, 0x240
	v_mad_u32_u24 v96, v183, s0, v132
	ds_write_b16 v96, v112
	v_mul_f32_e32 v112, 0xbfb8aa3b, v113
	v_exp_f32_e32 v112, v112
	v_lshl_add_u32 v130, s7, 8, v129
	v_lshrrev_b32_e32 v129, 2, v240
	v_mad_u32_u24 v128, v129, s42, v128
	v_add_f32_e32 v112, 1.0, v112
	v_rcp_f32_e32 v133, v112
	s_nop 0
	v_mul_f32_e32 v112, v113, v133
	v_mul_f32_e32 v97, v97, v112
	v_cvt_pk_bf16_f32 v97, v97, s0
	ds_write_b16 v96, v97 offset:144
	v_mul_f32_e32 v97, 0xbfb8aa3b, v114
	v_exp_f32_e32 v97, v97
	s_nop 0
	v_add_f32_e32 v97, 1.0, v97
	v_rcp_f32_e32 v113, v97
	s_nop 0
	v_mul_f32_e32 v97, v114, v113
	v_mul_f32_e32 v97, v98, v97
	v_cvt_pk_bf16_f32 v97, v97, s0
	ds_write_b16 v96, v97 offset:288
	v_mul_f32_e32 v97, 0xbfb8aa3b, v115
	v_exp_f32_e32 v97, v97
	s_nop 0
	v_add_f32_e32 v97, 1.0, v97
	v_rcp_f32_e32 v112, v97
	s_nop 0
	v_mul_f32_e32 v97, v115, v112
	v_mul_f32_e32 v97, v99, v97
	v_cvt_pk_bf16_f32 v97, v97, s0
	ds_write_b16 v96, v97 offset:432
	v_mul_f32_e32 v97, 0xbfb8aa3b, v116
	v_exp_f32_e32 v97, v97
	s_nop 0
	v_add_f32_e32 v97, 1.0, v97
	v_rcp_f32_e32 v99, v97
	s_nop 0
	v_mul_f32_e32 v97, v116, v99
	v_mul_f32_e32 v97, v100, v97
	v_cvt_pk_bf16_f32 v97, v97, s0
	ds_write_b16 v96, v97 offset:1152
	v_mul_f32_e32 v97, 0xbfb8aa3b, v117
	v_exp_f32_e32 v97, v97
	s_nop 0
	v_add_f32_e32 v97, 1.0, v97
	v_rcp_f32_e32 v99, v97
	s_nop 0
	v_mul_f32_e32 v97, v117, v99
	v_mul_f32_e32 v97, v101, v97
	v_cvt_pk_bf16_f32 v97, v97, s0
	ds_write_b16 v96, v97 offset:1296
	v_mul_f32_e32 v97, 0xbfb8aa3b, v118
	v_exp_f32_e32 v97, v97
	s_nop 0
	v_add_f32_e32 v97, 1.0, v97
	v_rcp_f32_e32 v99, v97
	s_nop 0
	v_mul_f32_e32 v97, v118, v99
	v_mul_f32_e32 v97, v102, v97
	v_cvt_pk_bf16_f32 v97, v97, s0
	ds_write_b16 v96, v97 offset:1440
	v_mul_f32_e32 v97, 0xbfb8aa3b, v119
	v_exp_f32_e32 v97, v97
	s_nop 0
	v_add_f32_e32 v97, 1.0, v97
	v_rcp_f32_e32 v99, v97
	s_nop 0
	v_mul_f32_e32 v97, v119, v99
	v_mul_f32_e32 v97, v103, v97
	v_cvt_pk_bf16_f32 v97, v97, s0
	ds_write_b16 v96, v97 offset:1584
	v_mul_f32_e32 v97, 0xbfb8aa3b, v120
	v_exp_f32_e32 v97, v97
	s_nop 0
	v_add_f32_e32 v97, 1.0, v97
	v_rcp_f32_e32 v99, v97
	s_nop 0
	v_mul_f32_e32 v97, v120, v99
	v_mul_f32_e32 v97, v104, v97
	v_cvt_pk_bf16_f32 v97, v97, s0
	ds_write_b16 v96, v97 offset:2304
	v_mul_f32_e32 v97, 0xbfb8aa3b, v121
	v_exp_f32_e32 v97, v97
	s_nop 0
	v_add_f32_e32 v97, 1.0, v97
	v_rcp_f32_e32 v99, v97
	s_nop 0
	v_mul_f32_e32 v97, v121, v99
	v_mul_f32_e32 v97, v105, v97
	v_cvt_pk_bf16_f32 v97, v97, s0
	ds_write_b16 v96, v97 offset:2448
	v_mul_f32_e32 v97, 0xbfb8aa3b, v122
	v_exp_f32_e32 v97, v97
	s_nop 0
	v_add_f32_e32 v97, 1.0, v97
	v_rcp_f32_e32 v99, v97
	s_nop 0
	v_mul_f32_e32 v97, v122, v99
	v_mul_f32_e32 v97, v106, v97
	v_cvt_pk_bf16_f32 v97, v97, s0
	ds_write_b16 v96, v97 offset:2592
	v_mul_f32_e32 v97, 0xbfb8aa3b, v123
	v_exp_f32_e32 v97, v97
	s_nop 0
	v_add_f32_e32 v97, 1.0, v97
	v_rcp_f32_e32 v99, v97
	s_nop 0
	v_mul_f32_e32 v97, v123, v99
	v_mul_f32_e32 v97, v107, v97
	v_cvt_pk_bf16_f32 v97, v97, s0
	ds_write_b16 v96, v97 offset:2736
	v_mul_f32_e32 v97, 0xbfb8aa3b, v124
	v_exp_f32_e32 v97, v97
	s_nop 0
	v_add_f32_e32 v97, 1.0, v97
	v_rcp_f32_e32 v99, v97
	s_nop 0
	v_mul_f32_e32 v97, v124, v99
	v_mul_f32_e32 v97, v108, v97
	v_cvt_pk_bf16_f32 v97, v97, s0
	ds_write_b16 v96, v97 offset:3456
	v_mul_f32_e32 v97, 0xbfb8aa3b, v125
	v_exp_f32_e32 v97, v97
	s_nop 0
	v_add_f32_e32 v97, 1.0, v97
	v_rcp_f32_e32 v99, v97
	s_nop 0
	v_mul_f32_e32 v97, v125, v99
	v_mul_f32_e32 v97, v109, v97
	v_cvt_pk_bf16_f32 v97, v97, s0
	ds_write_b16 v96, v97 offset:3600
	v_mul_f32_e32 v97, 0xbfb8aa3b, v126
	v_exp_f32_e32 v97, v97
	s_nop 0
	v_add_f32_e32 v97, 1.0, v97
	v_rcp_f32_e32 v99, v97
	s_nop 0
	v_mul_f32_e32 v97, v126, v99
	v_mul_f32_e32 v97, v110, v97
	v_cvt_pk_bf16_f32 v97, v97, s0
	ds_write_b16 v96, v97 offset:3744
	v_mul_f32_e32 v97, 0xbfb8aa3b, v127
	v_exp_f32_e32 v97, v97
	s_nop 0
	v_add_f32_e32 v97, 1.0, v97
	v_rcp_f32_e32 v99, v97
	s_nop 0
	v_mul_f32_e32 v97, v127, v99
	v_mul_f32_e32 v97, v111, v97
	v_cvt_pk_bf16_f32 v97, v97, s0
	ds_write_b16 v96, v97 offset:3888
	v_mul_f32_e32 v97, 0xbfb8aa3b, v80
	v_exp_f32_e32 v97, v97
	s_nop 0
	v_add_f32_e32 v97, 1.0, v97
	v_rcp_f32_e32 v99, v97
	s_nop 0
	v_mul_f32_e32 v80, v80, v99
	v_mul_f32_e32 v64, v64, v80
	v_cvt_pk_bf16_f32 v64, v64, s0
	ds_write_b16 v96, v64 offset:4608
	v_mul_f32_e32 v64, 0xbfb8aa3b, v81
	v_exp_f32_e32 v64, v64
	s_nop 0
	v_add_f32_e32 v64, 1.0, v64
	v_rcp_f32_e32 v97, v64
	s_nop 0
	v_mul_f32_e32 v64, v81, v97
	v_mul_f32_e32 v64, v65, v64
	v_cvt_pk_bf16_f32 v64, v64, s0
	ds_write_b16 v96, v64 offset:4752
	v_mul_f32_e32 v64, 0xbfb8aa3b, v82
	v_exp_f32_e32 v64, v64
	s_nop 0
	v_add_f32_e32 v64, 1.0, v64
	v_rcp_f32_e32 v80, v64
	s_nop 0
	v_mul_f32_e32 v64, v82, v80
	v_mul_f32_e32 v64, v66, v64
	v_cvt_pk_bf16_f32 v64, v64, s0
	ds_write_b16 v96, v64 offset:4896
	v_mul_f32_e32 v64, 0xbfb8aa3b, v83
	v_exp_f32_e32 v64, v64
	s_nop 0
	v_add_f32_e32 v64, 1.0, v64
	v_rcp_f32_e32 v66, v64
	s_nop 0
	v_mul_f32_e32 v64, v83, v66
	v_mul_f32_e32 v64, v67, v64
	v_cvt_pk_bf16_f32 v64, v64, s0
	ds_write_b16 v96, v64 offset:5040
	v_mul_f32_e32 v64, 0xbfb8aa3b, v84
	v_exp_f32_e32 v64, v64
	s_nop 0
	v_add_f32_e32 v64, 1.0, v64
	v_rcp_f32_e32 v66, v64
	s_nop 0
	v_mul_f32_e32 v64, v84, v66
	v_mul_f32_e32 v64, v68, v64
	v_cvt_pk_bf16_f32 v64, v64, s0
	ds_write_b16 v96, v64 offset:5760
	v_mul_f32_e32 v64, 0xbfb8aa3b, v85
	v_exp_f32_e32 v64, v64
	s_nop 0
	v_add_f32_e32 v64, 1.0, v64
	v_rcp_f32_e32 v66, v64
	s_nop 0
	v_mul_f32_e32 v64, v85, v66
	v_mul_f32_e32 v64, v69, v64
	v_cvt_pk_bf16_f32 v64, v64, s0
	ds_write_b16 v96, v64 offset:5904
	v_mul_f32_e32 v64, 0xbfb8aa3b, v86
	v_exp_f32_e32 v64, v64
	s_nop 0
	v_add_f32_e32 v64, 1.0, v64
	v_rcp_f32_e32 v66, v64
	s_nop 0
	v_mul_f32_e32 v64, v86, v66
	v_mul_f32_e32 v64, v70, v64
	v_cvt_pk_bf16_f32 v64, v64, s0
	ds_write_b16 v96, v64 offset:6048
	v_mul_f32_e32 v64, 0xbfb8aa3b, v87
	v_exp_f32_e32 v64, v64
	s_nop 0
	v_add_f32_e32 v64, 1.0, v64
	v_rcp_f32_e32 v66, v64
	s_nop 0
	v_mul_f32_e32 v64, v87, v66
	v_mul_f32_e32 v64, v71, v64
	v_cvt_pk_bf16_f32 v64, v64, s0
	ds_write_b16 v96, v64 offset:6192
	v_mul_f32_e32 v64, 0xbfb8aa3b, v88
	v_exp_f32_e32 v64, v64
	v_ashrrev_i32_e32 v71, 5, v130
	v_or_b32_e32 v70, 1, v71
	v_add_f32_e32 v64, 1.0, v64
	v_rcp_f32_e32 v66, v64
	s_nop 0
	v_mul_f32_e32 v64, v88, v66
	v_mul_f32_e32 v64, v72, v64
	v_cvt_pk_bf16_f32 v64, v64, s0
	ds_write_b16 v96, v64 offset:6912
	v_mul_f32_e32 v64, 0xbfb8aa3b, v89
	v_exp_f32_e32 v64, v64
	s_nop 0
	v_add_f32_e32 v64, 1.0, v64
	v_rcp_f32_e32 v66, v64
	s_nop 0
	v_mul_f32_e32 v64, v89, v66
	v_mul_f32_e32 v64, v73, v64
	v_cvt_pk_bf16_f32 v64, v64, s0
	ds_write_b16 v96, v64 offset:7056
	v_mul_f32_e32 v64, 0xbfb8aa3b, v90
	v_exp_f32_e32 v64, v64
	s_nop 0
	v_add_f32_e32 v64, 1.0, v64
	v_rcp_f32_e32 v66, v64
	s_nop 0
	v_mul_f32_e32 v64, v90, v66
	v_mul_f32_e32 v64, v74, v64
	v_cvt_pk_bf16_f32 v64, v64, s0
	ds_write_b16 v96, v64 offset:7200
	v_mul_f32_e32 v64, 0xbfb8aa3b, v91
	v_exp_f32_e32 v64, v64
	s_nop 0
	v_add_f32_e32 v64, 1.0, v64
	v_rcp_f32_e32 v66, v64
	s_nop 0
	v_mul_f32_e32 v64, v91, v66
	v_mul_f32_e32 v64, v75, v64
	v_cvt_pk_bf16_f32 v64, v64, s0
	ds_write_b16 v96, v64 offset:7344
	v_mul_f32_e32 v64, 0xbfb8aa3b, v92
	v_exp_f32_e32 v64, v64
	s_nop 0
	v_add_f32_e32 v64, 1.0, v64
	v_rcp_f32_e32 v66, v64
	s_nop 0
	v_mul_f32_e32 v64, v92, v66
	v_mul_f32_e32 v64, v76, v64
	v_cvt_pk_bf16_f32 v64, v64, s0
	ds_write_b16 v96, v64 offset:8064
	v_mul_f32_e32 v64, 0xbfb8aa3b, v93
	v_exp_f32_e32 v64, v64
	s_nop 0
	v_add_f32_e32 v64, 1.0, v64
	v_rcp_f32_e32 v66, v64
	s_nop 0
	v_mul_f32_e32 v64, v93, v66
	v_mul_f32_e32 v64, v77, v64
	v_cvt_pk_bf16_f32 v64, v64, s0
	ds_write_b16 v96, v64 offset:8208
	v_mul_f32_e32 v64, 0xbfb8aa3b, v94
	v_exp_f32_e32 v64, v64
	s_nop 0
	v_add_f32_e32 v64, 1.0, v64
	v_rcp_f32_e32 v66, v64
	s_nop 0
	v_mul_f32_e32 v64, v94, v66
	v_mul_f32_e32 v64, v78, v64
	v_cvt_pk_bf16_f32 v64, v64, s0
	ds_write_b16 v96, v64 offset:8352
	v_mul_f32_e32 v64, 0xbfb8aa3b, v95
	v_exp_f32_e32 v64, v64
	s_nop 0
	v_add_f32_e32 v64, 1.0, v64
	v_rcp_f32_e32 v66, v64
	s_nop 0
	v_mul_f32_e32 v64, v95, v66
	v_mul_f32_e32 v64, v79, v64
	v_cvt_pk_bf16_f32 v64, v64, s0
	ds_write_b16 v96, v64 offset:8496
	v_ashrrev_i32_e32 v68, 4, v131
	s_waitcnt lgkmcnt(0)
	v_ashrrev_i32_e32 v69, 31, v68
	ds_read_b128 v[72:75], v128
	v_mad_i64_i32 v[64:65], s[0:1], v71, s23, v[68:69]
	v_lshlrev_b64 v[64:65], 10, v[64:65]
	v_lshlrev_b32_e32 v66, 6, v181
	v_lshl_add_u64 v[64:65], s[66:67], 0, v[64:65]
	v_and_b32_e32 v176, 0x200, v66
	v_lshl_add_u64 v[76:77], v[64:65], 0, v[176:177]
	v_lshlrev_b32_e32 v66, 4, v129
	v_mov_b32_e32 v67, v177
	v_lshl_add_u64 v[64:65], v[76:77], 0, v[66:67]
	s_waitcnt lgkmcnt(0)
	global_store_dwordx4 v[64:65], v[72:75], off
	ds_read_b128 v[72:75], v128 offset:2304
	v_or_b32_e32 v64, 0x100, v66
	v_mov_b32_e32 v65, v177
	v_lshl_add_u64 v[76:77], v[76:77], 0, v[64:65]
	s_waitcnt lgkmcnt(0)
	global_store_dwordx4 v[76:77], v[72:75], off
	ds_read_b128 v[72:75], v128 offset:4608
	v_mad_i64_i32 v[76:77], s[0:1], v70, s23, v[68:69]
	v_lshlrev_b64 v[76:77], 10, v[76:77]
	v_lshl_add_u64 v[76:77], s[66:67], 0, v[76:77]
	v_lshl_add_u64 v[76:77], v[76:77], 0, v[176:177]
	v_lshl_add_u64 v[78:79], v[76:77], 0, v[66:67]
	v_mul_f32_e32 v69, 0xbfb8aa3b, v48
	s_waitcnt lgkmcnt(0)
	global_store_dwordx4 v[78:79], v[72:75], off
	ds_read_b128 v[72:75], v128 offset:6912
	v_exp_f32_e32 v69, v69
	v_lshl_add_u64 v[76:77], v[76:77], 0, v[64:65]
	v_add_f32_e32 v69, 1.0, v69
	s_waitcnt lgkmcnt(0)
	global_store_dwordx4 v[76:77], v[72:75], off
	s_waitcnt lgkmcnt(0)
	s_nop 1
	v_rcp_f32_e32 v73, v69
	s_nop 0
	v_mul_f32_e32 v48, v48, v73
	v_mul_f32_e32 v32, v32, v48
	v_cvt_pk_bf16_f32 v32, v32, s0
	ds_write_b16 v96, v32
	v_mul_f32_e32 v32, 0xbfb8aa3b, v49
	v_exp_f32_e32 v32, v32
	s_nop 0
	v_add_f32_e32 v32, 1.0, v32
	v_rcp_f32_e32 v69, v32
	s_nop 0
	v_mul_f32_e32 v32, v49, v69
	v_mul_f32_e32 v32, v33, v32
	v_cvt_pk_bf16_f32 v32, v32, s0
	ds_write_b16 v96, v32 offset:144
	v_mul_f32_e32 v32, 0xbfb8aa3b, v50
	v_exp_f32_e32 v32, v32
	s_nop 0
	v_add_f32_e32 v32, 1.0, v32
	v_rcp_f32_e32 v48, v32
	s_nop 0
	v_mul_f32_e32 v32, v50, v48
	v_mul_f32_e32 v32, v34, v32
	v_cvt_pk_bf16_f32 v32, v32, s0
	ds_write_b16 v96, v32 offset:288
	v_mul_f32_e32 v32, 0xbfb8aa3b, v51
	v_exp_f32_e32 v32, v32
	s_nop 0
	v_add_f32_e32 v32, 1.0, v32
	v_rcp_f32_e32 v34, v32
	s_nop 0
	v_mul_f32_e32 v32, v51, v34
	v_mul_f32_e32 v32, v35, v32
	v_cvt_pk_bf16_f32 v32, v32, s0
	ds_write_b16 v96, v32 offset:432
	v_mul_f32_e32 v32, 0xbfb8aa3b, v52
	v_exp_f32_e32 v32, v32
	s_nop 0
	v_add_f32_e32 v32, 1.0, v32
	v_rcp_f32_e32 v34, v32
	s_nop 0
	v_mul_f32_e32 v32, v52, v34
	v_mul_f32_e32 v32, v36, v32
	v_cvt_pk_bf16_f32 v32, v32, s0
	ds_write_b16 v96, v32 offset:1152
	v_mul_f32_e32 v32, 0xbfb8aa3b, v53
	v_exp_f32_e32 v32, v32
	s_nop 0
	v_add_f32_e32 v32, 1.0, v32
	v_rcp_f32_e32 v34, v32
	s_nop 0
	v_mul_f32_e32 v32, v53, v34
	v_mul_f32_e32 v32, v37, v32
	v_cvt_pk_bf16_f32 v32, v32, s0
	ds_write_b16 v96, v32 offset:1296
	v_mul_f32_e32 v32, 0xbfb8aa3b, v54
	v_exp_f32_e32 v32, v32
	s_nop 0
	v_add_f32_e32 v32, 1.0, v32
	v_rcp_f32_e32 v34, v32
	s_nop 0
	v_mul_f32_e32 v32, v54, v34
	v_mul_f32_e32 v32, v38, v32
	v_cvt_pk_bf16_f32 v32, v32, s0
	ds_write_b16 v96, v32 offset:1440
	v_mul_f32_e32 v32, 0xbfb8aa3b, v55
	v_exp_f32_e32 v32, v32
	s_nop 0
	v_add_f32_e32 v32, 1.0, v32
	v_rcp_f32_e32 v34, v32
	s_nop 0
	v_mul_f32_e32 v32, v55, v34
	v_mul_f32_e32 v32, v39, v32
	v_cvt_pk_bf16_f32 v32, v32, s0
	ds_write_b16 v96, v32 offset:1584
	v_mul_f32_e32 v32, 0xbfb8aa3b, v56
	v_exp_f32_e32 v32, v32
	s_nop 0
	v_add_f32_e32 v32, 1.0, v32
	v_rcp_f32_e32 v34, v32
	s_nop 0
	v_mul_f32_e32 v32, v56, v34
	v_mul_f32_e32 v32, v40, v32
	v_cvt_pk_bf16_f32 v32, v32, s0
	ds_write_b16 v96, v32 offset:2304
	v_mul_f32_e32 v32, 0xbfb8aa3b, v57
	v_exp_f32_e32 v32, v32
	s_nop 0
	v_add_f32_e32 v32, 1.0, v32
	v_rcp_f32_e32 v34, v32
	s_nop 0
	v_mul_f32_e32 v32, v57, v34
	v_mul_f32_e32 v32, v41, v32
	v_cvt_pk_bf16_f32 v32, v32, s0
	ds_write_b16 v96, v32 offset:2448
	v_mul_f32_e32 v32, 0xbfb8aa3b, v58
	v_exp_f32_e32 v32, v32
	s_nop 0
	v_add_f32_e32 v32, 1.0, v32
	v_rcp_f32_e32 v34, v32
	s_nop 0
	v_mul_f32_e32 v32, v58, v34
	v_mul_f32_e32 v32, v42, v32
	v_cvt_pk_bf16_f32 v32, v32, s0
	ds_write_b16 v96, v32 offset:2592
	v_mul_f32_e32 v32, 0xbfb8aa3b, v59
	v_exp_f32_e32 v32, v32
	s_nop 0
	v_add_f32_e32 v32, 1.0, v32
	v_rcp_f32_e32 v34, v32
	s_nop 0
	v_mul_f32_e32 v32, v59, v34
	v_mul_f32_e32 v32, v43, v32
	v_cvt_pk_bf16_f32 v32, v32, s0
	ds_write_b16 v96, v32 offset:2736
	v_mul_f32_e32 v32, 0xbfb8aa3b, v60
	v_exp_f32_e32 v32, v32
	s_nop 0
	v_add_f32_e32 v32, 1.0, v32
	v_rcp_f32_e32 v34, v32
	s_nop 0
	v_mul_f32_e32 v32, v60, v34
	v_mul_f32_e32 v32, v44, v32
	v_cvt_pk_bf16_f32 v32, v32, s0
	ds_write_b16 v96, v32 offset:3456
	v_mul_f32_e32 v32, 0xbfb8aa3b, v61
	v_exp_f32_e32 v32, v32
	s_nop 0
	v_add_f32_e32 v32, 1.0, v32
	v_rcp_f32_e32 v34, v32
	s_nop 0
	v_mul_f32_e32 v32, v61, v34
	v_mul_f32_e32 v32, v45, v32
	v_cvt_pk_bf16_f32 v32, v32, s0
	ds_write_b16 v96, v32 offset:3600
	v_mul_f32_e32 v32, 0xbfb8aa3b, v62
	v_exp_f32_e32 v32, v32
	s_nop 0
	v_add_f32_e32 v32, 1.0, v32
	v_rcp_f32_e32 v34, v32
	s_nop 0
	v_mul_f32_e32 v32, v62, v34
	v_mul_f32_e32 v32, v46, v32
	v_cvt_pk_bf16_f32 v32, v32, s0
	ds_write_b16 v96, v32 offset:3744
	v_mul_f32_e32 v32, 0xbfb8aa3b, v63
	v_exp_f32_e32 v32, v32
	s_nop 0
	v_add_f32_e32 v32, 1.0, v32
	v_rcp_f32_e32 v34, v32
	s_nop 0
	v_mul_f32_e32 v32, v63, v34
	v_mul_f32_e32 v32, v47, v32
	v_cvt_pk_bf16_f32 v32, v32, s0
	ds_write_b16 v96, v32 offset:3888
	v_mul_f32_e32 v32, 0xbfb8aa3b, v16
	v_exp_f32_e32 v32, v32
	s_nop 0
	v_add_f32_e32 v32, 1.0, v32
	v_rcp_f32_e32 v34, v32
	s_nop 0
	v_mul_f32_e32 v16, v16, v34
	v_mul_f32_e32 v0, v0, v16
	v_cvt_pk_bf16_f32 v0, v0, s0
	ds_write_b16 v96, v0 offset:4608
	v_mul_f32_e32 v0, 0xbfb8aa3b, v17
	v_exp_f32_e32 v0, v0
	s_nop 0
	v_add_f32_e32 v0, 1.0, v0
	v_rcp_f32_e32 v32, v0
	s_nop 0
	v_mul_f32_e32 v0, v17, v32
	v_mul_f32_e32 v0, v1, v0
	v_cvt_pk_bf16_f32 v0, v0, s0
	ds_write_b16 v96, v0 offset:4752
	v_mul_f32_e32 v0, 0xbfb8aa3b, v18
	v_exp_f32_e32 v0, v0
	s_nop 0
	v_add_f32_e32 v0, 1.0, v0
	v_rcp_f32_e32 v16, v0
	s_nop 0
	v_mul_f32_e32 v0, v18, v16
	v_mul_f32_e32 v0, v2, v0
	v_cvt_pk_bf16_f32 v0, v0, s0
	ds_write_b16 v96, v0 offset:4896
	v_mul_f32_e32 v0, 0xbfb8aa3b, v19
	v_exp_f32_e32 v0, v0
	s_nop 0
	v_add_f32_e32 v0, 1.0, v0
	v_rcp_f32_e32 v2, v0
	s_nop 0
	v_mul_f32_e32 v0, v19, v2
	v_mul_f32_e32 v0, v3, v0
	v_cvt_pk_bf16_f32 v0, v0, s0
	ds_write_b16 v96, v0 offset:5040
	v_mul_f32_e32 v0, 0xbfb8aa3b, v20
	v_exp_f32_e32 v0, v0
	s_nop 0
	v_add_f32_e32 v0, 1.0, v0
	v_rcp_f32_e32 v2, v0
	s_nop 0
	v_mul_f32_e32 v0, v20, v2
	v_mul_f32_e32 v0, v4, v0
	v_cvt_pk_bf16_f32 v0, v0, s0
	ds_write_b16 v96, v0 offset:5760
	v_mul_f32_e32 v0, 0xbfb8aa3b, v21
	v_exp_f32_e32 v0, v0
	s_nop 0
	v_add_f32_e32 v0, 1.0, v0
	v_rcp_f32_e32 v2, v0
	s_nop 0
	v_mul_f32_e32 v0, v21, v2
	v_mul_f32_e32 v0, v5, v0
	v_cvt_pk_bf16_f32 v0, v0, s0
	ds_write_b16 v96, v0 offset:5904
	v_mul_f32_e32 v0, 0xbfb8aa3b, v22
	v_exp_f32_e32 v0, v0
	s_nop 0
	v_add_f32_e32 v0, 1.0, v0
	v_rcp_f32_e32 v2, v0
	s_nop 0
	v_mul_f32_e32 v0, v22, v2
	v_mul_f32_e32 v0, v6, v0
	v_cvt_pk_bf16_f32 v0, v0, s0
	ds_write_b16 v96, v0 offset:6048
	v_mul_f32_e32 v0, 0xbfb8aa3b, v23
	v_exp_f32_e32 v0, v0
	s_nop 0
	v_add_f32_e32 v0, 1.0, v0
	v_rcp_f32_e32 v2, v0
	s_nop 0
	v_mul_f32_e32 v0, v23, v2
	v_mul_f32_e32 v0, v7, v0
	v_cvt_pk_bf16_f32 v0, v0, s0
	ds_write_b16 v96, v0 offset:6192
	v_mul_f32_e32 v0, 0xbfb8aa3b, v24
	v_exp_f32_e32 v0, v0
	s_nop 0
	v_add_f32_e32 v0, 1.0, v0
	v_rcp_f32_e32 v2, v0
	s_nop 0
	v_mul_f32_e32 v0, v24, v2
	v_mul_f32_e32 v0, v8, v0
	v_cvt_pk_bf16_f32 v0, v0, s0
	ds_write_b16 v96, v0 offset:6912
	v_mul_f32_e32 v0, 0xbfb8aa3b, v25
	v_exp_f32_e32 v0, v0
	s_nop 0
	v_add_f32_e32 v0, 1.0, v0
	v_rcp_f32_e32 v2, v0
	s_nop 0
	v_mul_f32_e32 v0, v25, v2
	v_mul_f32_e32 v0, v9, v0
	v_cvt_pk_bf16_f32 v0, v0, s0
	ds_write_b16 v96, v0 offset:7056
	v_mul_f32_e32 v0, 0xbfb8aa3b, v26
	v_exp_f32_e32 v0, v0
	s_nop 0
	v_add_f32_e32 v0, 1.0, v0
	v_rcp_f32_e32 v2, v0
	s_nop 0
	v_mul_f32_e32 v0, v26, v2
	v_mul_f32_e32 v0, v10, v0
	v_cvt_pk_bf16_f32 v0, v0, s0
	ds_write_b16 v96, v0 offset:7200
	v_mul_f32_e32 v0, 0xbfb8aa3b, v27
	v_exp_f32_e32 v0, v0
	s_nop 0
	v_add_f32_e32 v0, 1.0, v0
	v_rcp_f32_e32 v2, v0
	s_nop 0
	v_mul_f32_e32 v0, v27, v2
	v_mul_f32_e32 v0, v11, v0
	v_cvt_pk_bf16_f32 v0, v0, s0
	ds_write_b16 v96, v0 offset:7344
	v_mul_f32_e32 v0, 0xbfb8aa3b, v28
	v_exp_f32_e32 v0, v0
	s_nop 0
	v_add_f32_e32 v0, 1.0, v0
	v_rcp_f32_e32 v2, v0
	s_nop 0
	v_mul_f32_e32 v0, v28, v2
	v_mul_f32_e32 v0, v12, v0
	v_cvt_pk_bf16_f32 v0, v0, s0
	ds_write_b16 v96, v0 offset:8064
	v_mul_f32_e32 v0, 0xbfb8aa3b, v29
	v_exp_f32_e32 v0, v0
	s_nop 0
	v_add_f32_e32 v0, 1.0, v0
	v_rcp_f32_e32 v2, v0
	s_nop 0
	v_mul_f32_e32 v0, v29, v2
	v_mul_f32_e32 v0, v13, v0
	v_cvt_pk_bf16_f32 v0, v0, s0
	ds_write_b16 v96, v0 offset:8208
	v_mul_f32_e32 v0, 0xbfb8aa3b, v30
	v_exp_f32_e32 v0, v0
	s_nop 0
	v_add_f32_e32 v0, 1.0, v0
	v_rcp_f32_e32 v2, v0
	s_nop 0
	v_mul_f32_e32 v0, v30, v2
	v_mul_f32_e32 v0, v14, v0
	v_cvt_pk_bf16_f32 v0, v0, s0
	ds_write_b16 v96, v0 offset:8352
	v_mul_f32_e32 v0, 0xbfb8aa3b, v31
	v_exp_f32_e32 v0, v0
	s_nop 0
	v_add_f32_e32 v0, 1.0, v0
	v_rcp_f32_e32 v2, v0
	s_nop 0
	v_mul_f32_e32 v0, v31, v2
	v_mul_f32_e32 v0, v15, v0
	v_cvt_pk_bf16_f32 v0, v0, s0
	ds_write_b16 v96, v0 offset:8496
	v_or_b32_e32 v4, 2, v68
	s_waitcnt lgkmcnt(0)
	v_ashrrev_i32_e32 v5, 31, v4
	ds_read_b128 v[0:3], v128
	v_mad_i64_i32 v[6:7], s[0:1], v71, s23, v[4:5]
	v_lshlrev_b64 v[6:7], 10, v[6:7]
	v_lshl_add_u64 v[6:7], s[66:67], 0, v[6:7]
	v_lshl_add_u64 v[6:7], v[6:7], 0, v[176:177]
	v_lshl_add_u64 v[8:9], v[6:7], 0, v[66:67]
	s_waitcnt lgkmcnt(0)
	global_store_dwordx4 v[8:9], v[0:3], off
	ds_read_b128 v[0:3], v128 offset:2304
	v_lshl_add_u64 v[6:7], v[6:7], 0, v[64:65]
	v_mad_i64_i32 v[4:5], s[0:1], v70, s23, v[4:5]
	v_lshlrev_b64 v[4:5], 10, v[4:5]
	s_waitcnt lgkmcnt(0)
	global_store_dwordx4 v[6:7], v[0:3], off
	ds_read_b128 v[0:3], v128 offset:4608
	v_lshl_add_u64 v[4:5], s[66:67], 0, v[4:5]
	v_lshl_add_u64 v[4:5], v[4:5], 0, v[176:177]
	v_lshl_add_u64 v[6:7], v[4:5], 0, v[66:67]
	v_lshl_add_u64 v[4:5], v[4:5], 0, v[64:65]
	s_waitcnt lgkmcnt(0)
	global_store_dwordx4 v[6:7], v[0:3], off
	ds_read_b128 v[0:3], v128 offset:6912
	v_readlane_b32 s0, v254, 11
	s_add_i32 s2, s2, s0
	s_cmp_lt_i32 s2, s3
	s_waitcnt lgkmcnt(0)
	global_store_dwordx4 v[4:5], v[0:3], off
	s_waitcnt lgkmcnt(0)
	s_barrier
	s_cbranch_scc1 .LBB0_1031

.LBB0_1086:
	s_ashr_i32 s6, s2, 31
	s_lshr_b32 s6, s6, 26
	s_add_i32 s6, s2, s6
	s_ashr_i32 s7, s6, 6
	s_lshl_b32 s7, s7, 3
	s_sub_i32 s8, s25, s7
	s_min_i32 s8, s8, 8
	s_abs_i32 s9, s8
	v_cvt_f32_u32_e32 v0, s9
	s_sub_i32 s12, 0, s9
	s_andn2_b32 s6, s6, 63
	s_sub_i32 s10, s2, s6
	v_rcp_iflag_f32_e32 v0, v0
	s_abs_i32 s6, s10
	s_xor_b32 s11, s10, s8
	s_ashr_i32 s11, s11, 31
	v_mul_f32_e32 v0, 0x4f7ffffe, v0
	v_cvt_u32_f32_e32 v0, v0
	v_mov_b32_e32 v181, v179
	v_readfirstlane_b32 s13, v0
	s_mul_i32 s12, s12, s13
	s_mul_hi_u32 s12, s13, s12
	s_add_i32 s13, s13, s12
	s_mul_hi_u32 s12, s6, s13
	s_mul_i32 s13, s12, s9
	s_sub_i32 s6, s6, s13
	s_add_i32 s14, s12, 1
	s_sub_i32 s13, s6, s9
	s_cmp_ge_u32 s6, s9
	s_cselect_b32 s12, s14, s12
	s_cselect_b32 s6, s13, s6
	s_add_i32 s13, s12, 1
	s_cmp_ge_u32 s6, s9
	s_cselect_b32 s6, s13, s12
	s_xor_b32 s6, s6, s11
	s_sub_i32 s6, s6, s11
	s_mul_i32 s8, s8, s6
	s_add_i32 s7, s7, s5
	s_sub_i32 s8, s10, s8
	v_ashrrev_i32_e32 v237, 6, v181
	s_add_i32 s7, s7, s8
	v_lshlrev_b32_e32 v0, 1, v237
	v_bfe_u32 v183, v181, 5, 1
	v_lshl_add_u32 v2, s7, 3, v0
	v_mov_b64_e32 v[0:1], s[66:67]
	v_and_b32_e32 v238, 31, v181
	v_mad_i64_i32 v[0:1], s[8:9], v2, s24, v[0:1]
	v_lshlrev_b32_e32 v176, 9, v183
	v_lshl_add_u64 v[0:1], v[0:1], 0, v[176:177]
	v_lshlrev_b32_e32 v176, 4, v238
	v_ashrrev_i32_e32 v38, 2, v181
	s_mul_i32 s8, s6, 0xb0000
	v_lshl_add_u64 v[184:185], v[0:1], 0, v[176:177]
	s_mul_hi_i32 s9, s6, 0xb0000
	s_add_u32 s8, s3, s8
	v_lshlrev_b32_e32 v0, 5, v38
	s_addc_u32 s9, s4, s9
	v_ashrrev_i32_e32 v1, 31, v0
	v_lshlrev_b32_e32 v2, 4, v181
	v_lshl_add_u64 v[0:1], v[0:1], 1, s[8:9]
	v_and_b32_e32 v176, 48, v2
	v_lshl_add_u64 v[186:187], v[0:1], 0, v[176:177]
	s_movk_i32 s8, 0x2000
	v_add_co_u32_e32 v34, vcc, s8, v186
	v_mul_u32_u24_e32 v36, 40, v238
	s_nop 0
	v_addc_co_u32_e32 v35, vcc, 0, v187, vcc
	v_lshlrev_b32_e32 v37, 4, v183
	v_lshl_add_u32 v240, v36, 1, v37
	v_add_co_u32_e32 v36, vcc, s24, v184
	s_movk_i32 s9, 0x50
	s_nop 0
	v_addc_co_u32_e32 v37, vcc, 0, v185, vcc
	v_and_b32_e32 v239, 63, v181
	v_mov_b32_e32 v176, 0x800
	v_lshl_add_u64 v[188:189], v[186:187], 0, v[176:177]
	v_bfe_u32 v247, v181, 4, 1
	v_lshlrev_b32_e32 v176, 9, v183
	v_lshl_add_u32 v176, v247, 8, v176
	v_lshl_add_u64 v[184:185], v[184:185], 0, v[176:177]
	v_mov_b32_e32 v176, s24
	v_lshl_add_u64 v[186:187], v[184:185], 0, v[176:177]
	v_lshrrev_b32_e32 v241, 2, v181
	v_bfe_u32 v247, v181, 4, 2
	v_lshlrev_b32_e32 v247, 1, v247
	v_mov_b32_e32 v176, 0x78
	v_lshrrev_b32_e32 v247, v247, v176
	v_and_b32_e32 v247, 3, v247
	v_and_b32_e32 v246, 3, v181
	v_xor_b32_e32 v247, v247, v246
	v_lshlrev_b32_e32 v247, 4, v247
	v_lshl_add_u32 v241, v241, 6, v247
	v_bfe_u32 v247, v181, 2, 2
	v_lshlrev_b32_e32 v247, 1, v247
	v_lshrrev_b32_e32 v247, v247, v176
	v_and_b32_e32 v247, 3, v247
	v_bfe_u32 v246, v181, 4, 2
	v_xor_b32_e32 v247, v247, v246
	v_lshlrev_b32_e32 v247, 4, v247
	v_and_b32_e32 v246, 15, v181
	v_lshl_add_u32 v246, v246, 6, v247
	s_mov_b32 s96, 0
	v_lshl_add_u64 v[166:167], v[188:189], 0, s[96:97]
	global_load_dwordx4 v[160:163], v[166:167], off offset:-2048
	global_load_dwordx4 v[164:167], v[166:167], off offset:2048
	s_movk_i32 s96, 0x2000
	v_lshl_add_u64 v[174:175], v[188:189], 0, s[96:97]
	global_load_dwordx4 v[168:171], v[174:175], off offset:-2048
	global_load_dwordx4 v[172:175], v[174:175], off offset:2048
	s_mov_b32 s96, 0
	v_lshl_add_u64 v[248:249], v[184:185], 0, s[96:97]
	v_lshl_add_u64 v[250:251], v[186:187], 0, s[96:97]
	global_load_dwordx4 v[128:131], v[248:249], off
	global_load_dwordx4 v[132:135], v[248:249], off offset:256
	global_load_dwordx4 v[136:139], v[250:251], off
	global_load_dwordx4 v[140:143], v[250:251], off offset:256
	v_mov_b32_e32 v0, 0
	v_mov_b32_e32 v1, 0
	v_mov_b32_e32 v2, 0
	v_mov_b32_e32 v3, 0
	v_mov_b32_e32 v4, 0
	v_mov_b32_e32 v5, 0
	v_mov_b32_e32 v6, 0
	v_mov_b32_e32 v7, 0
	v_mov_b32_e32 v8, 0
	v_mov_b32_e32 v9, 0
	v_mov_b32_e32 v10, 0
	v_mov_b32_e32 v11, 0
	v_mov_b32_e32 v12, 0
	v_mov_b32_e32 v13, 0
	v_mov_b32_e32 v14, 0
	v_mov_b32_e32 v15, 0
	v_mov_b32_e32 v16, 0
	v_mov_b32_e32 v17, 0
	v_mov_b32_e32 v18, 0
	v_mov_b32_e32 v19, 0
	v_mov_b32_e32 v20, 0
	v_mov_b32_e32 v21, 0
	v_mov_b32_e32 v22, 0
	v_mov_b32_e32 v23, 0
	v_mov_b32_e32 v24, 0
	v_mov_b32_e32 v25, 0
	v_mov_b32_e32 v26, 0
	v_mov_b32_e32 v27, 0
	v_mov_b32_e32 v28, 0
	v_mov_b32_e32 v29, 0
	v_mov_b32_e32 v30, 0
	v_mov_b32_e32 v31, 0
	v_mov_b32_e32 v32, 0
	v_mov_b32_e32 v33, 0
	v_mov_b32_e32 v34, 0
	v_mov_b32_e32 v35, 0
	v_mov_b32_e32 v36, 0
	v_mov_b32_e32 v37, 0
	v_mov_b32_e32 v38, 0
	v_mov_b32_e32 v39, 0
	v_mov_b32_e32 v40, 0
	v_mov_b32_e32 v41, 0
	v_mov_b32_e32 v42, 0
	v_mov_b32_e32 v43, 0
	v_mov_b32_e32 v44, 0
	v_mov_b32_e32 v45, 0
	v_mov_b32_e32 v46, 0
	v_mov_b32_e32 v47, 0
	v_mov_b32_e32 v48, 0
	v_mov_b32_e32 v49, 0
	v_mov_b32_e32 v50, 0
	v_mov_b32_e32 v51, 0
	v_mov_b32_e32 v52, 0
	v_mov_b32_e32 v53, 0
	v_mov_b32_e32 v54, 0
	v_mov_b32_e32 v55, 0
	v_mov_b32_e32 v56, 0
	v_mov_b32_e32 v57, 0
	v_mov_b32_e32 v58, 0
	v_mov_b32_e32 v59, 0
	v_mov_b32_e32 v60, 0
	v_mov_b32_e32 v61, 0
	v_mov_b32_e32 v62, 0
	v_mov_b32_e32 v63, 0
	v_mov_b32_e32 v64, 0
	v_mov_b32_e32 v65, 0
	v_mov_b32_e32 v66, 0
	v_mov_b32_e32 v67, 0
	v_mov_b32_e32 v68, 0
	v_mov_b32_e32 v69, 0
	v_mov_b32_e32 v70, 0
	v_mov_b32_e32 v71, 0
	v_mov_b32_e32 v72, 0
	v_mov_b32_e32 v73, 0
	v_mov_b32_e32 v74, 0
	v_mov_b32_e32 v75, 0
	v_mov_b32_e32 v76, 0
	v_mov_b32_e32 v77, 0
	v_mov_b32_e32 v78, 0
	v_mov_b32_e32 v79, 0
	v_mov_b32_e32 v80, 0
	v_mov_b32_e32 v81, 0
	v_mov_b32_e32 v82, 0
	v_mov_b32_e32 v83, 0
	v_mov_b32_e32 v84, 0
	v_mov_b32_e32 v85, 0
	v_mov_b32_e32 v86, 0
	v_mov_b32_e32 v87, 0
	v_mov_b32_e32 v88, 0
	v_mov_b32_e32 v89, 0
	v_mov_b32_e32 v90, 0
	v_mov_b32_e32 v91, 0
	v_mov_b32_e32 v92, 0
	v_mov_b32_e32 v93, 0
	v_mov_b32_e32 v94, 0
	v_mov_b32_e32 v95, 0
	v_mov_b32_e32 v96, 0
	v_mov_b32_e32 v97, 0
	v_mov_b32_e32 v98, 0
	v_mov_b32_e32 v99, 0
	v_mov_b32_e32 v100, 0
	v_mov_b32_e32 v101, 0
	v_mov_b32_e32 v102, 0
	v_mov_b32_e32 v103, 0
	v_mov_b32_e32 v104, 0
	v_mov_b32_e32 v105, 0
	v_mov_b32_e32 v106, 0
	v_mov_b32_e32 v107, 0
	v_mov_b32_e32 v108, 0
	v_mov_b32_e32 v109, 0
	v_mov_b32_e32 v110, 0
	v_mov_b32_e32 v111, 0
	v_mov_b32_e32 v112, 0
	v_mov_b32_e32 v113, 0
	v_mov_b32_e32 v114, 0
	v_mov_b32_e32 v115, 0
	v_mov_b32_e32 v116, 0
	v_mov_b32_e32 v117, 0
	v_mov_b32_e32 v118, 0
	v_mov_b32_e32 v119, 0
	v_mov_b32_e32 v120, 0
	v_mov_b32_e32 v121, 0
	v_mov_b32_e32 v122, 0
	v_mov_b32_e32 v123, 0
	v_mov_b32_e32 v124, 0
	v_mov_b32_e32 v125, 0
	v_mov_b32_e32 v126, 0
	v_mov_b32_e32 v127, 0
	s_mov_b32 s8, 0
	s_waitcnt vmcnt(4)
	ds_write_b128 v241, v[160:163]
	ds_write_b128 v241, v[164:167] offset:4096
	ds_write_b128 v241, v[168:171] offset:8192
	ds_write_b128 v241, v[172:175] offset:12288
	s_nop 3
	s_movk_i32 s96, 0x4000
	v_lshl_add_u64 v[174:175], v[188:189], 0, s[96:97]
	global_load_dwordx4 v[168:171], v[174:175], off offset:-2048
	global_load_dwordx4 v[172:175], v[174:175], off offset:2048
	s_movk_i32 s96, 0x800
	v_lshl_add_u64 v[248:249], v[184:185], 0, s[96:97]
	v_lshl_add_u64 v[250:251], v[186:187], 0, s[96:97]
	global_load_dwordx4 v[144:147], v[248:249], off
	global_load_dwordx4 v[148:151], v[248:249], off offset:256
	global_load_dwordx4 v[152:155], v[250:251], off
	global_load_dwordx4 v[156:159], v[250:251], off offset:256
	s_waitcnt lgkmcnt(0)
	s_barrier
	ds_read_b128 v[196:199], v246 offset:0
	ds_read_b128 v[200:203], v246 offset:1024
	ds_read_b128 v[204:207], v246 offset:2048
	ds_read_b128 v[242:245], v246 offset:3072
.Lg16_down_k:
	s_add_i32 s9, s8, 3
	s_min_u32 s10, s9, 87
	s_lshl_b32 s96, s10, 13
	v_lshl_add_u64 v[166:167], v[188:189], 0, s[96:97]
	global_load_dwordx4 v[160:163], v[166:167], off offset:-2048
	global_load_dwordx4 v[164:167], v[166:167], off offset:2048
	s_add_i32 s9, s8, 2
	s_min_u32 s10, s9, 87
	s_lshl_b32 s96, s10, 11
	v_lshl_add_u64 v[248:249], v[184:185], 0, s[96:97]
	v_lshl_add_u64 v[250:251], v[186:187], 0, s[96:97]
	s_waitcnt vmcnt(8) lgkmcnt(3)
	v_mfma_f32_16x16x32_bf16 v[112:115], v[128:131], v[196:199], v[112:115]
	v_mfma_f32_16x16x32_bf16 v[120:123], v[132:135], v[196:199], v[120:123]
	v_mfma_f32_16x16x32_bf16 v[48:51], v[136:139], v[196:199], v[48:51]
	v_mfma_f32_16x16x32_bf16 v[56:59], v[140:143], v[196:199], v[56:59]
	ds_read_b128 v[196:199], v246 offset:4096
	s_waitcnt lgkmcnt(3)
	v_mfma_f32_16x16x32_bf16 v[116:119], v[128:131], v[200:203], v[116:119]
	v_mfma_f32_16x16x32_bf16 v[124:127], v[132:135], v[200:203], v[124:127]
	v_mfma_f32_16x16x32_bf16 v[52:55], v[136:139], v[200:203], v[52:55]
	v_mfma_f32_16x16x32_bf16 v[60:63], v[140:143], v[200:203], v[60:63]
	ds_read_b128 v[200:203], v246 offset:5120
	s_waitcnt lgkmcnt(3)
	v_mfma_f32_16x16x32_bf16 v[96:99], v[128:131], v[204:207], v[96:99]
	v_mfma_f32_16x16x32_bf16 v[104:107], v[132:135], v[204:207], v[104:107]
	v_mfma_f32_16x16x32_bf16 v[32:35], v[136:139], v[204:207], v[32:35]
	v_mfma_f32_16x16x32_bf16 v[40:43], v[140:143], v[204:207], v[40:43]
	ds_read_b128 v[204:207], v246 offset:6144
	s_waitcnt lgkmcnt(3)
	v_mfma_f32_16x16x32_bf16 v[100:103], v[128:131], v[242:245], v[100:103]
	v_mfma_f32_16x16x32_bf16 v[108:111], v[132:135], v[242:245], v[108:111]
	v_mfma_f32_16x16x32_bf16 v[36:39], v[136:139], v[242:245], v[36:39]
	v_mfma_f32_16x16x32_bf16 v[44:47], v[140:143], v[242:245], v[44:47]
	ds_read_b128 v[242:245], v246 offset:7168
	s_waitcnt vmcnt(6)
	ds_write_b128 v241, v[168:171] offset:16384
	ds_write_b128 v241, v[172:175] offset:20480
	s_waitcnt lgkmcnt(5)
	v_mfma_f32_16x16x32_bf16 v[80:83], v[128:131], v[196:199], v[80:83]
	v_mfma_f32_16x16x32_bf16 v[88:91], v[132:135], v[196:199], v[88:91]
	v_mfma_f32_16x16x32_bf16 v[16:19], v[136:139], v[196:199], v[16:19]
	v_mfma_f32_16x16x32_bf16 v[24:27], v[140:143], v[196:199], v[24:27]
	ds_read_b128 v[196:199], v246 offset:8192
	s_waitcnt lgkmcnt(5)
	v_mfma_f32_16x16x32_bf16 v[84:87], v[128:131], v[200:203], v[84:87]
	v_mfma_f32_16x16x32_bf16 v[92:95], v[132:135], v[200:203], v[92:95]
	v_mfma_f32_16x16x32_bf16 v[20:23], v[136:139], v[200:203], v[20:23]
	v_mfma_f32_16x16x32_bf16 v[28:31], v[140:143], v[200:203], v[28:31]
	ds_read_b128 v[200:203], v246 offset:9216
	s_waitcnt lgkmcnt(2)
	s_barrier
	v_mfma_f32_16x16x32_bf16 v[64:67], v[128:131], v[204:207], v[64:67]
	v_mfma_f32_16x16x32_bf16 v[72:75], v[132:135], v[204:207], v[72:75]
	v_mfma_f32_16x16x32_bf16 v[0:3], v[136:139], v[204:207], v[0:3]
	v_mfma_f32_16x16x32_bf16 v[8:11], v[140:143], v[204:207], v[8:11]
	ds_read_b128 v[204:207], v246 offset:10240
	v_mfma_f32_16x16x32_bf16 v[68:71], v[128:131], v[242:245], v[68:71]
	v_mfma_f32_16x16x32_bf16 v[76:79], v[132:135], v[242:245], v[76:79]
	v_mfma_f32_16x16x32_bf16 v[4:7], v[136:139], v[242:245], v[4:7]
	v_mfma_f32_16x16x32_bf16 v[12:15], v[140:143], v[242:245], v[12:15]
	ds_read_b128 v[242:245], v246 offset:11264
	global_load_dwordx4 v[128:131], v[248:249], off
	global_load_dwordx4 v[132:135], v[248:249], off offset:256
	global_load_dwordx4 v[136:139], v[250:251], off
	global_load_dwordx4 v[140:143], v[250:251], off offset:256
	s_add_i32 s9, s8, 4
	s_min_u32 s10, s9, 87
	s_lshl_b32 s96, s10, 13
	v_lshl_add_u64 v[174:175], v[188:189], 0, s[96:97]
	global_load_dwordx4 v[168:171], v[174:175], off offset:-2048
	global_load_dwordx4 v[172:175], v[174:175], off offset:2048
	s_add_i32 s9, s8, 3
	s_min_u32 s10, s9, 87
	s_lshl_b32 s96, s10, 11
	v_lshl_add_u64 v[248:249], v[184:185], 0, s[96:97]
	v_lshl_add_u64 v[250:251], v[186:187], 0, s[96:97]
	s_waitcnt vmcnt(8) lgkmcnt(3)
	v_mfma_f32_16x16x32_bf16 v[112:115], v[144:147], v[196:199], v[112:115]
	v_mfma_f32_16x16x32_bf16 v[120:123], v[148:151], v[196:199], v[120:123]
	v_mfma_f32_16x16x32_bf16 v[48:51], v[152:155], v[196:199], v[48:51]
	v_mfma_f32_16x16x32_bf16 v[56:59], v[156:159], v[196:199], v[56:59]
	ds_read_b128 v[196:199], v246 offset:12288
	s_waitcnt lgkmcnt(3)
	v_mfma_f32_16x16x32_bf16 v[116:119], v[144:147], v[200:203], v[116:119]
	v_mfma_f32_16x16x32_bf16 v[124:127], v[148:151], v[200:203], v[124:127]
	v_mfma_f32_16x16x32_bf16 v[52:55], v[152:155], v[200:203], v[52:55]
	v_mfma_f32_16x16x32_bf16 v[60:63], v[156:159], v[200:203], v[60:63]
	ds_read_b128 v[200:203], v246 offset:13312
	s_waitcnt lgkmcnt(3)
	v_mfma_f32_16x16x32_bf16 v[96:99], v[144:147], v[204:207], v[96:99]
	v_mfma_f32_16x16x32_bf16 v[104:107], v[148:151], v[204:207], v[104:107]
	v_mfma_f32_16x16x32_bf16 v[32:35], v[152:155], v[204:207], v[32:35]
	v_mfma_f32_16x16x32_bf16 v[40:43], v[156:159], v[204:207], v[40:43]
	ds_read_b128 v[204:207], v246 offset:14336
	s_waitcnt lgkmcnt(3)
	v_mfma_f32_16x16x32_bf16 v[100:103], v[144:147], v[242:245], v[100:103]
	v_mfma_f32_16x16x32_bf16 v[108:111], v[148:151], v[242:245], v[108:111]
	v_mfma_f32_16x16x32_bf16 v[36:39], v[152:155], v[242:245], v[36:39]
	v_mfma_f32_16x16x32_bf16 v[44:47], v[156:159], v[242:245], v[44:47]
	ds_read_b128 v[242:245], v246 offset:15360
	s_waitcnt vmcnt(6)
	ds_write_b128 v241, v[160:163] offset:0
	ds_write_b128 v241, v[164:167] offset:4096
	s_waitcnt lgkmcnt(5)
	v_mfma_f32_16x16x32_bf16 v[80:83], v[144:147], v[196:199], v[80:83]
	v_mfma_f32_16x16x32_bf16 v[88:91], v[148:151], v[196:199], v[88:91]
	v_mfma_f32_16x16x32_bf16 v[16:19], v[152:155], v[196:199], v[16:19]
	v_mfma_f32_16x16x32_bf16 v[24:27], v[156:159], v[196:199], v[24:27]
	ds_read_b128 v[196:199], v246 offset:16384
	s_waitcnt lgkmcnt(5)
	v_mfma_f32_16x16x32_bf16 v[84:87], v[144:147], v[200:203], v[84:87]
	v_mfma_f32_16x16x32_bf16 v[92:95], v[148:151], v[200:203], v[92:95]
	v_mfma_f32_16x16x32_bf16 v[20:23], v[152:155], v[200:203], v[20:23]
	v_mfma_f32_16x16x32_bf16 v[28:31], v[156:159], v[200:203], v[28:31]
	ds_read_b128 v[200:203], v246 offset:17408
	s_waitcnt lgkmcnt(2)
	s_barrier
	v_mfma_f32_16x16x32_bf16 v[64:67], v[144:147], v[204:207], v[64:67]
	v_mfma_f32_16x16x32_bf16 v[72:75], v[148:151], v[204:207], v[72:75]
	v_mfma_f32_16x16x32_bf16 v[0:3], v[152:155], v[204:207], v[0:3]
	v_mfma_f32_16x16x32_bf16 v[8:11], v[156:159], v[204:207], v[8:11]
	ds_read_b128 v[204:207], v246 offset:18432
	v_mfma_f32_16x16x32_bf16 v[68:71], v[144:147], v[242:245], v[68:71]
	v_mfma_f32_16x16x32_bf16 v[76:79], v[148:151], v[242:245], v[76:79]
	v_mfma_f32_16x16x32_bf16 v[4:7], v[152:155], v[242:245], v[4:7]
	v_mfma_f32_16x16x32_bf16 v[12:15], v[156:159], v[242:245], v[12:15]
	ds_read_b128 v[242:245], v246 offset:19456
	global_load_dwordx4 v[144:147], v[248:249], off
	global_load_dwordx4 v[148:151], v[248:249], off offset:256
	global_load_dwordx4 v[152:155], v[250:251], off
	global_load_dwordx4 v[156:159], v[250:251], off offset:256
	s_add_i32 s9, s8, 5
	s_min_u32 s10, s9, 87
	s_lshl_b32 s96, s10, 13
	v_lshl_add_u64 v[166:167], v[188:189], 0, s[96:97]
	global_load_dwordx4 v[160:163], v[166:167], off offset:-2048
	global_load_dwordx4 v[164:167], v[166:167], off offset:2048
	s_add_i32 s9, s8, 4
	s_min_u32 s10, s9, 87
	s_lshl_b32 s96, s10, 11
	v_lshl_add_u64 v[248:249], v[184:185], 0, s[96:97]
	v_lshl_add_u64 v[250:251], v[186:187], 0, s[96:97]
	s_waitcnt vmcnt(8) lgkmcnt(3)
	v_mfma_f32_16x16x32_bf16 v[112:115], v[128:131], v[196:199], v[112:115]
	v_mfma_f32_16x16x32_bf16 v[120:123], v[132:135], v[196:199], v[120:123]
	v_mfma_f32_16x16x32_bf16 v[48:51], v[136:139], v[196:199], v[48:51]
	v_mfma_f32_16x16x32_bf16 v[56:59], v[140:143], v[196:199], v[56:59]
	ds_read_b128 v[196:199], v246 offset:20480
	s_waitcnt lgkmcnt(3)
	v_mfma_f32_16x16x32_bf16 v[116:119], v[128:131], v[200:203], v[116:119]
	v_mfma_f32_16x16x32_bf16 v[124:127], v[132:135], v[200:203], v[124:127]
	v_mfma_f32_16x16x32_bf16 v[52:55], v[136:139], v[200:203], v[52:55]
	v_mfma_f32_16x16x32_bf16 v[60:63], v[140:143], v[200:203], v[60:63]
	ds_read_b128 v[200:203], v246 offset:21504
	s_waitcnt lgkmcnt(3)
	v_mfma_f32_16x16x32_bf16 v[96:99], v[128:131], v[204:207], v[96:99]
	v_mfma_f32_16x16x32_bf16 v[104:107], v[132:135], v[204:207], v[104:107]
	v_mfma_f32_16x16x32_bf16 v[32:35], v[136:139], v[204:207], v[32:35]
	v_mfma_f32_16x16x32_bf16 v[40:43], v[140:143], v[204:207], v[40:43]
	ds_read_b128 v[204:207], v246 offset:22528
	s_waitcnt lgkmcnt(3)
	v_mfma_f32_16x16x32_bf16 v[100:103], v[128:131], v[242:245], v[100:103]
	v_mfma_f32_16x16x32_bf16 v[108:111], v[132:135], v[242:245], v[108:111]
	v_mfma_f32_16x16x32_bf16 v[36:39], v[136:139], v[242:245], v[36:39]
	v_mfma_f32_16x16x32_bf16 v[44:47], v[140:143], v[242:245], v[44:47]
	ds_read_b128 v[242:245], v246 offset:23552
	s_waitcnt vmcnt(6)
	ds_write_b128 v241, v[168:171] offset:8192
	ds_write_b128 v241, v[172:175] offset:12288
	s_waitcnt lgkmcnt(5)
	v_mfma_f32_16x16x32_bf16 v[80:83], v[128:131], v[196:199], v[80:83]
	v_mfma_f32_16x16x32_bf16 v[88:91], v[132:135], v[196:199], v[88:91]
	v_mfma_f32_16x16x32_bf16 v[16:19], v[136:139], v[196:199], v[16:19]
	v_mfma_f32_16x16x32_bf16 v[24:27], v[140:143], v[196:199], v[24:27]
	ds_read_b128 v[196:199], v246 offset:0
	s_waitcnt lgkmcnt(5)
	v_mfma_f32_16x16x32_bf16 v[84:87], v[128:131], v[200:203], v[84:87]
	v_mfma_f32_16x16x32_bf16 v[92:95], v[132:135], v[200:203], v[92:95]
	v_mfma_f32_16x16x32_bf16 v[20:23], v[136:139], v[200:203], v[20:23]
	v_mfma_f32_16x16x32_bf16 v[28:31], v[140:143], v[200:203], v[28:31]
	ds_read_b128 v[200:203], v246 offset:1024
	s_waitcnt lgkmcnt(2)
	s_barrier
	v_mfma_f32_16x16x32_bf16 v[64:67], v[128:131], v[204:207], v[64:67]
	v_mfma_f32_16x16x32_bf16 v[72:75], v[132:135], v[204:207], v[72:75]
	v_mfma_f32_16x16x32_bf16 v[0:3], v[136:139], v[204:207], v[0:3]
	v_mfma_f32_16x16x32_bf16 v[8:11], v[140:143], v[204:207], v[8:11]
	ds_read_b128 v[204:207], v246 offset:2048
	v_mfma_f32_16x16x32_bf16 v[68:71], v[128:131], v[242:245], v[68:71]
	v_mfma_f32_16x16x32_bf16 v[76:79], v[132:135], v[242:245], v[76:79]
	v_mfma_f32_16x16x32_bf16 v[4:7], v[136:139], v[242:245], v[4:7]
	v_mfma_f32_16x16x32_bf16 v[12:15], v[140:143], v[242:245], v[12:15]
	ds_read_b128 v[242:245], v246 offset:3072
	global_load_dwordx4 v[128:131], v[248:249], off
	global_load_dwordx4 v[132:135], v[248:249], off offset:256
	global_load_dwordx4 v[136:139], v[250:251], off
	global_load_dwordx4 v[140:143], v[250:251], off offset:256
	s_add_i32 s9, s8, 6
	s_min_u32 s10, s9, 87
	s_lshl_b32 s96, s10, 13
	v_lshl_add_u64 v[174:175], v[188:189], 0, s[96:97]
	global_load_dwordx4 v[168:171], v[174:175], off offset:-2048
	global_load_dwordx4 v[172:175], v[174:175], off offset:2048
	s_add_i32 s9, s8, 5
	s_min_u32 s10, s9, 87
	s_lshl_b32 s96, s10, 11
	v_lshl_add_u64 v[248:249], v[184:185], 0, s[96:97]
	v_lshl_add_u64 v[250:251], v[186:187], 0, s[96:97]
	s_waitcnt vmcnt(8) lgkmcnt(3)
	v_mfma_f32_16x16x32_bf16 v[112:115], v[144:147], v[196:199], v[112:115]
	v_mfma_f32_16x16x32_bf16 v[120:123], v[148:151], v[196:199], v[120:123]
	v_mfma_f32_16x16x32_bf16 v[48:51], v[152:155], v[196:199], v[48:51]
	v_mfma_f32_16x16x32_bf16 v[56:59], v[156:159], v[196:199], v[56:59]
	ds_read_b128 v[196:199], v246 offset:4096
	s_waitcnt lgkmcnt(3)
	v_mfma_f32_16x16x32_bf16 v[116:119], v[144:147], v[200:203], v[116:119]
	v_mfma_f32_16x16x32_bf16 v[124:127], v[148:151], v[200:203], v[124:127]
	v_mfma_f32_16x16x32_bf16 v[52:55], v[152:155], v[200:203], v[52:55]
	v_mfma_f32_16x16x32_bf16 v[60:63], v[156:159], v[200:203], v[60:63]
	ds_read_b128 v[200:203], v246 offset:5120
	s_waitcnt lgkmcnt(3)
	v_mfma_f32_16x16x32_bf16 v[96:99], v[144:147], v[204:207], v[96:99]
	v_mfma_f32_16x16x32_bf16 v[104:107], v[148:151], v[204:207], v[104:107]
	v_mfma_f32_16x16x32_bf16 v[32:35], v[152:155], v[204:207], v[32:35]
	v_mfma_f32_16x16x32_bf16 v[40:43], v[156:159], v[204:207], v[40:43]
	ds_read_b128 v[204:207], v246 offset:6144
	s_waitcnt lgkmcnt(3)
	v_mfma_f32_16x16x32_bf16 v[100:103], v[144:147], v[242:245], v[100:103]
	v_mfma_f32_16x16x32_bf16 v[108:111], v[148:151], v[242:245], v[108:111]
	v_mfma_f32_16x16x32_bf16 v[36:39], v[152:155], v[242:245], v[36:39]
	v_mfma_f32_16x16x32_bf16 v[44:47], v[156:159], v[242:245], v[44:47]
	ds_read_b128 v[242:245], v246 offset:7168
	s_waitcnt vmcnt(6)
	ds_write_b128 v241, v[160:163] offset:16384
	ds_write_b128 v241, v[164:167] offset:20480
	s_waitcnt lgkmcnt(5)
	v_mfma_f32_16x16x32_bf16 v[80:83], v[144:147], v[196:199], v[80:83]
	v_mfma_f32_16x16x32_bf16 v[88:91], v[148:151], v[196:199], v[88:91]
	v_mfma_f32_16x16x32_bf16 v[16:19], v[152:155], v[196:199], v[16:19]
	v_mfma_f32_16x16x32_bf16 v[24:27], v[156:159], v[196:199], v[24:27]
	ds_read_b128 v[196:199], v246 offset:8192
	s_waitcnt lgkmcnt(5)
	v_mfma_f32_16x16x32_bf16 v[84:87], v[144:147], v[200:203], v[84:87]
	v_mfma_f32_16x16x32_bf16 v[92:95], v[148:151], v[200:203], v[92:95]
	v_mfma_f32_16x16x32_bf16 v[20:23], v[152:155], v[200:203], v[20:23]
	v_mfma_f32_16x16x32_bf16 v[28:31], v[156:159], v[200:203], v[28:31]
	ds_read_b128 v[200:203], v246 offset:9216
	s_waitcnt lgkmcnt(2)
	s_barrier
	v_mfma_f32_16x16x32_bf16 v[64:67], v[144:147], v[204:207], v[64:67]
	v_mfma_f32_16x16x32_bf16 v[72:75], v[148:151], v[204:207], v[72:75]
	v_mfma_f32_16x16x32_bf16 v[0:3], v[152:155], v[204:207], v[0:3]
	v_mfma_f32_16x16x32_bf16 v[8:11], v[156:159], v[204:207], v[8:11]
	ds_read_b128 v[204:207], v246 offset:10240
	v_mfma_f32_16x16x32_bf16 v[68:71], v[144:147], v[242:245], v[68:71]
	v_mfma_f32_16x16x32_bf16 v[76:79], v[148:151], v[242:245], v[76:79]
	v_mfma_f32_16x16x32_bf16 v[4:7], v[152:155], v[242:245], v[4:7]
	v_mfma_f32_16x16x32_bf16 v[12:15], v[156:159], v[242:245], v[12:15]
	ds_read_b128 v[242:245], v246 offset:11264
	global_load_dwordx4 v[144:147], v[248:249], off
	global_load_dwordx4 v[148:151], v[248:249], off offset:256
	global_load_dwordx4 v[152:155], v[250:251], off
	global_load_dwordx4 v[156:159], v[250:251], off offset:256
	s_add_i32 s9, s8, 7
	s_min_u32 s10, s9, 87
	s_lshl_b32 s96, s10, 13
	v_lshl_add_u64 v[166:167], v[188:189], 0, s[96:97]
	global_load_dwordx4 v[160:163], v[166:167], off offset:-2048
	global_load_dwordx4 v[164:167], v[166:167], off offset:2048
	s_add_i32 s9, s8, 6
	s_min_u32 s10, s9, 87
	s_lshl_b32 s96, s10, 11
	v_lshl_add_u64 v[248:249], v[184:185], 0, s[96:97]
	v_lshl_add_u64 v[250:251], v[186:187], 0, s[96:97]
	s_waitcnt vmcnt(8) lgkmcnt(3)
	v_mfma_f32_16x16x32_bf16 v[112:115], v[128:131], v[196:199], v[112:115]
	v_mfma_f32_16x16x32_bf16 v[120:123], v[132:135], v[196:199], v[120:123]
	v_mfma_f32_16x16x32_bf16 v[48:51], v[136:139], v[196:199], v[48:51]
	v_mfma_f32_16x16x32_bf16 v[56:59], v[140:143], v[196:199], v[56:59]
	ds_read_b128 v[196:199], v246 offset:12288
	s_waitcnt lgkmcnt(3)
	v_mfma_f32_16x16x32_bf16 v[116:119], v[128:131], v[200:203], v[116:119]
	v_mfma_f32_16x16x32_bf16 v[124:127], v[132:135], v[200:203], v[124:127]
	v_mfma_f32_16x16x32_bf16 v[52:55], v[136:139], v[200:203], v[52:55]
	v_mfma_f32_16x16x32_bf16 v[60:63], v[140:143], v[200:203], v[60:63]
	ds_read_b128 v[200:203], v246 offset:13312
	s_waitcnt lgkmcnt(3)
	v_mfma_f32_16x16x32_bf16 v[96:99], v[128:131], v[204:207], v[96:99]
	v_mfma_f32_16x16x32_bf16 v[104:107], v[132:135], v[204:207], v[104:107]
	v_mfma_f32_16x16x32_bf16 v[32:35], v[136:139], v[204:207], v[32:35]
	v_mfma_f32_16x16x32_bf16 v[40:43], v[140:143], v[204:207], v[40:43]
	ds_read_b128 v[204:207], v246 offset:14336
	s_waitcnt lgkmcnt(3)
	v_mfma_f32_16x16x32_bf16 v[100:103], v[128:131], v[242:245], v[100:103]
	v_mfma_f32_16x16x32_bf16 v[108:111], v[132:135], v[242:245], v[108:111]
	v_mfma_f32_16x16x32_bf16 v[36:39], v[136:139], v[242:245], v[36:39]
	v_mfma_f32_16x16x32_bf16 v[44:47], v[140:143], v[242:245], v[44:47]
	ds_read_b128 v[242:245], v246 offset:15360
	s_waitcnt vmcnt(6)
	ds_write_b128 v241, v[168:171] offset:0
	ds_write_b128 v241, v[172:175] offset:4096
	s_waitcnt lgkmcnt(5)
	v_mfma_f32_16x16x32_bf16 v[80:83], v[128:131], v[196:199], v[80:83]
	v_mfma_f32_16x16x32_bf16 v[88:91], v[132:135], v[196:199], v[88:91]
	v_mfma_f32_16x16x32_bf16 v[16:19], v[136:139], v[196:199], v[16:19]
	v_mfma_f32_16x16x32_bf16 v[24:27], v[140:143], v[196:199], v[24:27]
	ds_read_b128 v[196:199], v246 offset:16384
	s_waitcnt lgkmcnt(5)
	v_mfma_f32_16x16x32_bf16 v[84:87], v[128:131], v[200:203], v[84:87]
	v_mfma_f32_16x16x32_bf16 v[92:95], v[132:135], v[200:203], v[92:95]
	v_mfma_f32_16x16x32_bf16 v[20:23], v[136:139], v[200:203], v[20:23]
	v_mfma_f32_16x16x32_bf16 v[28:31], v[140:143], v[200:203], v[28:31]
	ds_read_b128 v[200:203], v246 offset:17408
	s_waitcnt lgkmcnt(2)
	s_barrier
	v_mfma_f32_16x16x32_bf16 v[64:67], v[128:131], v[204:207], v[64:67]
	v_mfma_f32_16x16x32_bf16 v[72:75], v[132:135], v[204:207], v[72:75]
	v_mfma_f32_16x16x32_bf16 v[0:3], v[136:139], v[204:207], v[0:3]
	v_mfma_f32_16x16x32_bf16 v[8:11], v[140:143], v[204:207], v[8:11]
	ds_read_b128 v[204:207], v246 offset:18432
	v_mfma_f32_16x16x32_bf16 v[68:71], v[128:131], v[242:245], v[68:71]
	v_mfma_f32_16x16x32_bf16 v[76:79], v[132:135], v[242:245], v[76:79]
	v_mfma_f32_16x16x32_bf16 v[4:7], v[136:139], v[242:245], v[4:7]
	v_mfma_f32_16x16x32_bf16 v[12:15], v[140:143], v[242:245], v[12:15]
	ds_read_b128 v[242:245], v246 offset:19456
	global_load_dwordx4 v[128:131], v[248:249], off
	global_load_dwordx4 v[132:135], v[248:249], off offset:256
	global_load_dwordx4 v[136:139], v[250:251], off
	global_load_dwordx4 v[140:143], v[250:251], off offset:256
	s_add_i32 s9, s8, 8
	s_min_u32 s10, s9, 87
	s_lshl_b32 s96, s10, 13
	v_lshl_add_u64 v[174:175], v[188:189], 0, s[96:97]
	global_load_dwordx4 v[168:171], v[174:175], off offset:-2048
	global_load_dwordx4 v[172:175], v[174:175], off offset:2048
	s_add_i32 s9, s8, 7
	s_min_u32 s10, s9, 87
	s_lshl_b32 s96, s10, 11
	v_lshl_add_u64 v[248:249], v[184:185], 0, s[96:97]
	v_lshl_add_u64 v[250:251], v[186:187], 0, s[96:97]
	s_waitcnt vmcnt(8) lgkmcnt(3)
	v_mfma_f32_16x16x32_bf16 v[112:115], v[144:147], v[196:199], v[112:115]
	v_mfma_f32_16x16x32_bf16 v[120:123], v[148:151], v[196:199], v[120:123]
	v_mfma_f32_16x16x32_bf16 v[48:51], v[152:155], v[196:199], v[48:51]
	v_mfma_f32_16x16x32_bf16 v[56:59], v[156:159], v[196:199], v[56:59]
	ds_read_b128 v[196:199], v246 offset:20480
	s_waitcnt lgkmcnt(3)
	v_mfma_f32_16x16x32_bf16 v[116:119], v[144:147], v[200:203], v[116:119]
	v_mfma_f32_16x16x32_bf16 v[124:127], v[148:151], v[200:203], v[124:127]
	v_mfma_f32_16x16x32_bf16 v[52:55], v[152:155], v[200:203], v[52:55]
	v_mfma_f32_16x16x32_bf16 v[60:63], v[156:159], v[200:203], v[60:63]
	ds_read_b128 v[200:203], v246 offset:21504
	s_waitcnt lgkmcnt(3)
	v_mfma_f32_16x16x32_bf16 v[96:99], v[144:147], v[204:207], v[96:99]
	v_mfma_f32_16x16x32_bf16 v[104:107], v[148:151], v[204:207], v[104:107]
	v_mfma_f32_16x16x32_bf16 v[32:35], v[152:155], v[204:207], v[32:35]
	v_mfma_f32_16x16x32_bf16 v[40:43], v[156:159], v[204:207], v[40:43]
	ds_read_b128 v[204:207], v246 offset:22528
	s_waitcnt lgkmcnt(3)
	v_mfma_f32_16x16x32_bf16 v[100:103], v[144:147], v[242:245], v[100:103]
	v_mfma_f32_16x16x32_bf16 v[108:111], v[148:151], v[242:245], v[108:111]
	v_mfma_f32_16x16x32_bf16 v[36:39], v[152:155], v[242:245], v[36:39]
	v_mfma_f32_16x16x32_bf16 v[44:47], v[156:159], v[242:245], v[44:47]
	ds_read_b128 v[242:245], v246 offset:23552
	s_waitcnt vmcnt(6)
	ds_write_b128 v241, v[160:163] offset:8192
	ds_write_b128 v241, v[164:167] offset:12288
	s_waitcnt lgkmcnt(5)
	v_mfma_f32_16x16x32_bf16 v[80:83], v[144:147], v[196:199], v[80:83]
	v_mfma_f32_16x16x32_bf16 v[88:91], v[148:151], v[196:199], v[88:91]
	v_mfma_f32_16x16x32_bf16 v[16:19], v[152:155], v[196:199], v[16:19]
	v_mfma_f32_16x16x32_bf16 v[24:27], v[156:159], v[196:199], v[24:27]
	ds_read_b128 v[196:199], v246 offset:0
	s_waitcnt lgkmcnt(5)
	v_mfma_f32_16x16x32_bf16 v[84:87], v[144:147], v[200:203], v[84:87]
	v_mfma_f32_16x16x32_bf16 v[92:95], v[148:151], v[200:203], v[92:95]
	v_mfma_f32_16x16x32_bf16 v[20:23], v[152:155], v[200:203], v[20:23]
	v_mfma_f32_16x16x32_bf16 v[28:31], v[156:159], v[200:203], v[28:31]
	ds_read_b128 v[200:203], v246 offset:1024
	s_waitcnt lgkmcnt(2)
	s_barrier
	v_mfma_f32_16x16x32_bf16 v[64:67], v[144:147], v[204:207], v[64:67]
	v_mfma_f32_16x16x32_bf16 v[72:75], v[148:151], v[204:207], v[72:75]
	v_mfma_f32_16x16x32_bf16 v[0:3], v[152:155], v[204:207], v[0:3]
	v_mfma_f32_16x16x32_bf16 v[8:11], v[156:159], v[204:207], v[8:11]
	ds_read_b128 v[204:207], v246 offset:2048
	v_mfma_f32_16x16x32_bf16 v[68:71], v[144:147], v[242:245], v[68:71]
	v_mfma_f32_16x16x32_bf16 v[76:79], v[148:151], v[242:245], v[76:79]
	v_mfma_f32_16x16x32_bf16 v[4:7], v[152:155], v[242:245], v[4:7]
	v_mfma_f32_16x16x32_bf16 v[12:15], v[156:159], v[242:245], v[12:15]
	ds_read_b128 v[242:245], v246 offset:3072
	global_load_dwordx4 v[144:147], v[248:249], off
	global_load_dwordx4 v[148:151], v[248:249], off offset:256
	global_load_dwordx4 v[152:155], v[250:251], off
	global_load_dwordx4 v[156:159], v[250:251], off offset:256
	s_add_i32 s8, s8, 6
	s_cmp_lt_u32 s8, 84
	s_cbranch_scc1 .Lg16_down_k
	s_add_i32 s9, s8, 3
	s_min_u32 s10, s9, 87
	s_lshl_b32 s96, s10, 13
	v_lshl_add_u64 v[166:167], v[188:189], 0, s[96:97]
	global_load_dwordx4 v[160:163], v[166:167], off offset:-2048
	global_load_dwordx4 v[164:167], v[166:167], off offset:2048
	s_add_i32 s9, s8, 2
	s_min_u32 s10, s9, 87
	s_lshl_b32 s96, s10, 11
	v_lshl_add_u64 v[248:249], v[184:185], 0, s[96:97]
	v_lshl_add_u64 v[250:251], v[186:187], 0, s[96:97]
	s_waitcnt vmcnt(8) lgkmcnt(3)
	v_mfma_f32_16x16x32_bf16 v[112:115], v[128:131], v[196:199], v[112:115]
	v_mfma_f32_16x16x32_bf16 v[120:123], v[132:135], v[196:199], v[120:123]
	v_mfma_f32_16x16x32_bf16 v[48:51], v[136:139], v[196:199], v[48:51]
	v_mfma_f32_16x16x32_bf16 v[56:59], v[140:143], v[196:199], v[56:59]
	ds_read_b128 v[196:199], v246 offset:4096
	s_waitcnt lgkmcnt(3)
	v_mfma_f32_16x16x32_bf16 v[116:119], v[128:131], v[200:203], v[116:119]
	v_mfma_f32_16x16x32_bf16 v[124:127], v[132:135], v[200:203], v[124:127]
	v_mfma_f32_16x16x32_bf16 v[52:55], v[136:139], v[200:203], v[52:55]
	v_mfma_f32_16x16x32_bf16 v[60:63], v[140:143], v[200:203], v[60:63]
	ds_read_b128 v[200:203], v246 offset:5120
	s_waitcnt lgkmcnt(3)
	v_mfma_f32_16x16x32_bf16 v[96:99], v[128:131], v[204:207], v[96:99]
	v_mfma_f32_16x16x32_bf16 v[104:107], v[132:135], v[204:207], v[104:107]
	v_mfma_f32_16x16x32_bf16 v[32:35], v[136:139], v[204:207], v[32:35]
	v_mfma_f32_16x16x32_bf16 v[40:43], v[140:143], v[204:207], v[40:43]
	ds_read_b128 v[204:207], v246 offset:6144
	s_waitcnt lgkmcnt(3)
	v_mfma_f32_16x16x32_bf16 v[100:103], v[128:131], v[242:245], v[100:103]
	v_mfma_f32_16x16x32_bf16 v[108:111], v[132:135], v[242:245], v[108:111]
	v_mfma_f32_16x16x32_bf16 v[36:39], v[136:139], v[242:245], v[36:39]
	v_mfma_f32_16x16x32_bf16 v[44:47], v[140:143], v[242:245], v[44:47]
	ds_read_b128 v[242:245], v246 offset:7168
	s_waitcnt vmcnt(6)
	ds_write_b128 v241, v[168:171] offset:16384
	ds_write_b128 v241, v[172:175] offset:20480
	s_waitcnt lgkmcnt(5)
	v_mfma_f32_16x16x32_bf16 v[80:83], v[128:131], v[196:199], v[80:83]
	v_mfma_f32_16x16x32_bf16 v[88:91], v[132:135], v[196:199], v[88:91]
	v_mfma_f32_16x16x32_bf16 v[16:19], v[136:139], v[196:199], v[16:19]
	v_mfma_f32_16x16x32_bf16 v[24:27], v[140:143], v[196:199], v[24:27]
	ds_read_b128 v[196:199], v246 offset:8192
	s_waitcnt lgkmcnt(5)
	v_mfma_f32_16x16x32_bf16 v[84:87], v[128:131], v[200:203], v[84:87]
	v_mfma_f32_16x16x32_bf16 v[92:95], v[132:135], v[200:203], v[92:95]
	v_mfma_f32_16x16x32_bf16 v[20:23], v[136:139], v[200:203], v[20:23]
	v_mfma_f32_16x16x32_bf16 v[28:31], v[140:143], v[200:203], v[28:31]
	ds_read_b128 v[200:203], v246 offset:9216
	s_waitcnt lgkmcnt(2)
	s_barrier
	v_mfma_f32_16x16x32_bf16 v[64:67], v[128:131], v[204:207], v[64:67]
	v_mfma_f32_16x16x32_bf16 v[72:75], v[132:135], v[204:207], v[72:75]
	v_mfma_f32_16x16x32_bf16 v[0:3], v[136:139], v[204:207], v[0:3]
	v_mfma_f32_16x16x32_bf16 v[8:11], v[140:143], v[204:207], v[8:11]
	ds_read_b128 v[204:207], v246 offset:10240
	v_mfma_f32_16x16x32_bf16 v[68:71], v[128:131], v[242:245], v[68:71]
	v_mfma_f32_16x16x32_bf16 v[76:79], v[132:135], v[242:245], v[76:79]
	v_mfma_f32_16x16x32_bf16 v[4:7], v[136:139], v[242:245], v[4:7]
	v_mfma_f32_16x16x32_bf16 v[12:15], v[140:143], v[242:245], v[12:15]
	ds_read_b128 v[242:245], v246 offset:11264
	global_load_dwordx4 v[128:131], v[248:249], off
	global_load_dwordx4 v[132:135], v[248:249], off offset:256
	global_load_dwordx4 v[136:139], v[250:251], off
	global_load_dwordx4 v[140:143], v[250:251], off offset:256
	s_add_i32 s9, s8, 4
	s_min_u32 s10, s9, 87
	s_lshl_b32 s96, s10, 13
	v_lshl_add_u64 v[174:175], v[188:189], 0, s[96:97]
	global_load_dwordx4 v[168:171], v[174:175], off offset:-2048
	global_load_dwordx4 v[172:175], v[174:175], off offset:2048
	s_add_i32 s9, s8, 3
	s_min_u32 s10, s9, 87
	s_lshl_b32 s96, s10, 11
	v_lshl_add_u64 v[248:249], v[184:185], 0, s[96:97]
	v_lshl_add_u64 v[250:251], v[186:187], 0, s[96:97]
	s_waitcnt vmcnt(8) lgkmcnt(3)
	v_mfma_f32_16x16x32_bf16 v[112:115], v[144:147], v[196:199], v[112:115]
	v_mfma_f32_16x16x32_bf16 v[120:123], v[148:151], v[196:199], v[120:123]
	v_mfma_f32_16x16x32_bf16 v[48:51], v[152:155], v[196:199], v[48:51]
	v_mfma_f32_16x16x32_bf16 v[56:59], v[156:159], v[196:199], v[56:59]
	ds_read_b128 v[196:199], v246 offset:12288
	s_waitcnt lgkmcnt(3)
	v_mfma_f32_16x16x32_bf16 v[116:119], v[144:147], v[200:203], v[116:119]
	v_mfma_f32_16x16x32_bf16 v[124:127], v[148:151], v[200:203], v[124:127]
	v_mfma_f32_16x16x32_bf16 v[52:55], v[152:155], v[200:203], v[52:55]
	v_mfma_f32_16x16x32_bf16 v[60:63], v[156:159], v[200:203], v[60:63]
	ds_read_b128 v[200:203], v246 offset:13312
	s_waitcnt lgkmcnt(3)
	v_mfma_f32_16x16x32_bf16 v[96:99], v[144:147], v[204:207], v[96:99]
	v_mfma_f32_16x16x32_bf16 v[104:107], v[148:151], v[204:207], v[104:107]
	v_mfma_f32_16x16x32_bf16 v[32:35], v[152:155], v[204:207], v[32:35]
	v_mfma_f32_16x16x32_bf16 v[40:43], v[156:159], v[204:207], v[40:43]
	ds_read_b128 v[204:207], v246 offset:14336
	s_waitcnt lgkmcnt(3)
	v_mfma_f32_16x16x32_bf16 v[100:103], v[144:147], v[242:245], v[100:103]
	v_mfma_f32_16x16x32_bf16 v[108:111], v[148:151], v[242:245], v[108:111]
	v_mfma_f32_16x16x32_bf16 v[36:39], v[152:155], v[242:245], v[36:39]
	v_mfma_f32_16x16x32_bf16 v[44:47], v[156:159], v[242:245], v[44:47]
	ds_read_b128 v[242:245], v246 offset:15360
	s_waitcnt vmcnt(6)
	ds_write_b128 v241, v[160:163] offset:0
	ds_write_b128 v241, v[164:167] offset:4096
	s_waitcnt lgkmcnt(5)
	v_mfma_f32_16x16x32_bf16 v[80:83], v[144:147], v[196:199], v[80:83]
	v_mfma_f32_16x16x32_bf16 v[88:91], v[148:151], v[196:199], v[88:91]
	v_mfma_f32_16x16x32_bf16 v[16:19], v[152:155], v[196:199], v[16:19]
	v_mfma_f32_16x16x32_bf16 v[24:27], v[156:159], v[196:199], v[24:27]
	ds_read_b128 v[196:199], v246 offset:16384
	s_waitcnt lgkmcnt(5)
	v_mfma_f32_16x16x32_bf16 v[84:87], v[144:147], v[200:203], v[84:87]
	v_mfma_f32_16x16x32_bf16 v[92:95], v[148:151], v[200:203], v[92:95]
	v_mfma_f32_16x16x32_bf16 v[20:23], v[152:155], v[200:203], v[20:23]
	v_mfma_f32_16x16x32_bf16 v[28:31], v[156:159], v[200:203], v[28:31]
	ds_read_b128 v[200:203], v246 offset:17408
	s_waitcnt lgkmcnt(2)
	s_barrier
	v_mfma_f32_16x16x32_bf16 v[64:67], v[144:147], v[204:207], v[64:67]
	v_mfma_f32_16x16x32_bf16 v[72:75], v[148:151], v[204:207], v[72:75]
	v_mfma_f32_16x16x32_bf16 v[0:3], v[152:155], v[204:207], v[0:3]
	v_mfma_f32_16x16x32_bf16 v[8:11], v[156:159], v[204:207], v[8:11]
	ds_read_b128 v[204:207], v246 offset:18432
	v_mfma_f32_16x16x32_bf16 v[68:71], v[144:147], v[242:245], v[68:71]
	v_mfma_f32_16x16x32_bf16 v[76:79], v[148:151], v[242:245], v[76:79]
	v_mfma_f32_16x16x32_bf16 v[4:7], v[152:155], v[242:245], v[4:7]
	v_mfma_f32_16x16x32_bf16 v[12:15], v[156:159], v[242:245], v[12:15]
	ds_read_b128 v[242:245], v246 offset:19456
	global_load_dwordx4 v[144:147], v[248:249], off
	global_load_dwordx4 v[148:151], v[248:249], off offset:256
	global_load_dwordx4 v[152:155], v[250:251], off
	global_load_dwordx4 v[156:159], v[250:251], off offset:256
	s_add_i32 s9, s8, 5
	s_min_u32 s10, s9, 87
	s_lshl_b32 s96, s10, 13
	v_lshl_add_u64 v[166:167], v[188:189], 0, s[96:97]
	global_load_dwordx4 v[160:163], v[166:167], off offset:-2048
	global_load_dwordx4 v[164:167], v[166:167], off offset:2048
	s_add_i32 s9, s8, 4
	s_min_u32 s10, s9, 87
	s_lshl_b32 s96, s10, 11
	v_lshl_add_u64 v[248:249], v[184:185], 0, s[96:97]
	v_lshl_add_u64 v[250:251], v[186:187], 0, s[96:97]
	s_waitcnt vmcnt(8) lgkmcnt(3)
	v_mfma_f32_16x16x32_bf16 v[112:115], v[128:131], v[196:199], v[112:115]
	v_mfma_f32_16x16x32_bf16 v[120:123], v[132:135], v[196:199], v[120:123]
	v_mfma_f32_16x16x32_bf16 v[48:51], v[136:139], v[196:199], v[48:51]
	v_mfma_f32_16x16x32_bf16 v[56:59], v[140:143], v[196:199], v[56:59]
	ds_read_b128 v[196:199], v246 offset:20480
	s_waitcnt lgkmcnt(3)
	v_mfma_f32_16x16x32_bf16 v[116:119], v[128:131], v[200:203], v[116:119]
	v_mfma_f32_16x16x32_bf16 v[124:127], v[132:135], v[200:203], v[124:127]
	v_mfma_f32_16x16x32_bf16 v[52:55], v[136:139], v[200:203], v[52:55]
	v_mfma_f32_16x16x32_bf16 v[60:63], v[140:143], v[200:203], v[60:63]
	ds_read_b128 v[200:203], v246 offset:21504
	s_waitcnt lgkmcnt(3)
	v_mfma_f32_16x16x32_bf16 v[96:99], v[128:131], v[204:207], v[96:99]
	v_mfma_f32_16x16x32_bf16 v[104:107], v[132:135], v[204:207], v[104:107]
	v_mfma_f32_16x16x32_bf16 v[32:35], v[136:139], v[204:207], v[32:35]
	v_mfma_f32_16x16x32_bf16 v[40:43], v[140:143], v[204:207], v[40:43]
	ds_read_b128 v[204:207], v246 offset:22528
	s_waitcnt lgkmcnt(3)
	v_mfma_f32_16x16x32_bf16 v[100:103], v[128:131], v[242:245], v[100:103]
	v_mfma_f32_16x16x32_bf16 v[108:111], v[132:135], v[242:245], v[108:111]
	v_mfma_f32_16x16x32_bf16 v[36:39], v[136:139], v[242:245], v[36:39]
	v_mfma_f32_16x16x32_bf16 v[44:47], v[140:143], v[242:245], v[44:47]
	ds_read_b128 v[242:245], v246 offset:23552
	s_waitcnt vmcnt(6)
	ds_write_b128 v241, v[168:171] offset:8192
	ds_write_b128 v241, v[172:175] offset:12288
	s_waitcnt lgkmcnt(5)
	v_mfma_f32_16x16x32_bf16 v[80:83], v[128:131], v[196:199], v[80:83]
	v_mfma_f32_16x16x32_bf16 v[88:91], v[132:135], v[196:199], v[88:91]
	v_mfma_f32_16x16x32_bf16 v[16:19], v[136:139], v[196:199], v[16:19]
	v_mfma_f32_16x16x32_bf16 v[24:27], v[140:143], v[196:199], v[24:27]
	ds_read_b128 v[196:199], v246 offset:0
	s_waitcnt lgkmcnt(5)
	v_mfma_f32_16x16x32_bf16 v[84:87], v[128:131], v[200:203], v[84:87]
	v_mfma_f32_16x16x32_bf16 v[92:95], v[132:135], v[200:203], v[92:95]
	v_mfma_f32_16x16x32_bf16 v[20:23], v[136:139], v[200:203], v[20:23]
	v_mfma_f32_16x16x32_bf16 v[28:31], v[140:143], v[200:203], v[28:31]
	ds_read_b128 v[200:203], v246 offset:1024
	s_waitcnt lgkmcnt(2)
	s_barrier
	v_mfma_f32_16x16x32_bf16 v[64:67], v[128:131], v[204:207], v[64:67]
	v_mfma_f32_16x16x32_bf16 v[72:75], v[132:135], v[204:207], v[72:75]
	v_mfma_f32_16x16x32_bf16 v[0:3], v[136:139], v[204:207], v[0:3]
	v_mfma_f32_16x16x32_bf16 v[8:11], v[140:143], v[204:207], v[8:11]
	ds_read_b128 v[204:207], v246 offset:2048
	v_mfma_f32_16x16x32_bf16 v[68:71], v[128:131], v[242:245], v[68:71]
	v_mfma_f32_16x16x32_bf16 v[76:79], v[132:135], v[242:245], v[76:79]
	v_mfma_f32_16x16x32_bf16 v[4:7], v[136:139], v[242:245], v[4:7]
	v_mfma_f32_16x16x32_bf16 v[12:15], v[140:143], v[242:245], v[12:15]
	ds_read_b128 v[242:245], v246 offset:3072
	global_load_dwordx4 v[128:131], v[248:249], off
	global_load_dwordx4 v[132:135], v[248:249], off offset:256
	global_load_dwordx4 v[136:139], v[250:251], off
	global_load_dwordx4 v[140:143], v[250:251], off offset:256
	s_add_i32 s9, s8, 6
	s_min_u32 s10, s9, 87
	s_lshl_b32 s96, s10, 13
	v_lshl_add_u64 v[174:175], v[188:189], 0, s[96:97]
	global_load_dwordx4 v[168:171], v[174:175], off offset:-2048
	global_load_dwordx4 v[172:175], v[174:175], off offset:2048
	s_add_i32 s9, s8, 5
	s_min_u32 s10, s9, 87
	s_lshl_b32 s96, s10, 11
	v_lshl_add_u64 v[248:249], v[184:185], 0, s[96:97]
	v_lshl_add_u64 v[250:251], v[186:187], 0, s[96:97]
	s_waitcnt vmcnt(8) lgkmcnt(3)
	v_mfma_f32_16x16x32_bf16 v[112:115], v[144:147], v[196:199], v[112:115]
	v_mfma_f32_16x16x32_bf16 v[120:123], v[148:151], v[196:199], v[120:123]
	v_mfma_f32_16x16x32_bf16 v[48:51], v[152:155], v[196:199], v[48:51]
	v_mfma_f32_16x16x32_bf16 v[56:59], v[156:159], v[196:199], v[56:59]
	ds_read_b128 v[196:199], v246 offset:4096
	s_waitcnt lgkmcnt(3)
	v_mfma_f32_16x16x32_bf16 v[116:119], v[144:147], v[200:203], v[116:119]
	v_mfma_f32_16x16x32_bf16 v[124:127], v[148:151], v[200:203], v[124:127]
	v_mfma_f32_16x16x32_bf16 v[52:55], v[152:155], v[200:203], v[52:55]
	v_mfma_f32_16x16x32_bf16 v[60:63], v[156:159], v[200:203], v[60:63]
	ds_read_b128 v[200:203], v246 offset:5120
	s_waitcnt lgkmcnt(3)
	v_mfma_f32_16x16x32_bf16 v[96:99], v[144:147], v[204:207], v[96:99]
	v_mfma_f32_16x16x32_bf16 v[104:107], v[148:151], v[204:207], v[104:107]
	v_mfma_f32_16x16x32_bf16 v[32:35], v[152:155], v[204:207], v[32:35]
	v_mfma_f32_16x16x32_bf16 v[40:43], v[156:159], v[204:207], v[40:43]
	ds_read_b128 v[204:207], v246 offset:6144
	s_waitcnt lgkmcnt(3)
	v_mfma_f32_16x16x32_bf16 v[100:103], v[144:147], v[242:245], v[100:103]
	v_mfma_f32_16x16x32_bf16 v[108:111], v[148:151], v[242:245], v[108:111]
	v_mfma_f32_16x16x32_bf16 v[36:39], v[152:155], v[242:245], v[36:39]
	v_mfma_f32_16x16x32_bf16 v[44:47], v[156:159], v[242:245], v[44:47]
	ds_read_b128 v[242:245], v246 offset:7168
	s_waitcnt vmcnt(6)
	ds_write_b128 v241, v[160:163] offset:16384
	ds_write_b128 v241, v[164:167] offset:20480
	s_waitcnt lgkmcnt(5)
	v_mfma_f32_16x16x32_bf16 v[80:83], v[144:147], v[196:199], v[80:83]
	v_mfma_f32_16x16x32_bf16 v[88:91], v[148:151], v[196:199], v[88:91]
	v_mfma_f32_16x16x32_bf16 v[16:19], v[152:155], v[196:199], v[16:19]
	v_mfma_f32_16x16x32_bf16 v[24:27], v[156:159], v[196:199], v[24:27]
	ds_read_b128 v[196:199], v246 offset:8192
	s_waitcnt lgkmcnt(5)
	v_mfma_f32_16x16x32_bf16 v[84:87], v[144:147], v[200:203], v[84:87]
	v_mfma_f32_16x16x32_bf16 v[92:95], v[148:151], v[200:203], v[92:95]
	v_mfma_f32_16x16x32_bf16 v[20:23], v[152:155], v[200:203], v[20:23]
	v_mfma_f32_16x16x32_bf16 v[28:31], v[156:159], v[200:203], v[28:31]
	ds_read_b128 v[200:203], v246 offset:9216
	s_waitcnt lgkmcnt(2)
	s_barrier
	v_mfma_f32_16x16x32_bf16 v[64:67], v[144:147], v[204:207], v[64:67]
	v_mfma_f32_16x16x32_bf16 v[72:75], v[148:151], v[204:207], v[72:75]
	v_mfma_f32_16x16x32_bf16 v[0:3], v[152:155], v[204:207], v[0:3]
	v_mfma_f32_16x16x32_bf16 v[8:11], v[156:159], v[204:207], v[8:11]
	ds_read_b128 v[204:207], v246 offset:10240
	v_mfma_f32_16x16x32_bf16 v[68:71], v[144:147], v[242:245], v[68:71]
	v_mfma_f32_16x16x32_bf16 v[76:79], v[148:151], v[242:245], v[76:79]
	v_mfma_f32_16x16x32_bf16 v[4:7], v[152:155], v[242:245], v[4:7]
	v_mfma_f32_16x16x32_bf16 v[12:15], v[156:159], v[242:245], v[12:15]
	ds_read_b128 v[242:245], v246 offset:11264
	global_load_dwordx4 v[144:147], v[248:249], off
	global_load_dwordx4 v[148:151], v[248:249], off offset:256
	global_load_dwordx4 v[152:155], v[250:251], off
	global_load_dwordx4 v[156:159], v[250:251], off offset:256
	s_waitcnt lgkmcnt(0)
	s_nop 7
	v_permlane16_swap_b32_e32 v112, v116
	v_permlane16_swap_b32_e32 v113, v117
	v_permlane16_swap_b32_e32 v114, v118
	v_permlane16_swap_b32_e32 v115, v119
	v_permlane16_swap_b32_e32 v120, v124
	v_permlane16_swap_b32_e32 v121, v125
	v_permlane16_swap_b32_e32 v122, v126
	v_permlane16_swap_b32_e32 v123, v127
	v_permlane16_swap_b32_e32 v96, v100
	v_permlane16_swap_b32_e32 v97, v101
	v_permlane16_swap_b32_e32 v98, v102
	v_permlane16_swap_b32_e32 v99, v103
	v_permlane16_swap_b32_e32 v104, v108
	v_permlane16_swap_b32_e32 v105, v109
	v_permlane16_swap_b32_e32 v106, v110
	v_permlane16_swap_b32_e32 v107, v111
	v_permlane16_swap_b32_e32 v80, v84
	v_permlane16_swap_b32_e32 v81, v85
	v_permlane16_swap_b32_e32 v82, v86
	v_permlane16_swap_b32_e32 v83, v87
	v_permlane16_swap_b32_e32 v88, v92
	v_permlane16_swap_b32_e32 v89, v93
	v_permlane16_swap_b32_e32 v90, v94
	v_permlane16_swap_b32_e32 v91, v95
	v_permlane16_swap_b32_e32 v64, v68
	v_permlane16_swap_b32_e32 v65, v69
	v_permlane16_swap_b32_e32 v66, v70
	v_permlane16_swap_b32_e32 v67, v71
	v_permlane16_swap_b32_e32 v72, v76
	v_permlane16_swap_b32_e32 v73, v77
	v_permlane16_swap_b32_e32 v74, v78
	v_permlane16_swap_b32_e32 v75, v79
	v_permlane16_swap_b32_e32 v48, v52
	v_permlane16_swap_b32_e32 v49, v53
	v_permlane16_swap_b32_e32 v50, v54
	v_permlane16_swap_b32_e32 v51, v55
	v_permlane16_swap_b32_e32 v56, v60
	v_permlane16_swap_b32_e32 v57, v61
	v_permlane16_swap_b32_e32 v58, v62
	v_permlane16_swap_b32_e32 v59, v63
	v_permlane16_swap_b32_e32 v32, v36
	v_permlane16_swap_b32_e32 v33, v37
	v_permlane16_swap_b32_e32 v34, v38
	v_permlane16_swap_b32_e32 v35, v39
	v_permlane16_swap_b32_e32 v40, v44
	v_permlane16_swap_b32_e32 v41, v45
	v_permlane16_swap_b32_e32 v42, v46
	v_permlane16_swap_b32_e32 v43, v47
	v_permlane16_swap_b32_e32 v16, v20
	v_permlane16_swap_b32_e32 v17, v21
	v_permlane16_swap_b32_e32 v18, v22
	v_permlane16_swap_b32_e32 v19, v23
	v_permlane16_swap_b32_e32 v24, v28
	v_permlane16_swap_b32_e32 v25, v29
	v_permlane16_swap_b32_e32 v26, v30
	v_permlane16_swap_b32_e32 v27, v31
	v_permlane16_swap_b32_e32 v0, v4
	v_permlane16_swap_b32_e32 v1, v5
	v_permlane16_swap_b32_e32 v2, v6
	v_permlane16_swap_b32_e32 v3, v7
	v_permlane16_swap_b32_e32 v8, v12
	v_permlane16_swap_b32_e32 v9, v13
	v_permlane16_swap_b32_e32 v10, v14
	v_permlane16_swap_b32_e32 v11, v15
	v_permlane32_swap_b32_e32 v112, v116
	v_permlane32_swap_b32_e32 v113, v117
	v_permlane32_swap_b32_e32 v114, v118
	v_permlane32_swap_b32_e32 v115, v119
	v_permlane32_swap_b32_e32 v120, v124
	v_permlane32_swap_b32_e32 v121, v125
	v_permlane32_swap_b32_e32 v122, v126
	v_permlane32_swap_b32_e32 v123, v127
	v_permlane32_swap_b32_e32 v96, v100
	v_permlane32_swap_b32_e32 v97, v101
	v_permlane32_swap_b32_e32 v98, v102
	v_permlane32_swap_b32_e32 v99, v103
	v_permlane32_swap_b32_e32 v104, v108
	v_permlane32_swap_b32_e32 v105, v109
	v_permlane32_swap_b32_e32 v106, v110
	v_permlane32_swap_b32_e32 v107, v111
	v_permlane32_swap_b32_e32 v80, v84
	v_permlane32_swap_b32_e32 v81, v85
	v_permlane32_swap_b32_e32 v82, v86
	v_permlane32_swap_b32_e32 v83, v87
	v_permlane32_swap_b32_e32 v88, v92
	v_permlane32_swap_b32_e32 v89, v93
	v_permlane32_swap_b32_e32 v90, v94
	v_permlane32_swap_b32_e32 v91, v95
	v_permlane32_swap_b32_e32 v64, v68
	v_permlane32_swap_b32_e32 v65, v69
	v_permlane32_swap_b32_e32 v66, v70
	v_permlane32_swap_b32_e32 v67, v71
	v_permlane32_swap_b32_e32 v72, v76
	v_permlane32_swap_b32_e32 v73, v77
	v_permlane32_swap_b32_e32 v74, v78
	v_permlane32_swap_b32_e32 v75, v79
	v_permlane32_swap_b32_e32 v48, v52
	v_permlane32_swap_b32_e32 v49, v53
	v_permlane32_swap_b32_e32 v50, v54
	v_permlane32_swap_b32_e32 v51, v55
	v_permlane32_swap_b32_e32 v56, v60
	v_permlane32_swap_b32_e32 v57, v61
	v_permlane32_swap_b32_e32 v58, v62
	v_permlane32_swap_b32_e32 v59, v63
	v_permlane32_swap_b32_e32 v32, v36
	v_permlane32_swap_b32_e32 v33, v37
	v_permlane32_swap_b32_e32 v34, v38
	v_permlane32_swap_b32_e32 v35, v39
	v_permlane32_swap_b32_e32 v40, v44
	v_permlane32_swap_b32_e32 v41, v45
	v_permlane32_swap_b32_e32 v42, v46
	v_permlane32_swap_b32_e32 v43, v47
	v_permlane32_swap_b32_e32 v16, v20
	v_permlane32_swap_b32_e32 v17, v21
	v_permlane32_swap_b32_e32 v18, v22
	v_permlane32_swap_b32_e32 v19, v23
	v_permlane32_swap_b32_e32 v24, v28
	v_permlane32_swap_b32_e32 v25, v29
	v_permlane32_swap_b32_e32 v26, v30
	v_permlane32_swap_b32_e32 v27, v31
	v_permlane32_swap_b32_e32 v0, v4
	v_permlane32_swap_b32_e32 v1, v5
	v_permlane32_swap_b32_e32 v2, v6
	v_permlane32_swap_b32_e32 v3, v7
	v_permlane32_swap_b32_e32 v8, v12
	v_permlane32_swap_b32_e32 v9, v13
	v_permlane32_swap_b32_e32 v10, v14
	v_permlane32_swap_b32_e32 v11, v15
	s_waitcnt vmcnt(0)
	s_movk_i32 s8, 0x2400
	s_waitcnt vmcnt(0)
	v_and_b32_e32 v132, 0xffffffc0, v181
	v_mul_lo_u32 v129, v237, s8
	v_lshlrev_b32_e32 v130, 2, v238
	v_lshl_add_u32 v156, s7, 8, v132
	v_mul_u32_u24_e32 v132, 0x110, v183
	v_or_b32_e32 v131, v129, v130
	v_lshlrev_b32_e32 v132, 2, v132
	v_add_u32_e32 v131, v131, v132
	v_add3_u32 v132, v129, v132, v130
	v_readlane_b32 s8, v253, 36
	v_lshlrev_b32_e32 v128, 2, v181
	v_add_u32_e32 v133, 0x800, v131
	v_add_u32_e32 v134, 0x800, v132
	v_lshrrev_b32_e32 v155, 4, v239
	v_readlane_b32 s12, v253, 40
	v_readlane_b32 s13, v253, 41
	v_readlane_b32 s14, v253, 42
	v_readlane_b32 s15, v253, 43
	v_readlane_b32 s16, v253, 44
	v_readlane_b32 s17, v253, 45
	v_readlane_b32 s18, v253, 46
	v_readlane_b32 s19, v253, 47
	v_and_b32_e32 v128, 60, v128
	ds_write2_b32 v131, v112, v113 offset1:68
	ds_write2_b32 v132, v96, v97 offset0:32 offset1:100
	ds_write2_b32 v131, v114, v115 offset0:136 offset1:204
	ds_write2_b32 v132, v98, v99 offset0:168 offset1:236
	ds_write2_b32 v133, v116, v117 offset0:32 offset1:100
	ds_write2_b32 v134, v100, v101 offset0:64 offset1:132
	ds_write2_b32 v133, v118, v119 offset0:168 offset1:236
	v_or_b32_e32 v100, v156, v155
	v_readlane_b32 s20, v253, 48
	v_readlane_b32 s21, v253, 49
	v_readlane_b32 s22, v253, 50
	v_readlane_b32 s23, v253, 51
	s_mov_b64 s[12:13], s[16:17]
	v_lshl_or_b32 v144, v128, 2, v129
	v_lshl_or_b32 v128, s6, 7, v128
	s_movk_i32 s6, 0x110
	v_cmp_gt_i32_e32 vcc, s39, v100
	v_add_u32_e32 v96, 0xffff8000, v100
	v_ashrrev_i32_e32 v97, 31, v100
	s_mov_b64 s[14:15], s[18:19]
	v_mad_u32_u24 v130, v155, s6, v144
	v_cndmask_b32_e32 v97, 0, v97, vcc
	v_cndmask_b32_e32 v96, v96, v100, vcc
	v_mov_b32_e32 v144, s63
	v_mov_b32_e32 v145, s15
	v_mov_b32_e32 v146, s62
	v_mov_b32_e32 v147, s14
	v_min_i32_e32 v100, 0x8000, v100
	v_add_u32_e32 v135, 0xa00, v132
	v_add_u32_e32 v136, 0x1000, v131
	v_add_u32_e32 v137, 0x1000, v132
	v_add_u32_e32 v138, 0x1200, v131
	v_add_u32_e32 v139, 0x1200, v132
	v_add_u32_e32 v140, 0x1800, v131
	v_add_u32_e32 v141, 0x1800, v132
	v_add_u32_e32 v142, 0x1a00, v131
	v_add_u32_e32 v143, 0x1c00, v132
	v_ashrrev_i32_e32 v129, 31, v128
	v_cndmask_b32_e32 v99, v144, v145, vcc
	v_cndmask_b32_e32 v98, v146, v147, vcc
	v_lshlrev_b64 v[96:97], 12, v[96:97]
	v_ashrrev_i32_e32 v100, 12, v100
	ds_write2_b32 v135, v102, v103 offset0:72 offset1:140
	ds_write2_b32 v136, v120, v121 offset0:64 offset1:132
	ds_write2_b32 v137, v104, v105 offset0:96 offset1:164
	ds_write2_b32 v138, v122, v123 offset0:72 offset1:140
	ds_write2_b32 v139, v106, v107 offset0:104 offset1:172
	ds_write2_b32 v140, v124, v125 offset0:96 offset1:164
	ds_write2_b32 v141, v108, v109 offset0:128 offset1:196
	ds_write2_b32 v142, v126, v127 offset0:104 offset1:172
	ds_write2_b32 v143, v110, v111 offset0:8 offset1:76
	v_lshl_add_u64 v[98:99], v[98:99], 0, v[96:97]
	v_lshlrev_b64 v[96:97], 2, v[128:129]
	v_mul_hi_i32_i24_e32 v101, 0x6000, v100
	v_mul_i32_i24_e32 v100, 0x6000, v100
	s_waitcnt lgkmcnt(0)
	v_lshl_add_u64 v[98:99], v[98:99], 0, v[96:97]
	v_lshl_add_u64 v[100:101], s[0:1], 0, v[100:101]
	v_lshl_add_u64 v[100:101], v[100:101], 0, v[96:97]
	ds_read_b128 v[102:105], v130
	global_load_dwordx4 v[106:109], v[98:99], off
	global_load_dwordx4 v[110:113], v[100:101], off
	v_or_b32_e32 v148, 4, v155
	v_or_b32_e32 v149, 8, v155
	v_or_b32_e32 v150, 12, v155
	v_or_b32_e32 v151, 16, v155
	v_or_b32_e32 v152, 20, v155
	v_or_b32_e32 v153, 24, v155
	v_or_b32_e32 v154, 28, v155
	v_or_b32_e32 v157, v156, v154
	v_readlane_b32 s6, v254, 11
	s_add_i32 s2, s2, s6
	s_cmp_lt_i32 s2, s26
	v_readlane_b32 s9, v253, 37
	v_readlane_b32 s10, v253, 38
	v_readlane_b32 s11, v253, 39
	s_mov_b64 s[16:17], s[20:21]
	s_mov_b64 s[18:19], s[22:23]
	s_waitcnt vmcnt(0) lgkmcnt(0)
	v_pk_fma_f32 v[102:103], v[102:103], v[110:111], v[106:107]
	v_pk_fma_f32 v[104:105], v[104:105], v[112:113], v[108:109]
	v_or_b32_e32 v106, v156, v148
	global_store_dwordx4 v[98:99], v[102:105], off
	v_cmp_gt_i32_e32 vcc, s39, v106
	s_nop 0
	v_ashrrev_i32_e32 v102, 31, v106
	v_add_u32_e32 v104, 0xffff8000, v106
	v_cndmask_b32_e32 v103, 0, v102, vcc
	v_cndmask_b32_e32 v102, v104, v106, vcc
	v_cndmask_b32_e32 v105, v144, v145, vcc
	v_cndmask_b32_e32 v104, v146, v147, vcc
	v_lshlrev_b64 v[102:103], 12, v[102:103]
	v_lshl_add_u64 v[102:103], v[104:105], 0, v[102:103]
	v_min_i32_e32 v104, 0x8000, v106
	v_ashrrev_i32_e32 v104, 12, v104
	v_mul_hi_i32_i24_e32 v105, 0x6000, v104
	v_mul_i32_i24_e32 v104, 0x6000, v104
	v_lshl_add_u64 v[102:103], v[102:103], 0, v[96:97]
	v_lshl_add_u64 v[104:105], s[0:1], 0, v[104:105]
	v_lshl_add_u64 v[104:105], v[104:105], 0, v[96:97]
	ds_read_b128 v[106:109], v130 offset:1088
	global_load_dwordx4 v[110:113], v[102:103], off
	global_load_dwordx4 v[114:117], v[104:105], off
	s_waitcnt vmcnt(0) lgkmcnt(0)
	v_pk_fma_f32 v[106:107], v[106:107], v[114:115], v[110:111]
	v_pk_fma_f32 v[108:109], v[108:109], v[116:117], v[112:113]
	v_or_b32_e32 v110, v156, v149
	global_store_dwordx4 v[102:103], v[106:109], off
	v_cmp_gt_i32_e32 vcc, s39, v110
	s_nop 0
	v_ashrrev_i32_e32 v106, 31, v110
	v_add_u32_e32 v108, 0xffff8000, v110
	v_cndmask_b32_e32 v107, 0, v106, vcc
	v_cndmask_b32_e32 v106, v108, v110, vcc
	v_cndmask_b32_e32 v109, v144, v145, vcc
	v_cndmask_b32_e32 v108, v146, v147, vcc
	v_lshlrev_b64 v[106:107], 12, v[106:107]
	v_lshl_add_u64 v[106:107], v[108:109], 0, v[106:107]
	v_min_i32_e32 v108, 0x8000, v110
	v_ashrrev_i32_e32 v108, 12, v108
	v_mul_hi_i32_i24_e32 v109, 0x6000, v108
	v_mul_i32_i24_e32 v108, 0x6000, v108
	v_lshl_add_u64 v[106:107], v[106:107], 0, v[96:97]
	v_lshl_add_u64 v[108:109], s[0:1], 0, v[108:109]
	v_lshl_add_u64 v[108:109], v[108:109], 0, v[96:97]
	ds_read_b128 v[110:113], v130 offset:2176
	global_load_dwordx4 v[114:117], v[106:107], off
	global_load_dwordx4 v[118:121], v[108:109], off
	s_waitcnt vmcnt(0) lgkmcnt(0)
	v_pk_fma_f32 v[110:111], v[110:111], v[118:119], v[114:115]
	v_pk_fma_f32 v[112:113], v[112:113], v[120:121], v[116:117]
	v_or_b32_e32 v114, v156, v150
	global_store_dwordx4 v[106:107], v[110:113], off
	v_cmp_gt_i32_e32 vcc, s39, v114
	s_nop 0
	v_ashrrev_i32_e32 v110, 31, v114
	v_add_u32_e32 v112, 0xffff8000, v114
	v_cndmask_b32_e32 v111, 0, v110, vcc
	v_cndmask_b32_e32 v110, v112, v114, vcc
	v_cndmask_b32_e32 v113, v144, v145, vcc
	v_cndmask_b32_e32 v112, v146, v147, vcc
	v_lshlrev_b64 v[110:111], 12, v[110:111]
	v_lshl_add_u64 v[110:111], v[112:113], 0, v[110:111]
	v_min_i32_e32 v112, 0x8000, v114
	v_ashrrev_i32_e32 v112, 12, v112
	v_mul_hi_i32_i24_e32 v113, 0x6000, v112
	v_mul_i32_i24_e32 v112, 0x6000, v112
	v_lshl_add_u64 v[110:111], v[110:111], 0, v[96:97]
	v_lshl_add_u64 v[112:113], s[0:1], 0, v[112:113]
	v_lshl_add_u64 v[112:113], v[112:113], 0, v[96:97]
	ds_read_b128 v[114:117], v130 offset:3264
	global_load_dwordx4 v[118:121], v[110:111], off
	global_load_dwordx4 v[122:125], v[112:113], off
	s_waitcnt vmcnt(0) lgkmcnt(0)
	v_pk_fma_f32 v[114:115], v[114:115], v[122:123], v[118:119]
	v_pk_fma_f32 v[116:117], v[116:117], v[124:125], v[120:121]
	v_or_b32_e32 v118, v156, v151
	global_store_dwordx4 v[110:111], v[114:117], off
	v_cmp_gt_i32_e32 vcc, s39, v118
	s_nop 0
	v_ashrrev_i32_e32 v114, 31, v118
	v_add_u32_e32 v116, 0xffff8000, v118
	v_cndmask_b32_e32 v115, 0, v114, vcc
	v_cndmask_b32_e32 v114, v116, v118, vcc
	v_cndmask_b32_e32 v117, v144, v145, vcc
	v_cndmask_b32_e32 v116, v146, v147, vcc
	v_lshlrev_b64 v[114:115], 12, v[114:115]
	v_lshl_add_u64 v[114:115], v[116:117], 0, v[114:115]
	v_min_i32_e32 v116, 0x8000, v118
	v_ashrrev_i32_e32 v116, 12, v116
	v_mul_hi_i32_i24_e32 v117, 0x6000, v116
	v_mul_i32_i24_e32 v116, 0x6000, v116
	v_lshl_add_u64 v[114:115], v[114:115], 0, v[96:97]
	v_lshl_add_u64 v[116:117], s[0:1], 0, v[116:117]
	v_lshl_add_u64 v[116:117], v[116:117], 0, v[96:97]
	ds_read_b128 v[118:121], v130 offset:4352
	global_load_dwordx4 v[122:125], v[114:115], off
	global_load_dwordx4 v[126:129], v[116:117], off
	s_waitcnt vmcnt(0) lgkmcnt(0)
	v_pk_fma_f32 v[118:119], v[118:119], v[126:127], v[122:123]
	v_pk_fma_f32 v[120:121], v[120:121], v[128:129], v[124:125]
	v_or_b32_e32 v122, v156, v152
	global_store_dwordx4 v[114:115], v[118:121], off
	v_cmp_gt_i32_e32 vcc, s39, v122
	s_nop 0
	v_ashrrev_i32_e32 v118, 31, v122
	v_add_u32_e32 v120, 0xffff8000, v122
	v_cndmask_b32_e32 v119, 0, v118, vcc
	v_cndmask_b32_e32 v118, v120, v122, vcc
	v_cndmask_b32_e32 v121, v144, v145, vcc
	v_cndmask_b32_e32 v120, v146, v147, vcc
	v_lshlrev_b64 v[118:119], 12, v[118:119]
	v_lshl_add_u64 v[118:119], v[120:121], 0, v[118:119]
	v_min_i32_e32 v120, 0x8000, v122
	v_ashrrev_i32_e32 v120, 12, v120
	v_mul_hi_i32_i24_e32 v121, 0x6000, v120
	v_mul_i32_i24_e32 v120, 0x6000, v120
	v_lshl_add_u64 v[118:119], v[118:119], 0, v[96:97]
	v_lshl_add_u64 v[120:121], s[0:1], 0, v[120:121]
	v_lshl_add_u64 v[120:121], v[120:121], 0, v[96:97]
	ds_read_b128 v[122:125], v130 offset:5440
	global_load_dwordx4 v[126:129], v[118:119], off
	global_load_dwordx4 v[158:161], v[120:121], off
	s_waitcnt vmcnt(0) lgkmcnt(0)
	v_pk_fma_f32 v[122:123], v[122:123], v[158:159], v[126:127]
	v_pk_fma_f32 v[124:125], v[124:125], v[160:161], v[128:129]
	v_or_b32_e32 v126, v156, v153
	global_store_dwordx4 v[118:119], v[122:125], off
	v_cmp_gt_i32_e32 vcc, s39, v126
	s_nop 0
	v_ashrrev_i32_e32 v122, 31, v126
	v_add_u32_e32 v124, 0xffff8000, v126
	v_cndmask_b32_e32 v123, 0, v122, vcc
	v_cndmask_b32_e32 v122, v124, v126, vcc
	v_cndmask_b32_e32 v125, v144, v145, vcc
	v_cndmask_b32_e32 v124, v146, v147, vcc
	v_lshlrev_b64 v[122:123], 12, v[122:123]
	v_lshl_add_u64 v[122:123], v[124:125], 0, v[122:123]
	v_min_i32_e32 v124, 0x8000, v126
	v_ashrrev_i32_e32 v124, 12, v124
	v_mul_hi_i32_i24_e32 v125, 0x6000, v124
	v_mul_i32_i24_e32 v124, 0x6000, v124
	v_lshl_add_u64 v[122:123], v[122:123], 0, v[96:97]
	v_lshl_add_u64 v[124:125], s[0:1], 0, v[124:125]
	v_lshl_add_u64 v[124:125], v[124:125], 0, v[96:97]
	ds_read_b128 v[126:129], v130 offset:6528
	global_load_dwordx4 v[158:161], v[122:123], off
	global_load_dwordx4 v[162:165], v[124:125], off
	v_cmp_gt_i32_e32 vcc, s39, v157
	s_waitcnt vmcnt(0) lgkmcnt(0)
	v_pk_fma_f32 v[126:127], v[126:127], v[162:163], v[158:159]
	v_pk_fma_f32 v[128:129], v[128:129], v[164:165], v[160:161]
	global_store_dwordx4 v[122:123], v[126:129], off
	ds_read_b128 v[158:161], v130 offset:7616
	s_nop 0
	v_ashrrev_i32_e32 v126, 31, v157
	v_add_u32_e32 v128, 0xffff8000, v157
	v_cndmask_b32_e32 v127, 0, v126, vcc
	v_cndmask_b32_e32 v126, v128, v157, vcc
	v_cndmask_b32_e32 v129, v144, v145, vcc
	v_cndmask_b32_e32 v128, v146, v147, vcc
	v_lshlrev_b64 v[126:127], 12, v[126:127]
	v_lshl_add_u64 v[126:127], v[128:129], 0, v[126:127]
	v_min_i32_e32 v128, 0x8000, v157
	v_ashrrev_i32_e32 v128, 12, v128
	v_mul_hi_i32_i24_e32 v129, 0x6000, v128
	v_mul_i32_i24_e32 v128, 0x6000, v128
	v_lshl_add_u64 v[126:127], v[126:127], 0, v[96:97]
	v_lshl_add_u64 v[128:129], s[0:1], 0, v[128:129]
	v_lshl_add_u64 v[128:129], v[128:129], 0, v[96:97]
	global_load_dwordx4 v[162:165], v[126:127], off
	global_load_dwordx4 v[166:169], v[128:129], off
	s_waitcnt vmcnt(0) lgkmcnt(0)
	v_pk_fma_f32 v[158:159], v[158:159], v[166:167], v[162:163]
	v_pk_fma_f32 v[160:161], v[160:161], v[168:169], v[164:165]
	global_store_dwordx4 v[126:127], v[158:161], off
	s_waitcnt lgkmcnt(0)
	ds_write2_b32 v131, v80, v81 offset1:68
	ds_write2_b32 v132, v64, v65 offset0:32 offset1:100
	ds_write2_b32 v131, v82, v83 offset0:136 offset1:204
	ds_write2_b32 v132, v66, v67 offset0:168 offset1:236
	ds_write2_b32 v133, v84, v85 offset0:32 offset1:100
	ds_write2_b32 v134, v68, v69 offset0:64 offset1:132
	ds_write2_b32 v133, v86, v87 offset0:168 offset1:236
	ds_write2_b32 v135, v70, v71 offset0:72 offset1:140
	ds_write2_b32 v136, v88, v89 offset0:64 offset1:132
	ds_write2_b32 v137, v72, v73 offset0:96 offset1:164
	ds_write2_b32 v138, v90, v91 offset0:72 offset1:140
	ds_write2_b32 v139, v74, v75 offset0:104 offset1:172
	ds_write2_b32 v140, v92, v93 offset0:96 offset1:164
	ds_write2_b32 v141, v76, v77 offset0:128 offset1:196
	ds_write2_b32 v142, v94, v95 offset0:104 offset1:172
	ds_write2_b32 v143, v78, v79 offset0:8 offset1:76
	s_waitcnt lgkmcnt(0)
	ds_read_b128 v[64:67], v130
	global_load_dwordx4 v[68:71], v[98:99], off offset:256
	global_load_dwordx4 v[72:75], v[100:101], off offset:256
	s_waitcnt vmcnt(0) lgkmcnt(0)
	v_pk_fma_f32 v[64:65], v[64:65], v[72:73], v[68:69]
	v_pk_fma_f32 v[66:67], v[66:67], v[74:75], v[70:71]
	global_store_dwordx4 v[98:99], v[64:67], off offset:256
	ds_read_b128 v[64:67], v130 offset:1088
	global_load_dwordx4 v[68:71], v[102:103], off offset:256
	global_load_dwordx4 v[72:75], v[104:105], off offset:256
	s_waitcnt vmcnt(0) lgkmcnt(0)
	v_pk_fma_f32 v[64:65], v[64:65], v[72:73], v[68:69]
	v_pk_fma_f32 v[66:67], v[66:67], v[74:75], v[70:71]
	global_store_dwordx4 v[102:103], v[64:67], off offset:256
	ds_read_b128 v[64:67], v130 offset:2176
	global_load_dwordx4 v[68:71], v[106:107], off offset:256
	global_load_dwordx4 v[72:75], v[108:109], off offset:256
	s_waitcnt vmcnt(0) lgkmcnt(0)
	v_pk_fma_f32 v[64:65], v[64:65], v[72:73], v[68:69]
	v_pk_fma_f32 v[66:67], v[66:67], v[74:75], v[70:71]
	global_store_dwordx4 v[106:107], v[64:67], off offset:256
	ds_read_b128 v[64:67], v130 offset:3264
	global_load_dwordx4 v[68:71], v[110:111], off offset:256
	global_load_dwordx4 v[72:75], v[112:113], off offset:256
	s_waitcnt vmcnt(0) lgkmcnt(0)
	v_pk_fma_f32 v[64:65], v[64:65], v[72:73], v[68:69]
	v_pk_fma_f32 v[66:67], v[66:67], v[74:75], v[70:71]
	global_store_dwordx4 v[110:111], v[64:67], off offset:256
	ds_read_b128 v[64:67], v130 offset:4352
	global_load_dwordx4 v[68:71], v[114:115], off offset:256
	global_load_dwordx4 v[72:75], v[116:117], off offset:256
	s_waitcnt vmcnt(0) lgkmcnt(0)
	v_pk_fma_f32 v[64:65], v[64:65], v[72:73], v[68:69]
	v_pk_fma_f32 v[66:67], v[66:67], v[74:75], v[70:71]
	global_store_dwordx4 v[114:115], v[64:67], off offset:256
	ds_read_b128 v[64:67], v130 offset:5440
	global_load_dwordx4 v[68:71], v[118:119], off offset:256
	global_load_dwordx4 v[72:75], v[120:121], off offset:256
	s_waitcnt vmcnt(0) lgkmcnt(0)
	v_pk_fma_f32 v[64:65], v[64:65], v[72:73], v[68:69]
	v_pk_fma_f32 v[66:67], v[66:67], v[74:75], v[70:71]
	global_store_dwordx4 v[118:119], v[64:67], off offset:256
	ds_read_b128 v[64:67], v130 offset:6528
	global_load_dwordx4 v[68:71], v[122:123], off offset:256
	global_load_dwordx4 v[72:75], v[124:125], off offset:256
	s_waitcnt vmcnt(0) lgkmcnt(0)
	v_pk_fma_f32 v[64:65], v[64:65], v[72:73], v[68:69]
	v_pk_fma_f32 v[66:67], v[66:67], v[74:75], v[70:71]
	global_store_dwordx4 v[122:123], v[64:67], off offset:256
	ds_read_b128 v[64:67], v130 offset:7616
	global_load_dwordx4 v[68:71], v[126:127], off offset:256
	global_load_dwordx4 v[72:75], v[128:129], off offset:256
	s_waitcnt vmcnt(0) lgkmcnt(0)
	v_pk_fma_f32 v[64:65], v[64:65], v[72:73], v[68:69]
	v_pk_fma_f32 v[66:67], v[66:67], v[74:75], v[70:71]
	global_store_dwordx4 v[126:127], v[64:67], off offset:256
	s_waitcnt lgkmcnt(0)
	ds_write2_b32 v131, v48, v49 offset1:68
	ds_write2_b32 v132, v32, v33 offset0:32 offset1:100
	ds_write2_b32 v131, v50, v51 offset0:136 offset1:204
	ds_write2_b32 v132, v34, v35 offset0:168 offset1:236
	ds_write2_b32 v133, v52, v53 offset0:32 offset1:100
	ds_write2_b32 v134, v36, v37 offset0:64 offset1:132
	ds_write2_b32 v133, v54, v55 offset0:168 offset1:236
	ds_write2_b32 v135, v38, v39 offset0:72 offset1:140
	ds_write2_b32 v136, v56, v57 offset0:64 offset1:132
	ds_write2_b32 v137, v40, v41 offset0:96 offset1:164
	ds_write2_b32 v138, v58, v59 offset0:72 offset1:140
	ds_write2_b32 v139, v42, v43 offset0:104 offset1:172
	ds_write2_b32 v140, v60, v61 offset0:96 offset1:164
	ds_write2_b32 v141, v44, v45 offset0:128 offset1:196
	ds_write2_b32 v142, v62, v63 offset0:104 offset1:172
	ds_write2_b32 v143, v46, v47 offset0:8 offset1:76
	v_or_b32_e32 v64, 32, v156
	v_or_b32_e32 v36, v64, v155
	v_cmp_gt_i32_e32 vcc, s39, v36
	v_ashrrev_i32_e32 v32, 31, v36
	v_add_u32_e32 v34, 0xffff8000, v36
	v_cndmask_b32_e32 v33, 0, v32, vcc
	v_cndmask_b32_e32 v32, v34, v36, vcc
	v_cndmask_b32_e32 v35, v144, v145, vcc
	v_cndmask_b32_e32 v34, v146, v147, vcc
	v_lshlrev_b64 v[32:33], 12, v[32:33]
	v_lshl_add_u64 v[32:33], v[34:35], 0, v[32:33]
	v_min_i32_e32 v34, 0x8000, v36
	v_ashrrev_i32_e32 v34, 12, v34
	v_mul_hi_i32_i24_e32 v35, 0x6000, v34
	v_mul_i32_i24_e32 v34, 0x6000, v34
	s_waitcnt lgkmcnt(0)
	v_lshl_add_u64 v[32:33], v[32:33], 0, v[96:97]
	v_lshl_add_u64 v[34:35], s[0:1], 0, v[34:35]
	v_lshl_add_u64 v[34:35], v[34:35], 0, v[96:97]
	ds_read_b128 v[36:39], v130
	global_load_dwordx4 v[40:43], v[32:33], off
	global_load_dwordx4 v[44:47], v[34:35], off
	s_waitcnt vmcnt(0) lgkmcnt(0)
	v_pk_fma_f32 v[36:37], v[36:37], v[44:45], v[40:41]
	v_pk_fma_f32 v[38:39], v[38:39], v[46:47], v[42:43]
	v_or_b32_e32 v40, v64, v148
	global_store_dwordx4 v[32:33], v[36:39], off
	v_cmp_gt_i32_e32 vcc, s39, v40
	s_nop 0
	v_ashrrev_i32_e32 v36, 31, v40
	v_add_u32_e32 v38, 0xffff8000, v40
	v_cndmask_b32_e32 v37, 0, v36, vcc
	v_cndmask_b32_e32 v36, v38, v40, vcc
	v_cndmask_b32_e32 v39, v144, v145, vcc
	v_cndmask_b32_e32 v38, v146, v147, vcc
	v_lshlrev_b64 v[36:37], 12, v[36:37]
	v_lshl_add_u64 v[36:37], v[38:39], 0, v[36:37]
	v_min_i32_e32 v38, 0x8000, v40
	v_ashrrev_i32_e32 v38, 12, v38
	v_mul_hi_i32_i24_e32 v39, 0x6000, v38
	v_mul_i32_i24_e32 v38, 0x6000, v38
	v_lshl_add_u64 v[36:37], v[36:37], 0, v[96:97]
	v_lshl_add_u64 v[38:39], s[0:1], 0, v[38:39]
	v_lshl_add_u64 v[38:39], v[38:39], 0, v[96:97]
	ds_read_b128 v[40:43], v130 offset:1088
	global_load_dwordx4 v[44:47], v[36:37], off
	global_load_dwordx4 v[48:51], v[38:39], off
	s_waitcnt vmcnt(0) lgkmcnt(0)
	v_pk_fma_f32 v[40:41], v[40:41], v[48:49], v[44:45]
	v_pk_fma_f32 v[42:43], v[42:43], v[50:51], v[46:47]
	v_or_b32_e32 v44, v64, v149
	global_store_dwordx4 v[36:37], v[40:43], off
	v_cmp_gt_i32_e32 vcc, s39, v44
	s_nop 0
	v_ashrrev_i32_e32 v40, 31, v44
	v_add_u32_e32 v42, 0xffff8000, v44
	v_cndmask_b32_e32 v41, 0, v40, vcc
	v_cndmask_b32_e32 v40, v42, v44, vcc
	v_cndmask_b32_e32 v43, v144, v145, vcc
	v_cndmask_b32_e32 v42, v146, v147, vcc
	v_lshlrev_b64 v[40:41], 12, v[40:41]
	v_lshl_add_u64 v[40:41], v[42:43], 0, v[40:41]
	v_min_i32_e32 v42, 0x8000, v44
	v_ashrrev_i32_e32 v42, 12, v42
	v_mul_hi_i32_i24_e32 v43, 0x6000, v42
	v_mul_i32_i24_e32 v42, 0x6000, v42
	v_lshl_add_u64 v[40:41], v[40:41], 0, v[96:97]
	v_lshl_add_u64 v[42:43], s[0:1], 0, v[42:43]
	v_lshl_add_u64 v[42:43], v[42:43], 0, v[96:97]
	ds_read_b128 v[44:47], v130 offset:2176
	global_load_dwordx4 v[48:51], v[40:41], off
	global_load_dwordx4 v[52:55], v[42:43], off
	s_waitcnt vmcnt(0) lgkmcnt(0)
	v_pk_fma_f32 v[44:45], v[44:45], v[52:53], v[48:49]
	v_pk_fma_f32 v[46:47], v[46:47], v[54:55], v[50:51]
	v_or_b32_e32 v48, v64, v150
	global_store_dwordx4 v[40:41], v[44:47], off
	v_cmp_gt_i32_e32 vcc, s39, v48
	s_nop 0
	v_ashrrev_i32_e32 v44, 31, v48
	v_add_u32_e32 v46, 0xffff8000, v48
	v_cndmask_b32_e32 v45, 0, v44, vcc
	v_cndmask_b32_e32 v44, v46, v48, vcc
	v_cndmask_b32_e32 v47, v144, v145, vcc
	v_cndmask_b32_e32 v46, v146, v147, vcc
	v_lshlrev_b64 v[44:45], 12, v[44:45]
	v_lshl_add_u64 v[44:45], v[46:47], 0, v[44:45]
	v_min_i32_e32 v46, 0x8000, v48
	v_ashrrev_i32_e32 v46, 12, v46
	v_mul_hi_i32_i24_e32 v47, 0x6000, v46
	v_mul_i32_i24_e32 v46, 0x6000, v46
	v_lshl_add_u64 v[44:45], v[44:45], 0, v[96:97]
	v_lshl_add_u64 v[46:47], s[0:1], 0, v[46:47]
	v_lshl_add_u64 v[46:47], v[46:47], 0, v[96:97]
	ds_read_b128 v[48:51], v130 offset:3264
	global_load_dwordx4 v[52:55], v[44:45], off
	global_load_dwordx4 v[56:59], v[46:47], off
	s_waitcnt vmcnt(0) lgkmcnt(0)
	v_pk_fma_f32 v[48:49], v[48:49], v[56:57], v[52:53]
	v_pk_fma_f32 v[50:51], v[50:51], v[58:59], v[54:55]
	v_or_b32_e32 v52, v64, v151
	global_store_dwordx4 v[44:45], v[48:51], off
	v_cmp_gt_i32_e32 vcc, s39, v52
	s_nop 0
	v_ashrrev_i32_e32 v48, 31, v52
	v_add_u32_e32 v50, 0xffff8000, v52
	v_cndmask_b32_e32 v49, 0, v48, vcc
	v_cndmask_b32_e32 v48, v50, v52, vcc
	v_cndmask_b32_e32 v51, v144, v145, vcc
	v_cndmask_b32_e32 v50, v146, v147, vcc
	v_lshlrev_b64 v[48:49], 12, v[48:49]
	v_lshl_add_u64 v[48:49], v[50:51], 0, v[48:49]
	v_min_i32_e32 v50, 0x8000, v52
	v_ashrrev_i32_e32 v50, 12, v50
	v_mul_hi_i32_i24_e32 v51, 0x6000, v50
	v_mul_i32_i24_e32 v50, 0x6000, v50
	v_lshl_add_u64 v[48:49], v[48:49], 0, v[96:97]
	v_lshl_add_u64 v[50:51], s[0:1], 0, v[50:51]
	v_lshl_add_u64 v[50:51], v[50:51], 0, v[96:97]
	ds_read_b128 v[52:55], v130 offset:4352
	global_load_dwordx4 v[56:59], v[48:49], off
	global_load_dwordx4 v[60:63], v[50:51], off
	s_waitcnt vmcnt(0) lgkmcnt(0)
	v_pk_fma_f32 v[52:53], v[52:53], v[60:61], v[56:57]
	v_pk_fma_f32 v[54:55], v[54:55], v[62:63], v[58:59]
	v_or_b32_e32 v56, v64, v152
	global_store_dwordx4 v[48:49], v[52:55], off
	v_cmp_gt_i32_e32 vcc, s39, v56
	s_nop 0
	v_ashrrev_i32_e32 v52, 31, v56
	v_add_u32_e32 v54, 0xffff8000, v56
	v_cndmask_b32_e32 v53, 0, v52, vcc
	v_cndmask_b32_e32 v52, v54, v56, vcc
	v_cndmask_b32_e32 v55, v144, v145, vcc
	v_cndmask_b32_e32 v54, v146, v147, vcc
	v_lshlrev_b64 v[52:53], 12, v[52:53]
	v_lshl_add_u64 v[52:53], v[54:55], 0, v[52:53]
	v_min_i32_e32 v54, 0x8000, v56
	v_ashrrev_i32_e32 v54, 12, v54
	v_mul_hi_i32_i24_e32 v55, 0x6000, v54
	v_mul_i32_i24_e32 v54, 0x6000, v54
	v_lshl_add_u64 v[52:53], v[52:53], 0, v[96:97]
	v_lshl_add_u64 v[54:55], s[0:1], 0, v[54:55]
	v_lshl_add_u64 v[54:55], v[54:55], 0, v[96:97]
	ds_read_b128 v[56:59], v130 offset:5440
	global_load_dwordx4 v[60:63], v[52:53], off
	global_load_dwordx4 v[66:69], v[54:55], off
	s_waitcnt vmcnt(0) lgkmcnt(0)
	v_pk_fma_f32 v[56:57], v[56:57], v[66:67], v[60:61]
	v_pk_fma_f32 v[58:59], v[58:59], v[68:69], v[62:63]
	v_or_b32_e32 v60, v64, v153
	global_store_dwordx4 v[52:53], v[56:59], off
	v_cmp_gt_i32_e32 vcc, s39, v60
	v_or_b32_e32 v64, v64, v154
	v_ashrrev_i32_e32 v56, 31, v60
	v_add_u32_e32 v58, 0xffff8000, v60
	v_cndmask_b32_e32 v57, 0, v56, vcc
	v_cndmask_b32_e32 v56, v58, v60, vcc
	v_cndmask_b32_e32 v59, v144, v145, vcc
	v_cndmask_b32_e32 v58, v146, v147, vcc
	v_lshlrev_b64 v[56:57], 12, v[56:57]
	v_lshl_add_u64 v[56:57], v[58:59], 0, v[56:57]
	v_min_i32_e32 v58, 0x8000, v60
	v_ashrrev_i32_e32 v58, 12, v58
	v_mul_hi_i32_i24_e32 v59, 0x6000, v58
	v_mul_i32_i24_e32 v58, 0x6000, v58
	v_lshl_add_u64 v[56:57], v[56:57], 0, v[96:97]
	v_lshl_add_u64 v[58:59], s[0:1], 0, v[58:59]
	v_lshl_add_u64 v[58:59], v[58:59], 0, v[96:97]
	ds_read_b128 v[60:63], v130 offset:6528
	global_load_dwordx4 v[66:69], v[56:57], off
	global_load_dwordx4 v[70:73], v[58:59], off
	v_cmp_gt_i32_e32 vcc, s39, v64
	s_waitcnt vmcnt(0) lgkmcnt(0)
	v_pk_fma_f32 v[60:61], v[60:61], v[70:71], v[66:67]
	v_pk_fma_f32 v[62:63], v[62:63], v[72:73], v[68:69]
	global_store_dwordx4 v[56:57], v[60:63], off
	s_nop 1
	v_ashrrev_i32_e32 v60, 31, v64
	v_add_u32_e32 v62, 0xffff8000, v64
	v_cndmask_b32_e32 v61, 0, v60, vcc
	v_cndmask_b32_e32 v60, v62, v64, vcc
	v_cndmask_b32_e32 v63, v144, v145, vcc
	v_cndmask_b32_e32 v62, v146, v147, vcc
	v_lshlrev_b64 v[60:61], 12, v[60:61]
	v_lshl_add_u64 v[60:61], v[62:63], 0, v[60:61]
	v_min_i32_e32 v62, 0x8000, v64
	v_ashrrev_i32_e32 v62, 12, v62
	v_mul_hi_i32_i24_e32 v63, 0x6000, v62
	v_mul_i32_i24_e32 v62, 0x6000, v62
	v_lshl_add_u64 v[60:61], v[60:61], 0, v[96:97]
	v_lshl_add_u64 v[62:63], s[0:1], 0, v[62:63]
	v_lshl_add_u64 v[62:63], v[62:63], 0, v[96:97]
	ds_read_b128 v[64:67], v130 offset:7616
	global_load_dwordx4 v[68:71], v[60:61], off
	global_load_dwordx4 v[72:75], v[62:63], off
	s_waitcnt vmcnt(0) lgkmcnt(0)
	v_pk_fma_f32 v[64:65], v[64:65], v[72:73], v[68:69]
	v_pk_fma_f32 v[66:67], v[66:67], v[74:75], v[70:71]
	global_store_dwordx4 v[60:61], v[64:67], off
	s_waitcnt lgkmcnt(0)
	ds_write2_b32 v131, v16, v17 offset1:68
	ds_write2_b32 v132, v0, v1 offset0:32 offset1:100
	ds_write2_b32 v131, v18, v19 offset0:136 offset1:204
	ds_write2_b32 v132, v2, v3 offset0:168 offset1:236
	ds_write2_b32 v133, v20, v21 offset0:32 offset1:100
	ds_write2_b32 v134, v4, v5 offset0:64 offset1:132
	ds_write2_b32 v133, v22, v23 offset0:168 offset1:236
	ds_write2_b32 v135, v6, v7 offset0:72 offset1:140
	ds_write2_b32 v136, v24, v25 offset0:64 offset1:132
	ds_write2_b32 v137, v8, v9 offset0:96 offset1:164
	ds_write2_b32 v138, v26, v27 offset0:72 offset1:140
	ds_write2_b32 v139, v10, v11 offset0:104 offset1:172
	ds_write2_b32 v140, v28, v29 offset0:96 offset1:164
	ds_write2_b32 v141, v12, v13 offset0:128 offset1:196
	ds_write2_b32 v142, v30, v31 offset0:104 offset1:172
	ds_write2_b32 v143, v14, v15 offset0:8 offset1:76
	s_waitcnt lgkmcnt(0)
	ds_read_b128 v[0:3], v130
	global_load_dwordx4 v[4:7], v[32:33], off offset:256
	global_load_dwordx4 v[8:11], v[34:35], off offset:256
	s_waitcnt vmcnt(0) lgkmcnt(0)
	v_pk_fma_f32 v[0:1], v[0:1], v[8:9], v[4:5]
	v_pk_fma_f32 v[2:3], v[2:3], v[10:11], v[6:7]
	global_store_dwordx4 v[32:33], v[0:3], off offset:256
	ds_read_b128 v[0:3], v130 offset:1088
	global_load_dwordx4 v[4:7], v[36:37], off offset:256
	global_load_dwordx4 v[8:11], v[38:39], off offset:256
	s_waitcnt vmcnt(0) lgkmcnt(0)
	v_pk_fma_f32 v[0:1], v[0:1], v[8:9], v[4:5]
	v_pk_fma_f32 v[2:3], v[2:3], v[10:11], v[6:7]
	global_store_dwordx4 v[36:37], v[0:3], off offset:256
	ds_read_b128 v[0:3], v130 offset:2176
	global_load_dwordx4 v[4:7], v[40:41], off offset:256
	global_load_dwordx4 v[8:11], v[42:43], off offset:256
	s_waitcnt vmcnt(0) lgkmcnt(0)
	v_pk_fma_f32 v[0:1], v[0:1], v[8:9], v[4:5]
	v_pk_fma_f32 v[2:3], v[2:3], v[10:11], v[6:7]
	global_store_dwordx4 v[40:41], v[0:3], off offset:256
	ds_read_b128 v[0:3], v130 offset:3264
	global_load_dwordx4 v[4:7], v[44:45], off offset:256
	global_load_dwordx4 v[8:11], v[46:47], off offset:256
	s_waitcnt vmcnt(0) lgkmcnt(0)
	v_pk_fma_f32 v[0:1], v[0:1], v[8:9], v[4:5]
	v_pk_fma_f32 v[2:3], v[2:3], v[10:11], v[6:7]
	global_store_dwordx4 v[44:45], v[0:3], off offset:256
	ds_read_b128 v[0:3], v130 offset:4352
	global_load_dwordx4 v[4:7], v[48:49], off offset:256
	global_load_dwordx4 v[8:11], v[50:51], off offset:256
	s_waitcnt vmcnt(0) lgkmcnt(0)
	v_pk_fma_f32 v[0:1], v[0:1], v[8:9], v[4:5]
	v_pk_fma_f32 v[2:3], v[2:3], v[10:11], v[6:7]
	global_store_dwordx4 v[48:49], v[0:3], off offset:256
	ds_read_b128 v[0:3], v130 offset:5440
	global_load_dwordx4 v[4:7], v[52:53], off offset:256
	global_load_dwordx4 v[8:11], v[54:55], off offset:256
	s_waitcnt vmcnt(0) lgkmcnt(0)
	v_pk_fma_f32 v[0:1], v[0:1], v[8:9], v[4:5]
	v_pk_fma_f32 v[2:3], v[2:3], v[10:11], v[6:7]
	global_store_dwordx4 v[52:53], v[0:3], off offset:256
	ds_read_b128 v[0:3], v130 offset:6528
	global_load_dwordx4 v[4:7], v[56:57], off offset:256
	global_load_dwordx4 v[8:11], v[58:59], off offset:256
	s_waitcnt vmcnt(0) lgkmcnt(0)
	v_pk_fma_f32 v[0:1], v[0:1], v[8:9], v[4:5]
	v_pk_fma_f32 v[2:3], v[2:3], v[10:11], v[6:7]
	global_store_dwordx4 v[56:57], v[0:3], off offset:256
	ds_read_b128 v[0:3], v130 offset:7616
	global_load_dwordx4 v[4:7], v[60:61], off offset:256
	global_load_dwordx4 v[8:11], v[62:63], off offset:256
	s_waitcnt vmcnt(0) lgkmcnt(0)
	v_pk_fma_f32 v[0:1], v[0:1], v[8:9], v[4:5]
	v_pk_fma_f32 v[2:3], v[2:3], v[10:11], v[6:7]
	global_store_dwordx4 v[60:61], v[0:3], off offset:256
	s_waitcnt lgkmcnt(0)
	s_barrier
	s_cbranch_scc1 .LBB0_1086
